# removed 209 hipcc inline-asm pad s_nop 0 after single packed-f32 asm ops in the FFT code (no ISA wait-state rule applies)
# baseline (speedup 1.0000x reference)
; __device__ __forceinline__ cf add_mib(cf a, cf b) { cf r; asm("v_pk_add_f32 %0, %1, %2 op_sel:[0,1] op_sel_hi:[1,0] neg_hi:[0,1]" : "=v"(r) : "v"(a), "v"(b)); return r; }
; template <bool INV, bool HALFIN = false> __device__ __forceinline__ void dft16(cf (&x)[16]) {
; #pragma unroll
;     for (int m2 = 0; m2 < 4; ++m2) {
;         if (HALFIN) { const cf a0 = x[m2], a1 = x[4 + m2]; x[m2] = a0 + a1; x[8 + m2] = a0 - a1; x[4 + m2] = add_mib(a0, a1); x[12 + m2] = add_pib(a0, a1); }
;         else dft4<INV>(x[m2], x[4 + m2], x[8 + m2], x[12 + m2]);
;     }
;     constexpr float C1 = 0.9238795325112867f, S1 = 0.3826834323650898f, C2 = 0.7071067811865476f;
;     x[4 * 1 + 1] = tw16<INV>(x[5], C1, S1);  x[4 * 1 + 2] = tw16<INV>(x[6], C2, C2);   x[4 * 1 + 3] = tw16<INV>(x[7], S1, C1);
;     x[4 * 2 + 1] = tw16<INV>(x[9], C2, C2);  x[4 * 2 + 2] = tw16<INV>(x[10], 0.f, 1.f); x[4 * 2 + 3] = tw16<INV>(x[11], -C2, C2);
;     x[4 * 3 + 1] = tw16<INV>(x[13], S1, C1); x[4 * 3 + 2] = tw16<INV>(x[14], -C2, C2); x[4 * 3 + 3] = tw16<INV>(x[15], -C1, -S1);
; #pragma unroll
;     for (int q1 = 0; q1 < 4; ++q1) dft4<INV>(x[4 * q1], x[4 * q1 + 1], x[4 * q1 + 2], x[4 * q1 + 3]);
; }
; template <bool INV, int LST, bool HALF = false> __device__ __forceinline__ void fft_pass16(LAS cf* z, const LAS cf* Thi, const LAS cf* Tlo, int tid) {
;     ...
;         const int g = tid + 512 * it; const int j0 = g & (st - 1); const int base = ((g >> LST) << (LST + 4)) + j0; const int phb = PH(base);
;         if (LST == 10 || it == 0) {
;             const int e1 = j0 << (10 - LST);
;             w[1] = cmul(Thi[e1 >> 7], Tlo[e1 & 127]);
;             w[2] = cmul(w[1], w[1]); w[3] = cmul(w[2], w[1]); w[4] = cmul(w[2], w[2]); w[5] = cmul(w[4], w[1]); w[6] = cmul(w[3], w[3]); w[7] = cmul(w[4], w[3]); w[8] = cmul(w[4], w[4]);
; #pragma unroll
;             for (int q = 9; q < 16; ++q) w[q] = cmul(w[8], w[q - 8]);
;         }
;         cf x[16];
;         if (!INV) {
; #pragma unroll
;             for (int m = 0; m < 16; ++m) { if (HALF && m >= 8) x[m] = (cf){0.f, 0.f}; else x[m] = z[pass_pos<LST>(base, phb, m)]; }
;             dft16<false, HALF>(x);
; #pragma unroll
;             for (int q = 0; q < 16; ++q) { cf y = x[4 * (q & 3) + (q >> 2)]; if (q) y = cmul(y, w[q]); z[pass_pos<LST>(base, phb, q)] = y; }
.LBB0_300:
	v_add_u32_e32 v16, s47, v152
	v_and_b32_e32 v17, 0x3ff, v16
	v_lshlrev_b32_e32 v18, 4, v16
	v_lshrrev_b32_e32 v16, 4, v16
	v_and_b32_e32 v18, 0x4000, v18
	v_and_b32_e32 v19, 60, v16
	v_and_b32_e32 v16, 56, v16
	v_bitop3_b32 v17, v18, v19, v17 bitop3:0x36
	v_add_u32_e32 v16, 0, v16
	v_lshl_add_u32 v86, v17, 3, 0
	v_add_u32_e32 v32, 0x20000, v16
	ds_read2st64_b64 v[16:19], v86 offset1:16
	ds_read2st64_b64 v[20:23], v86 offset0:32 offset1:48
	ds_read2st64_b64 v[24:27], v86 offset0:64 offset1:80
	ds_read2st64_b64 v[28:31], v86 offset0:96 offset1:112
	v_add_u32_e32 v87, 0x10000, v86
	v_add_u32_e32 v88, 0x12000, v86
	v_add_u32_e32 v89, 0x14000, v86
	v_add_u32_e32 v90, 0x16000, v86
	v_add_u32_e32 v91, 0x18000, v86
	v_add_u32_e32 v92, 0x1a000, v86
	v_add_u32_e32 v93, 0x1c000, v86
	v_add_u32_e32 v94, 0x1e000, v86
	ds_read_b64 v[32:33], v32
	ds_read_b64 v[34:35], v87
	ds_read_b64 v[36:37], v88
	ds_read_b64 v[38:39], v158
	ds_read_b64 v[40:41], v89
	ds_read_b64 v[42:43], v90
	ds_read_b64 v[44:45], v91
	ds_read_b64 v[46:47], v92
	ds_read_b64 v[48:49], v93
	ds_read_b64 v[50:51], v94
	s_waitcnt lgkmcnt(8)
	v_pk_add_f32 v[54:55], v[16:17], v[34:35]
	v_pk_add_f32 v[16:17], v[16:17], v[34:35] neg_lo:[0,1] neg_hi:[0,1]
	s_waitcnt lgkmcnt(3)
	v_pk_add_f32 v[34:35], v[24:25], v[44:45]
	v_pk_add_f32 v[24:25], v[24:25], v[44:45] neg_lo:[0,1] neg_hi:[0,1]
	v_pk_add_f32 v[44:45], v[18:19], v[36:37]
	v_pk_add_f32 v[18:19], v[18:19], v[36:37] neg_lo:[0,1] neg_hi:[0,1]
	s_waitcnt lgkmcnt(2)
	v_pk_add_f32 v[36:37], v[26:27], v[46:47]
	v_pk_add_f32 v[26:27], v[26:27], v[46:47] neg_lo:[0,1] neg_hi:[0,1]
	v_pk_add_f32 v[46:47], v[20:21], v[40:41]
	v_pk_add_f32 v[20:21], v[20:21], v[40:41] neg_lo:[0,1] neg_hi:[0,1]
	s_waitcnt lgkmcnt(1)
	v_pk_add_f32 v[40:41], v[28:29], v[48:49]
	v_pk_mul_f32 v[52:53], v[32:33], v[38:39] op_sel:[0,0] op_sel_hi:[0,1]
	v_pk_add_f32 v[28:29], v[28:29], v[48:49] neg_lo:[0,1] neg_hi:[0,1]
	v_pk_add_f32 v[48:49], v[22:23], v[42:43]
	v_pk_add_f32 v[22:23], v[22:23], v[42:43] neg_lo:[0,1] neg_hi:[0,1]
	s_waitcnt lgkmcnt(0)
	v_pk_add_f32 v[42:43], v[30:31], v[50:51]
	v_pk_add_f32 v[30:31], v[30:31], v[50:51] neg_lo:[0,1] neg_hi:[0,1]
	v_pk_add_f32 v[50:51], v[16:17], v[24:25] op_sel:[0,1] op_sel_hi:[1,0] neg_hi:[0,1]
	v_pk_add_f32 v[16:17], v[16:17], v[24:25] op_sel:[0,1] op_sel_hi:[1,0] neg_lo:[0,1]
	v_pk_add_f32 v[24:25], v[44:45], v[36:37]
	v_pk_add_f32 v[36:37], v[44:45], v[36:37] neg_lo:[0,1] neg_hi:[0,1]
	v_pk_add_f32 v[44:45], v[18:19], v[26:27] op_sel:[0,1] op_sel_hi:[1,0] neg_hi:[0,1]
	v_pk_add_f32 v[18:19], v[18:19], v[26:27] op_sel:[0,1] op_sel_hi:[1,0] neg_lo:[0,1]
	v_pk_add_f32 v[26:27], v[46:47], v[40:41]
	v_pk_add_f32 v[40:41], v[46:47], v[40:41] neg_lo:[0,1] neg_hi:[0,1]
	v_pk_fma_f32 v[32:33], v[32:33], v[38:39], v[52:53] op_sel:[1,1,0] op_sel_hi:[1,0,1] neg_lo:[1,0,0]
	v_pk_add_f32 v[38:39], v[54:55], v[34:35]
	v_pk_add_f32 v[34:35], v[54:55], v[34:35] neg_lo:[0,1] neg_hi:[0,1]
	v_pk_add_f32 v[46:47], v[20:21], v[28:29] op_sel:[0,1] op_sel_hi:[1,0] neg_hi:[0,1]
	v_pk_add_f32 v[20:21], v[20:21], v[28:29] op_sel:[0,1] op_sel_hi:[1,0] neg_lo:[0,1]
	v_pk_add_f32 v[28:29], v[48:49], v[42:43]
	v_pk_add_f32 v[42:43], v[48:49], v[42:43] neg_lo:[0,1] neg_hi:[0,1]
	v_pk_add_f32 v[48:49], v[22:23], v[30:31] op_sel:[0,1] op_sel_hi:[1,0] neg_hi:[0,1]
	v_pk_add_f32 v[22:23], v[22:23], v[30:31] op_sel:[0,1] op_sel_hi:[1,0] neg_lo:[0,1]
	v_pk_mul_f32 v[30:31], v[32:33], v[32:33] op_sel:[0,0] op_sel_hi:[0,1]
	v_pk_mul_f32 v[52:53], v[44:45], s[24:25] op_sel_hi:[1,0]
	v_pk_mul_f32 v[54:55], v[46:47], s[38:39] op_sel_hi:[1,0]
	v_pk_mul_f32 v[56:57], v[48:49], s[22:23] op_sel_hi:[1,0]
	v_pk_fma_f32 v[60:61], v[40:41], 0, v[40:41] op_sel:[0,0,1] op_sel_hi:[1,0,0]
	v_pk_fma_f32 v[40:41], v[40:41], 0, v[40:41] op_sel:[0,0,1] op_sel_hi:[1,0,0] neg_lo:[0,0,1] neg_hi:[0,0,1]
	v_pk_mul_f32 v[58:59], v[36:37], s[38:39] op_sel_hi:[1,0]
	v_mul_f32_e32 v40, 0x3f3504f3, v42
	v_pk_mul_f32 v[62:63], v[18:19], s[22:23] op_sel_hi:[1,0]
	v_pk_add_f32 v[68:69], v[38:39], v[26:27]
	v_pk_add_f32 v[26:27], v[38:39], v[26:27] neg_lo:[0,1] neg_hi:[0,1]
	v_pk_add_f32 v[38:39], v[24:25], v[28:29]
	v_pk_add_f32 v[24:25], v[24:25], v[28:29] neg_lo:[0,1] neg_hi:[0,1]
	v_pk_fma_f32 v[28:29], v[32:33], v[32:33], v[30:31] op_sel:[1,1,0] op_sel_hi:[1,0,1] neg_lo:[1,0,0]
	v_pk_fma_f32 v[30:31], v[44:45], s[22:23], v[52:53] op_sel:[0,0,1] op_sel_hi:[1,0,0] neg_hi:[0,0,1]
	v_pk_fma_f32 v[52:53], v[46:47], s[38:39], v[54:55] op_sel:[0,0,1] op_sel_hi:[1,0,0] neg_hi:[0,0,1]
	v_pk_fma_f32 v[54:55], v[48:49], s[24:25], v[56:57] op_sel:[0,0,1] op_sel_hi:[1,0,0] neg_hi:[0,0,1]
	s_mov_b32 s54, s43
	s_mov_b32 s55, s24
	v_mul_f32_e32 v64, 0x3f3504f3, v20
	v_pk_mul_f32 v[66:67], v[22:23], s[42:43] op_sel:[1,0]
	v_pk_fma_f32 v[56:57], v[36:37], s[38:39], v[58:59] op_sel:[0,0,1] op_sel_hi:[1,0,0] neg_hi:[0,0,1]
	v_mov_b32_e32 v61, v41
	v_pk_fma_f32 v[40:41], v[42:43], s[38:39], v[40:41] op_sel:[1,0,0] op_sel_hi:[1,1,0] neg_lo:[0,0,1] neg_hi:[0,0,1]
	v_pk_fma_f32 v[42:43], v[18:19], s[24:25], v[62:63] op_sel:[0,0,1] op_sel_hi:[1,0,0] neg_hi:[0,0,1]
	v_pk_fma_f32 v[20:21], v[20:21], s[38:39], v[64:65] op_sel:[1,0,0] op_sel_hi:[1,1,0] neg_lo:[0,0,1] neg_hi:[0,0,1]
	v_pk_fma_f32 v[22:23], v[22:23], s[54:55], v[66:67] op_sel_hi:[0,1,1]
	v_pk_add_f32 v[58:59], v[68:69], v[38:39] neg_lo:[0,1] neg_hi:[0,1]
	v_pk_add_f32 v[62:63], v[26:27], v[24:25] op_sel:[0,1] op_sel_hi:[1,0] neg_hi:[0,1]
	v_pk_add_f32 v[24:25], v[26:27], v[24:25] op_sel:[0,1] op_sel_hi:[1,0] neg_lo:[0,1]
	v_pk_add_f32 v[26:27], v[68:69], v[38:39]
	v_pk_mul_f32 v[38:39], v[28:29], v[32:33] op_sel:[0,0] op_sel_hi:[0,1]
; template <bool INV, int LST, bool HALF = false> __device__ __forceinline__ void fft_pass16(LAS cf* z, const LAS cf* Thi, const LAS cf* Tlo, int tid) {
;     ...
;             const int e1 = j0 << (10 - LST);
;             w[1] = cmul(Thi[e1 >> 7], Tlo[e1 & 127]);
;             w[2] = cmul(w[1], w[1]); w[3] = cmul(w[2], w[1]); w[4] = cmul(w[2], w[2]); w[5] = cmul(w[4], w[1]); w[6] = cmul(w[3], w[3]); w[7] = cmul(w[4], w[3]); w[8] = cmul(w[4], w[4]);
; #pragma unroll
;             for (int q = 9; q < 16; ++q) w[q] = cmul(w[8], w[q - 8]);
;         }
;         cf x[16];
;         if (!INV) {
; #pragma unroll
;             for (int m = 0; m < 16; ++m) { if (HALF && m >= 8) x[m] = (cf){0.f, 0.f}; else x[m] = z[pass_pos<LST>(base, phb, m)]; }
;             dft16<false, HALF>(x);
; #pragma unroll
;             for (int q = 0; q < 16; ++q) { cf y = x[4 * (q & 3) + (q >> 2)]; if (q) y = cmul(y, w[q]); z[pass_pos<LST>(base, phb, q)] = y; }
	v_pk_mul_f32 v[64:65], v[28:29], v[28:29] op_sel:[0,0] op_sel_hi:[0,1]
	v_pk_add_f32 v[44:45], v[50:51], v[52:53]
	v_pk_add_f32 v[48:49], v[30:31], v[54:55]
	v_pk_add_f32 v[18:19], v[34:35], v[60:61]
	v_pk_add_f32 v[34:35], v[34:35], v[60:61] neg_lo:[0,1] neg_hi:[0,1]
	v_pk_add_f32 v[36:37], v[16:17], v[20:21]
	v_pk_add_f32 v[16:17], v[16:17], v[20:21] neg_lo:[0,1] neg_hi:[0,1]
	v_pk_fma_f32 v[20:21], v[28:29], v[32:33], v[38:39] op_sel:[1,1,0] op_sel_hi:[1,0,1] neg_lo:[1,0,0]
	v_pk_fma_f32 v[38:39], v[28:29], v[28:29], v[64:65] op_sel:[1,1,0] op_sel_hi:[1,0,1] neg_lo:[1,0,0]
	v_pk_add_f32 v[46:47], v[50:51], v[52:53] neg_lo:[0,1] neg_hi:[0,1]
	v_pk_add_f32 v[30:31], v[30:31], v[54:55] neg_lo:[0,1] neg_hi:[0,1]
	v_pk_add_f32 v[50:51], v[56:57], v[40:41]
	v_pk_add_f32 v[40:41], v[56:57], v[40:41] neg_lo:[0,1] neg_hi:[0,1]
	v_pk_add_f32 v[52:53], v[42:43], v[22:23]
	v_pk_add_f32 v[22:23], v[42:43], v[22:23] neg_lo:[0,1] neg_hi:[0,1]
	v_pk_add_f32 v[64:65], v[44:45], v[48:49]
	v_pk_mul_f32 v[42:43], v[38:39], v[32:33] op_sel:[0,0] op_sel_hi:[0,1]
	v_pk_mul_f32 v[60:61], v[38:39], v[38:39] op_sel:[0,0] op_sel_hi:[0,1]
	v_pk_add_f32 v[44:45], v[44:45], v[48:49] neg_lo:[0,1] neg_hi:[0,1]
	v_pk_add_f32 v[48:49], v[46:47], v[30:31] op_sel:[0,1] op_sel_hi:[1,0] neg_hi:[0,1]
	v_pk_add_f32 v[30:31], v[46:47], v[30:31] op_sel:[0,1] op_sel_hi:[1,0] neg_lo:[0,1]
	v_pk_add_f32 v[46:47], v[18:19], v[50:51]
	v_pk_add_f32 v[18:19], v[18:19], v[50:51] neg_lo:[0,1] neg_hi:[0,1]
	v_pk_add_f32 v[50:51], v[34:35], v[40:41] op_sel:[0,1] op_sel_hi:[1,0] neg_hi:[0,1]
	v_pk_add_f32 v[34:35], v[34:35], v[40:41] op_sel:[0,1] op_sel_hi:[1,0] neg_lo:[0,1]
	v_pk_add_f32 v[40:41], v[36:37], v[52:53]
	v_pk_add_f32 v[36:37], v[36:37], v[52:53] neg_lo:[0,1] neg_hi:[0,1]
	v_pk_add_f32 v[52:53], v[16:17], v[22:23] op_sel:[0,1] op_sel_hi:[1,0] neg_hi:[0,1]
	v_pk_add_f32 v[16:17], v[16:17], v[22:23] op_sel:[0,1] op_sel_hi:[1,0] neg_lo:[0,1]
	v_pk_mul_f32 v[22:23], v[62:63], v[38:39] op_sel:[0,0] op_sel_hi:[0,1]
	v_pk_mul_f32 v[66:67], v[64:65], v[32:33] op_sel:[0,0] op_sel_hi:[0,1]
	v_pk_mul_f32 v[54:55], v[20:21], v[20:21] op_sel:[0,0] op_sel_hi:[0,1]
	v_pk_mul_f32 v[56:57], v[38:39], v[20:21] op_sel:[0,0] op_sel_hi:[0,1]
	v_pk_fma_f32 v[42:43], v[38:39], v[32:33], v[42:43] op_sel:[1,1,0] op_sel_hi:[1,0,1] neg_lo:[1,0,0]
	v_pk_fma_f32 v[60:61], v[38:39], v[38:39], v[60:61] op_sel:[1,1,0] op_sel_hi:[1,0,1] neg_lo:[1,0,0]
	v_pk_mul_f32 v[68:69], v[46:47], v[28:29] op_sel:[0,0] op_sel_hi:[0,1]
	v_pk_fma_f32 v[64:65], v[64:65], v[32:33], v[66:67] op_sel:[1,1,0] op_sel_hi:[1,0,1] neg_lo:[1,0,0]
	v_pk_mul_f32 v[70:71], v[40:41], v[20:21] op_sel:[0,0] op_sel_hi:[0,1]
	v_pk_fma_f32 v[22:23], v[62:63], v[38:39], v[22:23] op_sel:[1,1,0] op_sel_hi:[1,0,1] neg_lo:[1,0,0]
	v_pk_mul_f32 v[66:67], v[48:49], v[42:43] op_sel:[0,0] op_sel_hi:[0,1]
	v_pk_mul_f32 v[62:63], v[60:61], v[32:33] op_sel:[0,0] op_sel_hi:[0,1]
	v_pk_fma_f32 v[46:47], v[46:47], v[28:29], v[68:69] op_sel:[1,1,0] op_sel_hi:[1,0,1] neg_lo:[1,0,0]
	v_pk_fma_f32 v[54:55], v[20:21], v[20:21], v[54:55] op_sel:[1,1,0] op_sel_hi:[1,0,1] neg_lo:[1,0,0]
	v_pk_fma_f32 v[40:41], v[40:41], v[20:21], v[70:71] op_sel:[1,1,0] op_sel_hi:[1,0,1] neg_lo:[1,0,0]
	ds_write2st64_b64 v86, v[26:27], v[64:65] offset1:16
	ds_write2st64_b64 v86, v[46:47], v[40:41] offset0:32 offset1:48
	v_pk_fma_f32 v[26:27], v[48:49], v[42:43], v[66:67] op_sel:[1,1,0] op_sel_hi:[1,0,1] neg_lo:[1,0,0]
	v_pk_fma_f32 v[56:57], v[38:39], v[20:21], v[56:57] op_sel:[1,1,0] op_sel_hi:[1,0,1] neg_lo:[1,0,0]
	v_pk_mul_f32 v[78:79], v[60:61], v[42:43] op_sel:[0,0] op_sel_hi:[0,1]
	v_pk_mul_f32 v[68:69], v[50:51], v[54:55] op_sel:[0,0] op_sel_hi:[0,1]
	v_pk_mul_f32 v[84:85], v[58:59], v[60:61] op_sel:[0,0] op_sel_hi:[0,1]
	v_pk_fma_f32 v[32:33], v[60:61], v[32:33], v[62:63] op_sel:[1,1,0] op_sel_hi:[1,0,1] neg_lo:[1,0,0]
	s_movk_i32 s47, 0x200
	v_pk_mul_f32 v[70:71], v[52:53], v[56:57] op_sel:[0,0] op_sel_hi:[0,1]
	v_pk_fma_f32 v[62:63], v[60:61], v[42:43], v[78:79] op_sel:[1,1,0] op_sel_hi:[1,0,1] neg_lo:[1,0,0]
	v_pk_fma_f32 v[40:41], v[50:51], v[54:55], v[68:69] op_sel:[1,1,0] op_sel_hi:[1,0,1] neg_lo:[1,0,0]
	v_pk_fma_f32 v[46:47], v[58:59], v[60:61], v[84:85] op_sel:[1,1,0] op_sel_hi:[1,0,1] neg_lo:[1,0,0]
	s_and_b64 vcc, exec, s[52:53]
	v_pk_fma_f32 v[42:43], v[52:53], v[56:57], v[70:71] op_sel:[1,1,0] op_sel_hi:[1,0,1] neg_lo:[1,0,0]
	ds_write2st64_b64 v86, v[22:23], v[26:27] offset0:64 offset1:80
	ds_write2st64_b64 v86, v[40:41], v[42:43] offset0:96 offset1:112
	ds_write_b64 v87, v[46:47]
	v_pk_mul_f32 v[22:23], v[44:45], v[32:33] op_sel:[0,0] op_sel_hi:[0,1]
	s_mov_b64 s[52:53], 0
	v_pk_mul_f32 v[72:73], v[60:61], v[28:29] op_sel:[0,0] op_sel_hi:[0,1]
	v_pk_mul_f32 v[74:75], v[60:61], v[20:21] op_sel:[0,0] op_sel_hi:[0,1]
	v_pk_fma_f32 v[22:23], v[44:45], v[32:33], v[22:23] op_sel:[1,1,0] op_sel_hi:[1,0,1] neg_lo:[1,0,0]
	v_pk_mul_f32 v[76:77], v[60:61], v[38:39] op_sel:[0,0] op_sel_hi:[0,1]
	v_pk_mul_f32 v[80:81], v[60:61], v[54:55] op_sel:[0,0] op_sel_hi:[0,1]
	v_pk_mul_f32 v[82:83], v[60:61], v[56:57] op_sel:[0,0] op_sel_hi:[0,1]
	v_pk_fma_f32 v[28:29], v[60:61], v[28:29], v[72:73] op_sel:[1,1,0] op_sel_hi:[1,0,1] neg_lo:[1,0,0]
	v_pk_fma_f32 v[20:21], v[60:61], v[20:21], v[74:75] op_sel:[1,1,0] op_sel_hi:[1,0,1] neg_lo:[1,0,0]
	v_pk_mul_f32 v[46:47], v[30:31], v[62:63] op_sel:[0,0] op_sel_hi:[0,1]
	v_pk_fma_f32 v[38:39], v[60:61], v[38:39], v[76:77] op_sel:[1,1,0] op_sel_hi:[1,0,1] neg_lo:[1,0,0]
	v_pk_fma_f32 v[72:73], v[60:61], v[54:55], v[80:81] op_sel:[1,1,0] op_sel_hi:[1,0,1] neg_lo:[1,0,0]
	v_pk_fma_f32 v[74:75], v[60:61], v[56:57], v[82:83] op_sel:[1,1,0] op_sel_hi:[1,0,1] neg_lo:[1,0,0]
	v_pk_mul_f32 v[26:27], v[18:19], v[28:29] op_sel:[0,0] op_sel_hi:[0,1]
	v_pk_mul_f32 v[40:41], v[36:37], v[20:21] op_sel:[0,0] op_sel_hi:[0,1]
	v_pk_mul_f32 v[42:43], v[24:25], v[38:39] op_sel:[0,0] op_sel_hi:[0,1]
	v_pk_mul_f32 v[48:49], v[34:35], v[72:73] op_sel:[0,0] op_sel_hi:[0,1]
	v_pk_mul_f32 v[50:51], v[16:17], v[74:75] op_sel:[0,0] op_sel_hi:[0,1]
	v_pk_fma_f32 v[18:19], v[18:19], v[28:29], v[26:27] op_sel:[1,1,0] op_sel_hi:[1,0,1] neg_lo:[1,0,0]
	v_pk_fma_f32 v[20:21], v[36:37], v[20:21], v[40:41] op_sel:[1,1,0] op_sel_hi:[1,0,1] neg_lo:[1,0,0]
	v_pk_fma_f32 v[26:27], v[30:31], v[62:63], v[46:47] op_sel:[1,1,0] op_sel_hi:[1,0,1] neg_lo:[1,0,0]
	v_pk_fma_f32 v[24:25], v[24:25], v[38:39], v[42:43] op_sel:[1,1,0] op_sel_hi:[1,0,1] neg_lo:[1,0,0]
	v_pk_fma_f32 v[28:29], v[34:35], v[72:73], v[48:49] op_sel:[1,1,0] op_sel_hi:[1,0,1] neg_lo:[1,0,0]
	v_pk_fma_f32 v[16:17], v[16:17], v[74:75], v[50:51] op_sel:[1,1,0] op_sel_hi:[1,0,1] neg_lo:[1,0,0]
	ds_write_b64 v88, v[22:23]
	ds_write_b64 v89, v[18:19]
	ds_write_b64 v90, v[20:21]
	ds_write_b64 v91, v[24:25]
	ds_write_b64 v92, v[26:27]
	ds_write_b64 v93, v[28:29]
	ds_write_b64 v94, v[16:17]
	s_cbranch_vccnz .LBB0_300
	s_mov_b32 s47, 0
	s_mov_b64 s[52:53], -1
	s_waitcnt lgkmcnt(0)
	s_barrier
	s_branch .LBB0_303
; __device__ __forceinline__ cf add_mib(cf a, cf b) { cf r; asm("v_pk_add_f32 %0, %1, %2 op_sel:[0,1] op_sel_hi:[1,0] neg_hi:[0,1]" : "=v"(r) : "v"(a), "v"(b)); return r; }
; __device__ __forceinline__ cf add_pib(cf a, cf b) { cf r; asm("v_pk_add_f32 %0, %1, %2 op_sel:[0,1] op_sel_hi:[1,0] neg_lo:[0,1]" : "=v"(r) : "v"(a), "v"(b)); return r; }
; template <bool INV, bool HALFIN = false> __device__ __forceinline__ void dft16(cf (&x)[16]) {
; #pragma unroll
;     for (int m2 = 0; m2 < 4; ++m2) {
;         if (HALFIN) { const cf a0 = x[m2], a1 = x[4 + m2]; x[m2] = a0 + a1; x[8 + m2] = a0 - a1; x[4 + m2] = add_mib(a0, a1); x[12 + m2] = add_pib(a0, a1); }
;         else dft4<INV>(x[m2], x[4 + m2], x[8 + m2], x[12 + m2]);
;     }
;     constexpr float C1 = 0.9238795325112867f, S1 = 0.3826834323650898f, C2 = 0.7071067811865476f;
;     x[4 * 1 + 1] = tw16<INV>(x[5], C1, S1);  x[4 * 1 + 2] = tw16<INV>(x[6], C2, C2);   x[4 * 1 + 3] = tw16<INV>(x[7], S1, C1);
;     x[4 * 2 + 1] = tw16<INV>(x[9], C2, C2);  x[4 * 2 + 2] = tw16<INV>(x[10], 0.f, 1.f); x[4 * 2 + 3] = tw16<INV>(x[11], -C2, C2);
;     x[4 * 3 + 1] = tw16<INV>(x[13], S1, C1); x[4 * 3 + 2] = tw16<INV>(x[14], -C2, C2); x[4 * 3 + 3] = tw16<INV>(x[15], -C1, -S1);
; template <bool INV, int LST, bool HALF = false> __device__ __forceinline__ void fft_pass16(LAS cf* z, const LAS cf* Thi, const LAS cf* Tlo, int tid) {
;     ...
;         const int g = tid + 512 * it; const int j0 = g & (st - 1); const int base = ((g >> LST) << (LST + 4)) + j0; const int phb = PH(base);
;         if (LST == 10 || it == 0) {
;             const int e1 = j0 << (10 - LST);
;             w[1] = cmul(Thi[e1 >> 7], Tlo[e1 & 127]);
;             w[2] = cmul(w[1], w[1]); w[3] = cmul(w[2], w[1]); w[4] = cmul(w[2], w[2]); w[5] = cmul(w[4], w[1]); w[6] = cmul(w[3], w[3]); w[7] = cmul(w[4], w[3]); w[8] = cmul(w[4], w[4]);
; #pragma unroll
;             for (int q = 9; q < 16; ++q) w[q] = cmul(w[8], w[q - 8]);
;         }
;         cf x[16];
;         if (!INV) {
; #pragma unroll
;             for (int m = 0; m < 16; ++m) { if (HALF && m >= 8) x[m] = (cf){0.f, 0.f}; else x[m] = z[pass_pos<LST>(base, phb, m)]; }
;             dft16<false, HALF>(x);
.LBB0_302:
	v_add_u32_e32 v46, s47, v159
	v_and_b32_e32 v70, 0x7c00, v46
	v_or_b32_e32 v46, v70, v153
	v_bitop3_b32 v54, v70, 16, v153 bitop3:0x36
	v_bitop3_b32 v62, v70, 32, v153 bitop3:0x36
	v_lshl_add_u32 v84, v46, 3, 0
	v_bitop3_b32 v46, v70, 4, v153 bitop3:0x36
	v_lshl_add_u32 v88, v54, 3, 0
	v_bitop3_b32 v54, v70, 20, v153 bitop3:0x36
	v_lshl_add_u32 v92, v62, 3, 0
	v_bitop3_b32 v62, v70, 36, v153 bitop3:0x36
	v_bitop3_b32 v71, v70, 48, v153 bitop3:0x36
	v_lshl_add_u32 v85, v46, 3, 0
	v_bitop3_b32 v46, v70, 8, v153 bitop3:0x36
	v_lshl_add_u32 v89, v54, 3, 0
	v_bitop3_b32 v54, v70, 24, v153 bitop3:0x36
	v_lshl_add_u32 v93, v62, 3, 0
	v_bitop3_b32 v62, v70, 40, v153 bitop3:0x36
	v_lshl_add_u32 v96, v71, 3, 0
	v_bitop3_b32 v71, v70, 52, v153 bitop3:0x36
	v_lshl_add_u32 v86, v46, 3, 0
	v_bitop3_b32 v46, v70, 12, v153 bitop3:0x36
	v_lshl_add_u32 v90, v54, 3, 0
	v_bitop3_b32 v54, v70, 28, v153 bitop3:0x36
	v_lshl_add_u32 v94, v62, 3, 0
	v_bitop3_b32 v62, v70, 44, v153 bitop3:0x36
	v_lshl_add_u32 v97, v71, 3, 0
	v_bitop3_b32 v71, v70, 56, v153 bitop3:0x36
	v_bitop3_b32 v70, v70, 60, v153 bitop3:0x36
	v_lshl_add_u32 v87, v46, 3, 0
	ds_read_b64 v[46:47], v84
	ds_read_b64 v[48:49], v85 offset:512
	ds_read_b64 v[50:51], v86 offset:1024
	ds_read_b64 v[52:53], v87 offset:1536
	v_lshl_add_u32 v91, v54, 3, 0
	ds_read_b64 v[54:55], v88 offset:2048
	ds_read_b64 v[56:57], v89 offset:2560
	ds_read_b64 v[58:59], v90 offset:3072
	ds_read_b64 v[60:61], v91 offset:3584
	v_lshl_add_u32 v95, v62, 3, 0
	ds_read_b64 v[62:63], v92 offset:4096
	ds_read_b64 v[64:65], v93 offset:4608
	ds_read_b64 v[66:67], v94 offset:5120
	ds_read_b64 v[68:69], v95 offset:5632
	v_lshl_add_u32 v98, v71, 3, 0
	v_lshl_add_u32 v99, v70, 3, 0
	ds_read_b64 v[70:71], v96 offset:6144
	ds_read_b64 v[72:73], v97 offset:6656
	ds_read_b64 v[74:75], v98 offset:7168
	ds_read_b64 v[76:77], v99 offset:7680
	s_waitcnt lgkmcnt(7)
	v_pk_add_f32 v[78:79], v[46:47], v[62:63]
	v_pk_add_f32 v[46:47], v[46:47], v[62:63] neg_lo:[0,1] neg_hi:[0,1]
	s_waitcnt lgkmcnt(3)
	v_pk_add_f32 v[62:63], v[54:55], v[70:71]
	v_pk_add_f32 v[54:55], v[54:55], v[70:71] neg_lo:[0,1] neg_hi:[0,1]
	v_pk_add_f32 v[70:71], v[78:79], v[62:63]
	v_pk_add_f32 v[62:63], v[78:79], v[62:63] neg_lo:[0,1] neg_hi:[0,1]
	v_pk_add_f32 v[78:79], v[46:47], v[54:55] op_sel:[0,1] op_sel_hi:[1,0] neg_hi:[0,1]
	v_pk_add_f32 v[46:47], v[46:47], v[54:55] op_sel:[0,1] op_sel_hi:[1,0] neg_lo:[0,1]
	v_pk_add_f32 v[54:55], v[48:49], v[64:65]
	v_pk_add_f32 v[48:49], v[48:49], v[64:65] neg_lo:[0,1] neg_hi:[0,1]
	s_waitcnt lgkmcnt(2)
	v_pk_add_f32 v[64:65], v[56:57], v[72:73]
	v_pk_add_f32 v[56:57], v[56:57], v[72:73] neg_lo:[0,1] neg_hi:[0,1]
	v_pk_add_f32 v[72:73], v[54:55], v[64:65]
	v_pk_add_f32 v[54:55], v[54:55], v[64:65] neg_lo:[0,1] neg_hi:[0,1]
	v_pk_add_f32 v[64:65], v[48:49], v[56:57] op_sel:[0,1] op_sel_hi:[1,0] neg_hi:[0,1]
	v_pk_add_f32 v[48:49], v[48:49], v[56:57] op_sel:[0,1] op_sel_hi:[1,0] neg_lo:[0,1]
	v_pk_add_f32 v[56:57], v[50:51], v[66:67]
	v_pk_add_f32 v[50:51], v[50:51], v[66:67] neg_lo:[0,1] neg_hi:[0,1]
	s_waitcnt lgkmcnt(1)
	v_pk_add_f32 v[66:67], v[58:59], v[74:75]
	v_pk_add_f32 v[58:59], v[58:59], v[74:75] neg_lo:[0,1] neg_hi:[0,1]
	v_pk_add_f32 v[74:75], v[56:57], v[66:67]
	v_pk_add_f32 v[56:57], v[56:57], v[66:67] neg_lo:[0,1] neg_hi:[0,1]
	v_pk_add_f32 v[66:67], v[50:51], v[58:59] op_sel:[0,1] op_sel_hi:[1,0] neg_hi:[0,1]
	v_pk_add_f32 v[50:51], v[50:51], v[58:59] op_sel:[0,1] op_sel_hi:[1,0] neg_lo:[0,1]
	v_pk_add_f32 v[58:59], v[52:53], v[68:69]
	v_pk_add_f32 v[52:53], v[52:53], v[68:69] neg_lo:[0,1] neg_hi:[0,1]
	s_waitcnt lgkmcnt(0)
	v_pk_add_f32 v[68:69], v[60:61], v[76:77]
	v_pk_add_f32 v[60:61], v[60:61], v[76:77] neg_lo:[0,1] neg_hi:[0,1]
	v_pk_add_f32 v[76:77], v[58:59], v[68:69]
	v_pk_add_f32 v[58:59], v[58:59], v[68:69] neg_lo:[0,1] neg_hi:[0,1]
	v_pk_add_f32 v[68:69], v[52:53], v[60:61] op_sel:[0,1] op_sel_hi:[1,0] neg_hi:[0,1]
	v_pk_add_f32 v[52:53], v[52:53], v[60:61] op_sel:[0,1] op_sel_hi:[1,0] neg_lo:[0,1]
	v_pk_mul_f32 v[60:61], v[64:65], s[24:25] op_sel_hi:[1,0]
	s_mov_b32 s54, s43
	v_pk_fma_f32 v[80:81], v[64:65], s[22:23], v[60:61] op_sel:[0,0,1] op_sel_hi:[1,0,0] neg_hi:[0,0,1]
	s_mov_b32 s55, s24
	v_pk_mul_f32 v[60:61], v[66:67], s[38:39] op_sel_hi:[1,0]
	s_movk_i32 s47, 0x2000
	v_pk_fma_f32 v[64:65], v[66:67], s[38:39], v[60:61] op_sel:[0,0,1] op_sel_hi:[1,0,0] neg_hi:[0,0,1]
	v_pk_mul_f32 v[66:67], v[68:69], s[22:23] op_sel_hi:[1,0]
	s_nop 0
	v_pk_fma_f32 v[82:83], v[68:69], s[24:25], v[66:67] op_sel:[0,0,1] op_sel_hi:[1,0,0] neg_hi:[0,0,1]
	v_pk_add_f32 v[60:61], v[78:79], v[64:65]
	v_pk_mul_f32 v[66:67], v[54:55], s[38:39] op_sel_hi:[1,0]
	v_pk_add_f32 v[64:65], v[78:79], v[64:65] neg_lo:[0,1] neg_hi:[0,1]
	v_pk_fma_f32 v[68:69], v[54:55], s[38:39], v[66:67] op_sel:[0,0,1] op_sel_hi:[1,0,0] neg_hi:[0,0,1]
	v_pk_add_f32 v[78:79], v[80:81], v[82:83] neg_lo:[0,1] neg_hi:[0,1]
	v_pk_fma_f32 v[54:55], v[56:57], 0, v[56:57] op_sel:[0,0,1] op_sel_hi:[1,0,0]
	v_pk_fma_f32 v[56:57], v[56:57], 0, v[56:57] op_sel:[0,0,1] op_sel_hi:[1,0,0] neg_lo:[0,0,1] neg_hi:[0,0,1]
	s_andn2_b64 vcc, exec, s[52:53]
	v_mul_f32_e32 v56, 0x3f3504f3, v58
	v_mov_b32_e32 v55, v57
	v_pk_fma_f32 v[56:57], v[58:59], s[38:39], v[56:57] op_sel:[1,0,0] op_sel_hi:[1,1,0] neg_lo:[0,0,1] neg_hi:[0,0,1]
	v_pk_mul_f32 v[58:59], v[48:49], s[22:23] op_sel_hi:[1,0]
	s_mov_b64 s[52:53], 0
	v_pk_fma_f32 v[66:67], v[48:49], s[24:25], v[58:59] op_sel:[0,0,1] op_sel_hi:[1,0,0]
	v_pk_fma_f32 v[48:49], v[48:49], s[24:25], v[58:59] op_sel:[0,0,1] op_sel_hi:[1,0,0] neg_lo:[0,0,1] neg_hi:[0,0,1]
	v_pk_add_f32 v[58:59], v[70:71], v[74:75] neg_lo:[0,1] neg_hi:[0,1]
; template <bool INV, bool HALFIN = false> __device__ __forceinline__ void dft16(cf (&x)[16]) {
;     ...
;     x[4 * 3 + 1] = tw16<INV>(x[13], S1, C1); x[4 * 3 + 2] = tw16<INV>(x[14], -C2, C2); x[4 * 3 + 3] = tw16<INV>(x[15], -C1, -S1);
; #pragma unroll
;     for (int q1 = 0; q1 < 4; ++q1) dft4<INV>(x[4 * q1], x[4 * q1 + 1], x[4 * q1 + 2], x[4 * q1 + 3]);
; }
; template <bool INV, int LST, bool HALF = false> __device__ __forceinline__ void fft_pass16(LAS cf* z, const LAS cf* Thi, const LAS cf* Tlo, int tid) {
;     ...
;             for (int q = 0; q < 16; ++q) { cf y = x[4 * (q & 3) + (q >> 2)]; if (q) y = cmul(y, w[q]); z[pass_pos<LST>(base, phb, q)] = y; }
	v_mul_f32_e32 v48, 0x3f3504f3, v50
	v_mov_b32_e32 v67, v49
	v_pk_fma_f32 v[48:49], v[50:51], s[38:39], v[48:49] op_sel:[1,0,0] op_sel_hi:[1,1,0] neg_lo:[0,0,1] neg_hi:[0,0,1]
	v_pk_mul_f32 v[50:51], v[52:53], s[42:43] op_sel:[1,0]
	s_nop 0
	v_pk_fma_f32 v[50:51], v[52:53], s[54:55], v[50:51] op_sel_hi:[0,1,1]
	v_pk_add_f32 v[52:53], v[70:71], v[74:75]
	v_pk_add_f32 v[70:71], v[72:73], v[76:77]
	v_pk_add_f32 v[72:73], v[72:73], v[76:77] neg_lo:[0,1] neg_hi:[0,1]
	v_pk_add_f32 v[74:75], v[52:53], v[70:71] neg_lo:[0,1] neg_hi:[0,1]
	v_pk_add_f32 v[76:77], v[58:59], v[72:73] op_sel:[0,1] op_sel_hi:[1,0] neg_hi:[0,1]
	v_pk_add_f32 v[58:59], v[58:59], v[72:73] op_sel:[0,1] op_sel_hi:[1,0] neg_lo:[0,1]
	v_pk_add_f32 v[72:73], v[80:81], v[82:83]
	s_nop 0
	v_pk_add_f32 v[80:81], v[60:61], v[72:73]
	v_pk_add_f32 v[60:61], v[60:61], v[72:73] neg_lo:[0,1] neg_hi:[0,1]
	v_pk_add_f32 v[72:73], v[64:65], v[78:79] op_sel:[0,1] op_sel_hi:[1,0] neg_hi:[0,1]
	v_pk_add_f32 v[64:65], v[64:65], v[78:79] op_sel:[0,1] op_sel_hi:[1,0] neg_lo:[0,1]
	v_pk_add_f32 v[78:79], v[62:63], v[54:55]
	v_pk_add_f32 v[54:55], v[62:63], v[54:55] neg_lo:[0,1] neg_hi:[0,1]
	v_pk_add_f32 v[62:63], v[68:69], v[56:57]
	v_pk_add_f32 v[56:57], v[68:69], v[56:57] neg_lo:[0,1] neg_hi:[0,1]
	v_pk_add_f32 v[68:69], v[78:79], v[62:63]
	v_pk_add_f32 v[62:63], v[78:79], v[62:63] neg_lo:[0,1] neg_hi:[0,1]
	v_pk_add_f32 v[78:79], v[54:55], v[56:57] op_sel:[0,1] op_sel_hi:[1,0] neg_hi:[0,1]
	v_pk_add_f32 v[54:55], v[54:55], v[56:57] op_sel:[0,1] op_sel_hi:[1,0] neg_lo:[0,1]
	v_pk_add_f32 v[56:57], v[46:47], v[48:49]
	v_pk_add_f32 v[46:47], v[46:47], v[48:49] neg_lo:[0,1] neg_hi:[0,1]
	v_pk_add_f32 v[48:49], v[66:67], v[50:51]
	v_pk_add_f32 v[50:51], v[66:67], v[50:51] neg_lo:[0,1] neg_hi:[0,1]
	v_pk_add_f32 v[66:67], v[56:57], v[48:49]
	v_pk_add_f32 v[48:49], v[56:57], v[48:49] neg_lo:[0,1] neg_hi:[0,1]
	v_pk_add_f32 v[56:57], v[46:47], v[50:51] op_sel:[0,1] op_sel_hi:[1,0] neg_hi:[0,1]
	v_pk_add_f32 v[46:47], v[46:47], v[50:51] op_sel:[0,1] op_sel_hi:[1,0] neg_lo:[0,1]
	v_pk_add_f32 v[50:51], v[52:53], v[70:71]
	ds_write_b64 v84, v[50:51]
	v_pk_mul_f32 v[50:51], v[80:81], v[16:17] op_sel:[0,0] op_sel_hi:[0,1]
	v_pk_fma_f32 v[50:51], v[80:81], v[16:17], v[50:51] op_sel:[1,1,0] op_sel_hi:[1,0,1] neg_lo:[1,0,0]
	ds_write_b64 v85, v[50:51] offset:512
	v_pk_mul_f32 v[50:51], v[68:69], v[18:19] op_sel:[0,0] op_sel_hi:[0,1]
	v_pk_fma_f32 v[50:51], v[68:69], v[18:19], v[50:51] op_sel:[1,1,0] op_sel_hi:[1,0,1] neg_lo:[1,0,0]
	ds_write_b64 v86, v[50:51] offset:1024
	v_pk_mul_f32 v[50:51], v[66:67], v[20:21] op_sel:[0,0] op_sel_hi:[0,1]
	v_pk_fma_f32 v[50:51], v[66:67], v[20:21], v[50:51] op_sel:[1,1,0] op_sel_hi:[1,0,1] neg_lo:[1,0,0]
	ds_write_b64 v87, v[50:51] offset:1536
	v_pk_mul_f32 v[50:51], v[76:77], v[22:23] op_sel:[0,0] op_sel_hi:[0,1]
	v_pk_fma_f32 v[50:51], v[76:77], v[22:23], v[50:51] op_sel:[1,1,0] op_sel_hi:[1,0,1] neg_lo:[1,0,0]
	ds_write_b64 v88, v[50:51] offset:2048
	v_pk_mul_f32 v[50:51], v[72:73], v[24:25] op_sel:[0,0] op_sel_hi:[0,1]
	v_pk_fma_f32 v[50:51], v[72:73], v[24:25], v[50:51] op_sel:[1,1,0] op_sel_hi:[1,0,1] neg_lo:[1,0,0]
	ds_write_b64 v89, v[50:51] offset:2560
	v_pk_mul_f32 v[50:51], v[78:79], v[26:27] op_sel:[0,0] op_sel_hi:[0,1]
	v_pk_fma_f32 v[50:51], v[78:79], v[26:27], v[50:51] op_sel:[1,1,0] op_sel_hi:[1,0,1] neg_lo:[1,0,0]
	ds_write_b64 v90, v[50:51] offset:3072
	v_pk_mul_f32 v[50:51], v[56:57], v[28:29] op_sel:[0,0] op_sel_hi:[0,1]
	v_pk_fma_f32 v[50:51], v[56:57], v[28:29], v[50:51] op_sel:[1,1,0] op_sel_hi:[1,0,1] neg_lo:[1,0,0]
	ds_write_b64 v91, v[50:51] offset:3584
	v_pk_mul_f32 v[50:51], v[74:75], v[30:31] op_sel:[0,0] op_sel_hi:[0,1]
	v_pk_fma_f32 v[50:51], v[74:75], v[30:31], v[50:51] op_sel:[1,1,0] op_sel_hi:[1,0,1] neg_lo:[1,0,0]
	ds_write_b64 v92, v[50:51] offset:4096
	v_pk_mul_f32 v[50:51], v[60:61], v[32:33] op_sel:[0,0] op_sel_hi:[0,1]
	v_pk_fma_f32 v[50:51], v[60:61], v[32:33], v[50:51] op_sel:[1,1,0] op_sel_hi:[1,0,1] neg_lo:[1,0,0]
	ds_write_b64 v93, v[50:51] offset:4608
	v_pk_mul_f32 v[50:51], v[62:63], v[34:35] op_sel:[0,0] op_sel_hi:[0,1]
	v_pk_fma_f32 v[50:51], v[62:63], v[34:35], v[50:51] op_sel:[1,1,0] op_sel_hi:[1,0,1] neg_lo:[1,0,0]
	ds_write_b64 v94, v[50:51] offset:5120
	v_pk_mul_f32 v[50:51], v[48:49], v[36:37] op_sel:[0,0] op_sel_hi:[0,1]
	v_pk_fma_f32 v[48:49], v[48:49], v[36:37], v[50:51] op_sel:[1,1,0] op_sel_hi:[1,0,1] neg_lo:[1,0,0]
	ds_write_b64 v95, v[48:49] offset:5632
	v_pk_mul_f32 v[48:49], v[58:59], v[38:39] op_sel:[0,0] op_sel_hi:[0,1]
	v_pk_fma_f32 v[48:49], v[58:59], v[38:39], v[48:49] op_sel:[1,1,0] op_sel_hi:[1,0,1] neg_lo:[1,0,0]
	ds_write_b64 v96, v[48:49] offset:6144
	v_pk_mul_f32 v[48:49], v[64:65], v[40:41] op_sel:[0,0] op_sel_hi:[0,1]
	v_pk_fma_f32 v[48:49], v[64:65], v[40:41], v[48:49] op_sel:[1,1,0] op_sel_hi:[1,0,1] neg_lo:[1,0,0]
	ds_write_b64 v97, v[48:49] offset:6656
	v_pk_mul_f32 v[48:49], v[54:55], v[42:43] op_sel:[0,0] op_sel_hi:[0,1]
	v_pk_fma_f32 v[48:49], v[54:55], v[42:43], v[48:49] op_sel:[1,1,0] op_sel_hi:[1,0,1] neg_lo:[1,0,0]
	ds_write_b64 v98, v[48:49] offset:7168
	v_pk_mul_f32 v[48:49], v[46:47], v[44:45] op_sel:[0,0] op_sel_hi:[0,1]
	v_pk_fma_f32 v[46:47], v[46:47], v[44:45], v[48:49] op_sel:[1,1,0] op_sel_hi:[1,0,1] neg_lo:[1,0,0]
	ds_write_b64 v99, v[46:47] offset:7680
	s_cbranch_vccz .LBB0_305
; template <bool INV, int LST, bool HALF = false> __device__ __forceinline__ void fft_pass16(LAS cf* z, const LAS cf* Thi, const LAS cf* Tlo, int tid) {
;     ...
;         if (LST == 10 || it == 0) {
;             const int e1 = j0 << (10 - LST);
;             w[1] = cmul(Thi[e1 >> 7], Tlo[e1 & 127]);
;             w[2] = cmul(w[1], w[1]); w[3] = cmul(w[2], w[1]); w[4] = cmul(w[2], w[2]); w[5] = cmul(w[4], w[1]); w[6] = cmul(w[3], w[3]); w[7] = cmul(w[4], w[3]); w[8] = cmul(w[4], w[4]);
; #pragma unroll
;             for (int q = 9; q < 16; ++q) w[q] = cmul(w[8], w[q - 8]);
;         }
.LBB0_303:
	s_xor_b64 s[52:53], s[52:53], -1
	s_and_b64 vcc, exec, s[52:53]
	s_cbranch_vccnz .LBB0_302
	ds_read_b64 v[16:17], v160
	ds_read_b64 v[18:19], v161
	s_waitcnt lgkmcnt(0)
	v_pk_mul_f32 v[20:21], v[16:17], v[18:19] op_sel:[0,0] op_sel_hi:[0,1]
	v_pk_fma_f32 v[16:17], v[16:17], v[18:19], v[20:21] op_sel:[1,1,0] op_sel_hi:[1,0,1] neg_lo:[1,0,0]
	v_pk_mul_f32 v[18:19], v[16:17], v[16:17] op_sel:[0,0] op_sel_hi:[0,1]
	v_pk_fma_f32 v[18:19], v[16:17], v[16:17], v[18:19] op_sel:[1,1,0] op_sel_hi:[1,0,1] neg_lo:[1,0,0]
	v_pk_mul_f32 v[20:21], v[18:19], v[16:17] op_sel:[0,0] op_sel_hi:[0,1]
	v_pk_mul_f32 v[22:23], v[18:19], v[18:19] op_sel:[0,0] op_sel_hi:[0,1]
	v_pk_fma_f32 v[20:21], v[18:19], v[16:17], v[20:21] op_sel:[1,1,0] op_sel_hi:[1,0,1] neg_lo:[1,0,0]
	v_pk_fma_f32 v[22:23], v[18:19], v[18:19], v[22:23] op_sel:[1,1,0] op_sel_hi:[1,0,1] neg_lo:[1,0,0]
	v_pk_mul_f32 v[24:25], v[22:23], v[16:17] op_sel:[0,0] op_sel_hi:[0,1]
	v_pk_mul_f32 v[26:27], v[20:21], v[20:21] op_sel:[0,0] op_sel_hi:[0,1]
	v_pk_mul_f32 v[28:29], v[22:23], v[20:21] op_sel:[0,0] op_sel_hi:[0,1]
	v_pk_mul_f32 v[30:31], v[22:23], v[22:23] op_sel:[0,0] op_sel_hi:[0,1]
	v_pk_fma_f32 v[24:25], v[22:23], v[16:17], v[24:25] op_sel:[1,1,0] op_sel_hi:[1,0,1] neg_lo:[1,0,0]
	v_pk_fma_f32 v[26:27], v[20:21], v[20:21], v[26:27] op_sel:[1,1,0] op_sel_hi:[1,0,1] neg_lo:[1,0,0]
	v_pk_fma_f32 v[28:29], v[22:23], v[20:21], v[28:29] op_sel:[1,1,0] op_sel_hi:[1,0,1] neg_lo:[1,0,0]
	v_pk_fma_f32 v[30:31], v[22:23], v[22:23], v[30:31] op_sel:[1,1,0] op_sel_hi:[1,0,1] neg_lo:[1,0,0]
	v_pk_mul_f32 v[32:33], v[30:31], v[16:17] op_sel:[0,0] op_sel_hi:[0,1]
	v_pk_mul_f32 v[34:35], v[30:31], v[18:19] op_sel:[0,0] op_sel_hi:[0,1]
	v_pk_mul_f32 v[36:37], v[30:31], v[20:21] op_sel:[0,0] op_sel_hi:[0,1]
	v_pk_mul_f32 v[38:39], v[30:31], v[22:23] op_sel:[0,0] op_sel_hi:[0,1]
	v_pk_mul_f32 v[40:41], v[30:31], v[24:25] op_sel:[0,0] op_sel_hi:[0,1]
	v_pk_mul_f32 v[42:43], v[30:31], v[26:27] op_sel:[0,0] op_sel_hi:[0,1]
	v_pk_mul_f32 v[44:45], v[30:31], v[28:29] op_sel:[0,0] op_sel_hi:[0,1]
	v_pk_fma_f32 v[32:33], v[30:31], v[16:17], v[32:33] op_sel:[1,1,0] op_sel_hi:[1,0,1] neg_lo:[1,0,0]
	v_pk_fma_f32 v[34:35], v[30:31], v[18:19], v[34:35] op_sel:[1,1,0] op_sel_hi:[1,0,1] neg_lo:[1,0,0]
	v_pk_fma_f32 v[36:37], v[30:31], v[20:21], v[36:37] op_sel:[1,1,0] op_sel_hi:[1,0,1] neg_lo:[1,0,0]
	v_pk_fma_f32 v[38:39], v[30:31], v[22:23], v[38:39] op_sel:[1,1,0] op_sel_hi:[1,0,1] neg_lo:[1,0,0]
	v_pk_fma_f32 v[40:41], v[30:31], v[24:25], v[40:41] op_sel:[1,1,0] op_sel_hi:[1,0,1] neg_lo:[1,0,0]
	v_pk_fma_f32 v[42:43], v[30:31], v[26:27], v[42:43] op_sel:[1,1,0] op_sel_hi:[1,0,1] neg_lo:[1,0,0]
	v_pk_fma_f32 v[44:45], v[30:31], v[28:29], v[44:45] op_sel:[1,1,0] op_sel_hi:[1,0,1] neg_lo:[1,0,0]
	s_branch .LBB0_302

; __device__ __forceinline__ cf add_mib(cf a, cf b) { cf r; asm("v_pk_add_f32 %0, %1, %2 op_sel:[0,1] op_sel_hi:[1,0] neg_hi:[0,1]" : "=v"(r) : "v"(a), "v"(b)); return r; }
; __device__ __forceinline__ cf add_pib(cf a, cf b) { cf r; asm("v_pk_add_f32 %0, %1, %2 op_sel:[0,1] op_sel_hi:[1,0] neg_lo:[0,1]" : "=v"(r) : "v"(a), "v"(b)); return r; }
; template <bool INV, bool HALFIN = false> __device__ __forceinline__ void dft16(cf (&x)[16]) {
; #pragma unroll
;     for (int m2 = 0; m2 < 4; ++m2) {
;         if (HALFIN) { const cf a0 = x[m2], a1 = x[4 + m2]; x[m2] = a0 + a1; x[8 + m2] = a0 - a1; x[4 + m2] = add_mib(a0, a1); x[12 + m2] = add_pib(a0, a1); }
;         else dft4<INV>(x[m2], x[4 + m2], x[8 + m2], x[12 + m2]);
;     }
;     constexpr float C1 = 0.9238795325112867f, S1 = 0.3826834323650898f, C2 = 0.7071067811865476f;
;     x[4 * 1 + 1] = tw16<INV>(x[5], C1, S1);  x[4 * 1 + 2] = tw16<INV>(x[6], C2, C2);   x[4 * 1 + 3] = tw16<INV>(x[7], S1, C1);
;     x[4 * 2 + 1] = tw16<INV>(x[9], C2, C2);  x[4 * 2 + 2] = tw16<INV>(x[10], 0.f, 1.f); x[4 * 2 + 3] = tw16<INV>(x[11], -C2, C2);
; template <bool INV, int LST, bool HALF = false> __device__ __forceinline__ void fft_pass16(LAS cf* z, const LAS cf* Thi, const LAS cf* Tlo, int tid) {
;     ...
;         const int g = tid + 512 * it; const int j0 = g & (st - 1); const int base = ((g >> LST) << (LST + 4)) + j0; const int phb = PH(base);
;         if (LST == 10 || it == 0) {
;             const int e1 = j0 << (10 - LST);
;             w[1] = cmul(Thi[e1 >> 7], Tlo[e1 & 127]);
;             w[2] = cmul(w[1], w[1]); w[3] = cmul(w[2], w[1]); w[4] = cmul(w[2], w[2]); w[5] = cmul(w[4], w[1]); w[6] = cmul(w[3], w[3]); w[7] = cmul(w[4], w[3]); w[8] = cmul(w[4], w[4]);
; #pragma unroll
;             for (int q = 9; q < 16; ++q) w[q] = cmul(w[8], w[q - 8]);
;         }
;         cf x[16];
;         if (!INV) {
; #pragma unroll
;             for (int m = 0; m < 16; ++m) { if (HALF && m >= 8) x[m] = (cf){0.f, 0.f}; else x[m] = z[pass_pos<LST>(base, phb, m)]; }
;             dft16<false, HALF>(x);
.LBB0_306:
	v_add_u32_e32 v46, s47, v159
	v_and_or_b32 v70, v46, s87, v155
	v_bitop3_b32 v54, v70, v162, 16 bitop3:0x36
	v_bitop3_b32 v62, v70, v162, 32 bitop3:0x36
	v_bitop3_b32 v46, v70, v162, 4 bitop3:0x36
	v_lshl_add_u32 v88, v54, 3, 0
	v_bitop3_b32 v54, v70, v162, 20 bitop3:0x36
	v_lshl_add_u32 v92, v62, 3, 0
	v_bitop3_b32 v62, v70, v162, 36 bitop3:0x36
	v_bitop3_b32 v71, v70, v162, 48 bitop3:0x36
	v_lshl_add_u32 v85, v46, 3, 0
	v_bitop3_b32 v46, v70, v162, 8 bitop3:0x36
	v_lshl_add_u32 v89, v54, 3, 0
	v_bitop3_b32 v54, v70, v162, 24 bitop3:0x36
	v_lshl_add_u32 v93, v62, 3, 0
	v_bitop3_b32 v62, v70, v162, 40 bitop3:0x36
	v_lshl_add_u32 v96, v71, 3, 0
	v_bitop3_b32 v71, v70, v162, 52 bitop3:0x36
	v_lshl_add_u32 v84, v70, 3, v163
	v_lshl_add_u32 v86, v46, 3, 0
	v_bitop3_b32 v46, v70, v162, 12 bitop3:0x36
	v_lshl_add_u32 v90, v54, 3, 0
	v_bitop3_b32 v54, v70, v162, 28 bitop3:0x36
	v_lshl_add_u32 v94, v62, 3, 0
	v_bitop3_b32 v62, v70, v162, 44 bitop3:0x36
	v_lshl_add_u32 v97, v71, 3, 0
	v_bitop3_b32 v71, v70, v162, 56 bitop3:0x36
	v_bitop3_b32 v70, v70, v162, 60 bitop3:0x36
	v_lshl_add_u32 v87, v46, 3, 0
	ds_read_b64 v[46:47], v84
	ds_read_b64 v[48:49], v85
	ds_read_b64 v[50:51], v86
	ds_read_b64 v[52:53], v87
	v_lshl_add_u32 v91, v54, 3, 0
	ds_read_b64 v[54:55], v88
	ds_read_b64 v[56:57], v89
	ds_read_b64 v[58:59], v90
	ds_read_b64 v[60:61], v91
	v_lshl_add_u32 v95, v62, 3, 0
	ds_read_b64 v[62:63], v92
	ds_read_b64 v[64:65], v93
	ds_read_b64 v[66:67], v94
	ds_read_b64 v[68:69], v95
	v_lshl_add_u32 v98, v71, 3, 0
	v_lshl_add_u32 v99, v70, 3, 0
	ds_read_b64 v[70:71], v96
	ds_read_b64 v[72:73], v97
	ds_read_b64 v[74:75], v98
	ds_read_b64 v[76:77], v99
	s_waitcnt lgkmcnt(7)
	v_pk_add_f32 v[78:79], v[46:47], v[62:63]
	v_pk_add_f32 v[46:47], v[46:47], v[62:63] neg_lo:[0,1] neg_hi:[0,1]
	s_waitcnt lgkmcnt(3)
	v_pk_add_f32 v[62:63], v[54:55], v[70:71]
	v_pk_add_f32 v[54:55], v[54:55], v[70:71] neg_lo:[0,1] neg_hi:[0,1]
	v_pk_add_f32 v[70:71], v[78:79], v[62:63]
	v_pk_add_f32 v[62:63], v[78:79], v[62:63] neg_lo:[0,1] neg_hi:[0,1]
	v_pk_add_f32 v[78:79], v[46:47], v[54:55] op_sel:[0,1] op_sel_hi:[1,0] neg_hi:[0,1]
	v_pk_add_f32 v[46:47], v[46:47], v[54:55] op_sel:[0,1] op_sel_hi:[1,0] neg_lo:[0,1]
	v_pk_add_f32 v[54:55], v[48:49], v[64:65]
	v_pk_add_f32 v[48:49], v[48:49], v[64:65] neg_lo:[0,1] neg_hi:[0,1]
	s_waitcnt lgkmcnt(2)
	v_pk_add_f32 v[64:65], v[56:57], v[72:73]
	v_pk_add_f32 v[56:57], v[56:57], v[72:73] neg_lo:[0,1] neg_hi:[0,1]
	v_pk_add_f32 v[72:73], v[54:55], v[64:65]
	v_pk_add_f32 v[54:55], v[54:55], v[64:65] neg_lo:[0,1] neg_hi:[0,1]
	v_pk_add_f32 v[64:65], v[48:49], v[56:57] op_sel:[0,1] op_sel_hi:[1,0] neg_hi:[0,1]
	v_pk_add_f32 v[48:49], v[48:49], v[56:57] op_sel:[0,1] op_sel_hi:[1,0] neg_lo:[0,1]
	v_pk_add_f32 v[56:57], v[50:51], v[66:67]
	v_pk_add_f32 v[50:51], v[50:51], v[66:67] neg_lo:[0,1] neg_hi:[0,1]
	s_waitcnt lgkmcnt(1)
	v_pk_add_f32 v[66:67], v[58:59], v[74:75]
	v_pk_add_f32 v[58:59], v[58:59], v[74:75] neg_lo:[0,1] neg_hi:[0,1]
	v_pk_add_f32 v[74:75], v[56:57], v[66:67]
	v_pk_add_f32 v[56:57], v[56:57], v[66:67] neg_lo:[0,1] neg_hi:[0,1]
	v_pk_add_f32 v[66:67], v[50:51], v[58:59] op_sel:[0,1] op_sel_hi:[1,0] neg_hi:[0,1]
	v_pk_add_f32 v[50:51], v[50:51], v[58:59] op_sel:[0,1] op_sel_hi:[1,0] neg_lo:[0,1]
	v_pk_add_f32 v[58:59], v[52:53], v[68:69]
	v_pk_add_f32 v[52:53], v[52:53], v[68:69] neg_lo:[0,1] neg_hi:[0,1]
	s_waitcnt lgkmcnt(0)
	v_pk_add_f32 v[68:69], v[60:61], v[76:77]
	v_pk_add_f32 v[60:61], v[60:61], v[76:77] neg_lo:[0,1] neg_hi:[0,1]
	v_pk_add_f32 v[76:77], v[58:59], v[68:69]
	v_pk_add_f32 v[58:59], v[58:59], v[68:69] neg_lo:[0,1] neg_hi:[0,1]
	v_pk_add_f32 v[68:69], v[52:53], v[60:61] op_sel:[0,1] op_sel_hi:[1,0] neg_hi:[0,1]
	v_pk_add_f32 v[52:53], v[52:53], v[60:61] op_sel:[0,1] op_sel_hi:[1,0] neg_lo:[0,1]
	v_pk_mul_f32 v[60:61], v[64:65], s[24:25] op_sel_hi:[1,0]
	s_mov_b32 s54, s43
	v_pk_fma_f32 v[80:81], v[64:65], s[22:23], v[60:61] op_sel:[0,0,1] op_sel_hi:[1,0,0] neg_hi:[0,0,1]
	s_mov_b32 s55, s24
	v_pk_mul_f32 v[60:61], v[66:67], s[38:39] op_sel_hi:[1,0]
	s_movk_i32 s47, 0x2000
	v_pk_fma_f32 v[64:65], v[66:67], s[38:39], v[60:61] op_sel:[0,0,1] op_sel_hi:[1,0,0] neg_hi:[0,0,1]
	v_pk_mul_f32 v[66:67], v[68:69], s[22:23] op_sel_hi:[1,0]
	s_nop 0
	v_pk_fma_f32 v[82:83], v[68:69], s[24:25], v[66:67] op_sel:[0,0,1] op_sel_hi:[1,0,0] neg_hi:[0,0,1]
	v_pk_add_f32 v[60:61], v[78:79], v[64:65]
	v_pk_mul_f32 v[66:67], v[54:55], s[38:39] op_sel_hi:[1,0]
	v_pk_add_f32 v[64:65], v[78:79], v[64:65] neg_lo:[0,1] neg_hi:[0,1]
	v_pk_fma_f32 v[68:69], v[54:55], s[38:39], v[66:67] op_sel:[0,0,1] op_sel_hi:[1,0,0] neg_hi:[0,0,1]
	v_pk_add_f32 v[78:79], v[80:81], v[82:83] neg_lo:[0,1] neg_hi:[0,1]
	v_pk_fma_f32 v[54:55], v[56:57], 0, v[56:57] op_sel:[0,0,1] op_sel_hi:[1,0,0]
	v_pk_fma_f32 v[56:57], v[56:57], 0, v[56:57] op_sel:[0,0,1] op_sel_hi:[1,0,0] neg_lo:[0,0,1] neg_hi:[0,0,1]
	s_andn2_b64 vcc, exec, s[52:53]
	v_mul_f32_e32 v56, 0x3f3504f3, v58
	v_mov_b32_e32 v55, v57
	v_pk_fma_f32 v[56:57], v[58:59], s[38:39], v[56:57] op_sel:[1,0,0] op_sel_hi:[1,1,0] neg_lo:[0,0,1] neg_hi:[0,0,1]
	v_pk_mul_f32 v[58:59], v[48:49], s[22:23] op_sel_hi:[1,0]
	s_mov_b64 s[52:53], 0
	v_pk_fma_f32 v[66:67], v[48:49], s[24:25], v[58:59] op_sel:[0,0,1] op_sel_hi:[1,0,0]
	v_pk_fma_f32 v[48:49], v[48:49], s[24:25], v[58:59] op_sel:[0,0,1] op_sel_hi:[1,0,0] neg_lo:[0,0,1] neg_hi:[0,0,1]
	v_pk_add_f32 v[58:59], v[70:71], v[74:75] neg_lo:[0,1] neg_hi:[0,1]
	v_mul_f32_e32 v48, 0x3f3504f3, v50
	v_mov_b32_e32 v67, v49
	v_pk_fma_f32 v[48:49], v[50:51], s[38:39], v[48:49] op_sel:[1,0,0] op_sel_hi:[1,1,0] neg_lo:[0,0,1] neg_hi:[0,0,1]
; template <bool INV, bool HALFIN = false> __device__ __forceinline__ void dft16(cf (&x)[16]) {
;     ...
;     x[4 * 3 + 1] = tw16<INV>(x[13], S1, C1); x[4 * 3 + 2] = tw16<INV>(x[14], -C2, C2); x[4 * 3 + 3] = tw16<INV>(x[15], -C1, -S1);
; #pragma unroll
;     for (int q1 = 0; q1 < 4; ++q1) dft4<INV>(x[4 * q1], x[4 * q1 + 1], x[4 * q1 + 2], x[4 * q1 + 3]);
; }
; template <bool INV, int LST, bool HALF = false> __device__ __forceinline__ void fft_pass16(LAS cf* z, const LAS cf* Thi, const LAS cf* Tlo, int tid) {
;     ...
;             for (int q = 0; q < 16; ++q) { cf y = x[4 * (q & 3) + (q >> 2)]; if (q) y = cmul(y, w[q]); z[pass_pos<LST>(base, phb, q)] = y; }
	v_pk_mul_f32 v[50:51], v[52:53], s[42:43] op_sel:[1,0]
	s_nop 0
	v_pk_fma_f32 v[50:51], v[52:53], s[54:55], v[50:51] op_sel_hi:[0,1,1]
	v_pk_add_f32 v[52:53], v[70:71], v[74:75]
	v_pk_add_f32 v[70:71], v[72:73], v[76:77]
	v_pk_add_f32 v[72:73], v[72:73], v[76:77] neg_lo:[0,1] neg_hi:[0,1]
	v_pk_add_f32 v[74:75], v[52:53], v[70:71] neg_lo:[0,1] neg_hi:[0,1]
	v_pk_add_f32 v[76:77], v[58:59], v[72:73] op_sel:[0,1] op_sel_hi:[1,0] neg_hi:[0,1]
	v_pk_add_f32 v[58:59], v[58:59], v[72:73] op_sel:[0,1] op_sel_hi:[1,0] neg_lo:[0,1]
	v_pk_add_f32 v[72:73], v[80:81], v[82:83]
	s_nop 0
	v_pk_add_f32 v[80:81], v[60:61], v[72:73]
	v_pk_add_f32 v[60:61], v[60:61], v[72:73] neg_lo:[0,1] neg_hi:[0,1]
	v_pk_add_f32 v[72:73], v[64:65], v[78:79] op_sel:[0,1] op_sel_hi:[1,0] neg_hi:[0,1]
	v_pk_add_f32 v[64:65], v[64:65], v[78:79] op_sel:[0,1] op_sel_hi:[1,0] neg_lo:[0,1]
	v_pk_add_f32 v[78:79], v[62:63], v[54:55]
	v_pk_add_f32 v[54:55], v[62:63], v[54:55] neg_lo:[0,1] neg_hi:[0,1]
	v_pk_add_f32 v[62:63], v[68:69], v[56:57]
	v_pk_add_f32 v[56:57], v[68:69], v[56:57] neg_lo:[0,1] neg_hi:[0,1]
	v_pk_add_f32 v[68:69], v[78:79], v[62:63]
	v_pk_add_f32 v[62:63], v[78:79], v[62:63] neg_lo:[0,1] neg_hi:[0,1]
	v_pk_add_f32 v[78:79], v[54:55], v[56:57] op_sel:[0,1] op_sel_hi:[1,0] neg_hi:[0,1]
	v_pk_add_f32 v[54:55], v[54:55], v[56:57] op_sel:[0,1] op_sel_hi:[1,0] neg_lo:[0,1]
	v_pk_add_f32 v[56:57], v[46:47], v[48:49]
	v_pk_add_f32 v[46:47], v[46:47], v[48:49] neg_lo:[0,1] neg_hi:[0,1]
	v_pk_add_f32 v[48:49], v[66:67], v[50:51]
	v_pk_add_f32 v[50:51], v[66:67], v[50:51] neg_lo:[0,1] neg_hi:[0,1]
	v_pk_add_f32 v[66:67], v[56:57], v[48:49]
	v_pk_add_f32 v[48:49], v[56:57], v[48:49] neg_lo:[0,1] neg_hi:[0,1]
	v_pk_add_f32 v[56:57], v[46:47], v[50:51] op_sel:[0,1] op_sel_hi:[1,0] neg_hi:[0,1]
	v_pk_add_f32 v[46:47], v[46:47], v[50:51] op_sel:[0,1] op_sel_hi:[1,0] neg_lo:[0,1]
	v_pk_add_f32 v[50:51], v[52:53], v[70:71]
	ds_write_b64 v84, v[50:51]
	v_pk_mul_f32 v[50:51], v[80:81], v[16:17] op_sel:[0,0] op_sel_hi:[0,1]
	v_pk_fma_f32 v[50:51], v[80:81], v[16:17], v[50:51] op_sel:[1,1,0] op_sel_hi:[1,0,1] neg_lo:[1,0,0]
	ds_write_b64 v85, v[50:51]
	v_pk_mul_f32 v[50:51], v[68:69], v[18:19] op_sel:[0,0] op_sel_hi:[0,1]
	v_pk_fma_f32 v[50:51], v[68:69], v[18:19], v[50:51] op_sel:[1,1,0] op_sel_hi:[1,0,1] neg_lo:[1,0,0]
	ds_write_b64 v86, v[50:51]
	v_pk_mul_f32 v[50:51], v[66:67], v[20:21] op_sel:[0,0] op_sel_hi:[0,1]
	v_pk_fma_f32 v[50:51], v[66:67], v[20:21], v[50:51] op_sel:[1,1,0] op_sel_hi:[1,0,1] neg_lo:[1,0,0]
	ds_write_b64 v87, v[50:51]
	v_pk_mul_f32 v[50:51], v[76:77], v[22:23] op_sel:[0,0] op_sel_hi:[0,1]
	v_pk_fma_f32 v[50:51], v[76:77], v[22:23], v[50:51] op_sel:[1,1,0] op_sel_hi:[1,0,1] neg_lo:[1,0,0]
	ds_write_b64 v88, v[50:51]
	v_pk_mul_f32 v[50:51], v[72:73], v[24:25] op_sel:[0,0] op_sel_hi:[0,1]
	v_pk_fma_f32 v[50:51], v[72:73], v[24:25], v[50:51] op_sel:[1,1,0] op_sel_hi:[1,0,1] neg_lo:[1,0,0]
	ds_write_b64 v89, v[50:51]
	v_pk_mul_f32 v[50:51], v[78:79], v[26:27] op_sel:[0,0] op_sel_hi:[0,1]
	v_pk_fma_f32 v[50:51], v[78:79], v[26:27], v[50:51] op_sel:[1,1,0] op_sel_hi:[1,0,1] neg_lo:[1,0,0]
	ds_write_b64 v90, v[50:51]
	v_pk_mul_f32 v[50:51], v[56:57], v[28:29] op_sel:[0,0] op_sel_hi:[0,1]
	v_pk_fma_f32 v[50:51], v[56:57], v[28:29], v[50:51] op_sel:[1,1,0] op_sel_hi:[1,0,1] neg_lo:[1,0,0]
	ds_write_b64 v91, v[50:51]
	v_pk_mul_f32 v[50:51], v[74:75], v[30:31] op_sel:[0,0] op_sel_hi:[0,1]
	v_pk_fma_f32 v[50:51], v[74:75], v[30:31], v[50:51] op_sel:[1,1,0] op_sel_hi:[1,0,1] neg_lo:[1,0,0]
	ds_write_b64 v92, v[50:51]
	v_pk_mul_f32 v[50:51], v[60:61], v[32:33] op_sel:[0,0] op_sel_hi:[0,1]
	v_pk_fma_f32 v[50:51], v[60:61], v[32:33], v[50:51] op_sel:[1,1,0] op_sel_hi:[1,0,1] neg_lo:[1,0,0]
	ds_write_b64 v93, v[50:51]
	v_pk_mul_f32 v[50:51], v[62:63], v[34:35] op_sel:[0,0] op_sel_hi:[0,1]
	v_pk_fma_f32 v[50:51], v[62:63], v[34:35], v[50:51] op_sel:[1,1,0] op_sel_hi:[1,0,1] neg_lo:[1,0,0]
	ds_write_b64 v94, v[50:51]
	v_pk_mul_f32 v[50:51], v[48:49], v[36:37] op_sel:[0,0] op_sel_hi:[0,1]
	v_pk_fma_f32 v[48:49], v[48:49], v[36:37], v[50:51] op_sel:[1,1,0] op_sel_hi:[1,0,1] neg_lo:[1,0,0]
	ds_write_b64 v95, v[48:49]
	v_pk_mul_f32 v[48:49], v[58:59], v[38:39] op_sel:[0,0] op_sel_hi:[0,1]
	v_pk_fma_f32 v[48:49], v[58:59], v[38:39], v[48:49] op_sel:[1,1,0] op_sel_hi:[1,0,1] neg_lo:[1,0,0]
	ds_write_b64 v96, v[48:49]
	v_pk_mul_f32 v[48:49], v[64:65], v[40:41] op_sel:[0,0] op_sel_hi:[0,1]
	v_pk_fma_f32 v[48:49], v[64:65], v[40:41], v[48:49] op_sel:[1,1,0] op_sel_hi:[1,0,1] neg_lo:[1,0,0]
	ds_write_b64 v97, v[48:49]
	v_pk_mul_f32 v[48:49], v[54:55], v[42:43] op_sel:[0,0] op_sel_hi:[0,1]
	v_pk_fma_f32 v[48:49], v[54:55], v[42:43], v[48:49] op_sel:[1,1,0] op_sel_hi:[1,0,1] neg_lo:[1,0,0]
	ds_write_b64 v98, v[48:49]
	v_pk_mul_f32 v[48:49], v[46:47], v[44:45] op_sel:[0,0] op_sel_hi:[0,1]
	v_pk_fma_f32 v[46:47], v[46:47], v[44:45], v[48:49] op_sel:[1,1,0] op_sel_hi:[1,0,1] neg_lo:[1,0,0]
	ds_write_b64 v99, v[46:47]
	s_cbranch_vccz .LBB0_309
; template <bool INV, int LST, bool HALF = false> __device__ __forceinline__ void fft_pass16(LAS cf* z, const LAS cf* Thi, const LAS cf* Tlo, int tid) {
;     ...
;         if (LST == 10 || it == 0) {
;             const int e1 = j0 << (10 - LST);
;             w[1] = cmul(Thi[e1 >> 7], Tlo[e1 & 127]);
;             w[2] = cmul(w[1], w[1]); w[3] = cmul(w[2], w[1]); w[4] = cmul(w[2], w[2]); w[5] = cmul(w[4], w[1]); w[6] = cmul(w[3], w[3]); w[7] = cmul(w[4], w[3]); w[8] = cmul(w[4], w[4]);
; #pragma unroll
;             for (int q = 9; q < 16; ++q) w[q] = cmul(w[8], w[q - 8]);
;         }
.LBB0_307:
	s_xor_b64 s[52:53], s[52:53], -1
	s_and_b64 vcc, exec, s[52:53]
	s_cbranch_vccnz .LBB0_306
	v_mov_b32_e32 v16, s73
	ds_read_b64 v[16:17], v16
	ds_read_b64 v[18:19], v205
	s_waitcnt lgkmcnt(0)
	v_pk_mul_f32 v[20:21], v[18:19], v[16:17] op_sel:[0,0] op_sel_hi:[0,1]
	v_pk_fma_f32 v[16:17], v[18:19], v[16:17], v[20:21] op_sel:[1,1,0] op_sel_hi:[1,0,1] neg_lo:[1,0,0]
	v_pk_mul_f32 v[18:19], v[16:17], v[16:17] op_sel:[0,0] op_sel_hi:[0,1]
	v_pk_fma_f32 v[18:19], v[16:17], v[16:17], v[18:19] op_sel:[1,1,0] op_sel_hi:[1,0,1] neg_lo:[1,0,0]
	v_pk_mul_f32 v[20:21], v[18:19], v[16:17] op_sel:[0,0] op_sel_hi:[0,1]
	v_pk_mul_f32 v[22:23], v[18:19], v[18:19] op_sel:[0,0] op_sel_hi:[0,1]
	v_pk_fma_f32 v[20:21], v[18:19], v[16:17], v[20:21] op_sel:[1,1,0] op_sel_hi:[1,0,1] neg_lo:[1,0,0]
	v_pk_fma_f32 v[22:23], v[18:19], v[18:19], v[22:23] op_sel:[1,1,0] op_sel_hi:[1,0,1] neg_lo:[1,0,0]
	v_pk_mul_f32 v[24:25], v[22:23], v[16:17] op_sel:[0,0] op_sel_hi:[0,1]
	v_pk_mul_f32 v[26:27], v[20:21], v[20:21] op_sel:[0,0] op_sel_hi:[0,1]
	v_pk_mul_f32 v[28:29], v[22:23], v[20:21] op_sel:[0,0] op_sel_hi:[0,1]
	v_pk_mul_f32 v[30:31], v[22:23], v[22:23] op_sel:[0,0] op_sel_hi:[0,1]
	v_pk_fma_f32 v[24:25], v[22:23], v[16:17], v[24:25] op_sel:[1,1,0] op_sel_hi:[1,0,1] neg_lo:[1,0,0]
	v_pk_fma_f32 v[26:27], v[20:21], v[20:21], v[26:27] op_sel:[1,1,0] op_sel_hi:[1,0,1] neg_lo:[1,0,0]
	v_pk_fma_f32 v[28:29], v[22:23], v[20:21], v[28:29] op_sel:[1,1,0] op_sel_hi:[1,0,1] neg_lo:[1,0,0]
	v_pk_fma_f32 v[30:31], v[22:23], v[22:23], v[30:31] op_sel:[1,1,0] op_sel_hi:[1,0,1] neg_lo:[1,0,0]
	v_pk_mul_f32 v[32:33], v[30:31], v[16:17] op_sel:[0,0] op_sel_hi:[0,1]
	v_pk_mul_f32 v[34:35], v[30:31], v[18:19] op_sel:[0,0] op_sel_hi:[0,1]
	v_pk_mul_f32 v[36:37], v[30:31], v[20:21] op_sel:[0,0] op_sel_hi:[0,1]
	v_pk_mul_f32 v[38:39], v[30:31], v[22:23] op_sel:[0,0] op_sel_hi:[0,1]
	v_pk_mul_f32 v[40:41], v[30:31], v[24:25] op_sel:[0,0] op_sel_hi:[0,1]
	v_pk_mul_f32 v[42:43], v[30:31], v[26:27] op_sel:[0,0] op_sel_hi:[0,1]
	v_pk_mul_f32 v[44:45], v[30:31], v[28:29] op_sel:[0,0] op_sel_hi:[0,1]
	v_pk_fma_f32 v[32:33], v[30:31], v[16:17], v[32:33] op_sel:[1,1,0] op_sel_hi:[1,0,1] neg_lo:[1,0,0]
	v_pk_fma_f32 v[34:35], v[30:31], v[18:19], v[34:35] op_sel:[1,1,0] op_sel_hi:[1,0,1] neg_lo:[1,0,0]
	v_pk_fma_f32 v[36:37], v[30:31], v[20:21], v[36:37] op_sel:[1,1,0] op_sel_hi:[1,0,1] neg_lo:[1,0,0]
	v_pk_fma_f32 v[38:39], v[30:31], v[22:23], v[38:39] op_sel:[1,1,0] op_sel_hi:[1,0,1] neg_lo:[1,0,0]
	v_pk_fma_f32 v[40:41], v[30:31], v[24:25], v[40:41] op_sel:[1,1,0] op_sel_hi:[1,0,1] neg_lo:[1,0,0]
	v_pk_fma_f32 v[42:43], v[30:31], v[26:27], v[42:43] op_sel:[1,1,0] op_sel_hi:[1,0,1] neg_lo:[1,0,0]
	v_pk_fma_f32 v[44:45], v[30:31], v[28:29], v[44:45] op_sel:[1,1,0] op_sel_hi:[1,0,1] neg_lo:[1,0,0]
	s_branch .LBB0_306

; __device__ __forceinline__ cf add_mib(cf a, cf b) { cf r; asm("v_pk_add_f32 %0, %1, %2 op_sel:[0,1] op_sel_hi:[1,0] neg_hi:[0,1]" : "=v"(r) : "v"(a), "v"(b)); return r; }
; __device__ __forceinline__ cf add_pib(cf a, cf b) { cf r; asm("v_pk_add_f32 %0, %1, %2 op_sel:[0,1] op_sel_hi:[1,0] neg_lo:[0,1]" : "=v"(r) : "v"(a), "v"(b)); return r; }
; template <bool INV, bool HALFIN = false> __device__ __forceinline__ void dft16(cf (&x)[16]) {
; #pragma unroll
;     for (int m2 = 0; m2 < 4; ++m2) {
;         if (HALFIN) { const cf a0 = x[m2], a1 = x[4 + m2]; x[m2] = a0 + a1; x[8 + m2] = a0 - a1; x[4 + m2] = add_mib(a0, a1); x[12 + m2] = add_pib(a0, a1); }
;         else dft4<INV>(x[m2], x[4 + m2], x[8 + m2], x[12 + m2]);
;     }
;     constexpr float C1 = 0.9238795325112867f, S1 = 0.3826834323650898f, C2 = 0.7071067811865476f;
;     x[4 * 1 + 1] = tw16<INV>(x[5], C1, S1);  x[4 * 1 + 2] = tw16<INV>(x[6], C2, C2);   x[4 * 1 + 3] = tw16<INV>(x[7], S1, C1);
;     x[4 * 2 + 1] = tw16<INV>(x[9], C2, C2);  x[4 * 2 + 2] = tw16<INV>(x[10], 0.f, 1.f); x[4 * 2 + 3] = tw16<INV>(x[11], -C2, C2);
;     x[4 * 3 + 1] = tw16<INV>(x[13], S1, C1); x[4 * 3 + 2] = tw16<INV>(x[14], -C2, C2); x[4 * 3 + 3] = tw16<INV>(x[15], -C1, -S1);
; #pragma unroll
;     for (int q1 = 0; q1 < 4; ++q1) dft4<INV>(x[4 * q1], x[4 * q1 + 1], x[4 * q1 + 2], x[4 * q1 + 3]);
; }
; template <bool INV, int LST, bool HALF = false> __device__ __forceinline__ void fft_pass16(LAS cf* z, const LAS cf* Thi, const LAS cf* Tlo, int tid) {
;     ...
;         const int g = tid + 512 * it; const int j0 = g & (st - 1); const int base = ((g >> LST) << (LST + 4)) + j0; const int phb = PH(base);
;         if (LST == 10 || it == 0) {
;             const int e1 = j0 << (10 - LST);
;             w[1] = cmul(Thi[e1 >> 7], Tlo[e1 & 127]);
;             w[2] = cmul(w[1], w[1]); w[3] = cmul(w[2], w[1]); w[4] = cmul(w[2], w[2]); w[5] = cmul(w[4], w[1]); w[6] = cmul(w[3], w[3]); w[7] = cmul(w[4], w[3]); w[8] = cmul(w[4], w[4]);
; #pragma unroll
;             for (int q = 9; q < 16; ++q) w[q] = cmul(w[8], w[q - 8]);
;         }
;         cf x[16];
;         if (!INV) {
; #pragma unroll
;             for (int m = 0; m < 16; ++m) { if (HALF && m >= 8) x[m] = (cf){0.f, 0.f}; else x[m] = z[pass_pos<LST>(base, phb, m)]; }
;             dft16<false, HALF>(x);
.LBB0_1020:
	v_add_u32_e32 v21, s21, v152
	v_and_b32_e32 v22, 0x3ff, v21
	v_lshlrev_b32_e32 v23, 4, v21
	v_lshrrev_b32_e32 v21, 4, v21
	v_and_b32_e32 v29, 60, v21
	v_and_b32_e32 v21, 56, v21
	v_and_b32_e32 v23, 0x4000, v23
	v_add_u32_e32 v21, 0, v21
	v_bitop3_b32 v22, v23, v29, v22 bitop3:0x36
	v_add_u32_e32 v21, 0x20000, v21
	v_lshl_add_u32 v29, v22, 3, 0
	ds_read_b64 v[22:23], v21
	ds_read_b64 v[30:31], v120
	ds_read2st64_b64 v[48:51], v29 offset1:16
	ds_read2st64_b64 v[52:55], v29 offset0:32 offset1:48
	ds_read2st64_b64 v[56:59], v29 offset0:64 offset1:80
	ds_read2st64_b64 v[60:63], v29 offset0:96 offset1:112
	s_movk_i32 s21, 0x200
	s_waitcnt lgkmcnt(4)
	v_pk_mul_f32 v[38:39], v[22:23], v[30:31] op_sel:[0,0] op_sel_hi:[0,1]
	s_waitcnt lgkmcnt(1)
	v_pk_add_f32 v[66:67], v[48:49], v[56:57] op_sel:[0,1] op_sel_hi:[1,0] neg_hi:[0,1]
	s_waitcnt lgkmcnt(0)
	v_pk_add_f32 v[72:73], v[52:53], v[60:61] neg_lo:[0,1] neg_hi:[0,1]
	v_pk_add_f32 v[68:69], v[50:51], v[58:59] neg_lo:[0,1] neg_hi:[0,1]
	v_pk_add_f32 v[76:77], v[54:55], v[62:63] neg_lo:[0,1] neg_hi:[0,1]
	v_pk_fma_f32 v[82:83], v[72:73], 0, v[72:73] op_sel:[0,0,1] op_sel_hi:[1,0,0]
	v_pk_fma_f32 v[72:73], v[72:73], 0, v[72:73] op_sel:[0,0,1] op_sel_hi:[1,0,0] neg_lo:[0,0,1] neg_hi:[0,0,1]
	v_pk_add_f32 v[42:43], v[48:49], v[56:57]
	v_pk_add_f32 v[64:65], v[48:49], v[56:57] neg_lo:[0,1] neg_hi:[0,1]
	v_pk_add_f32 v[48:49], v[48:49], v[56:57] op_sel:[0,1] op_sel_hi:[1,0] neg_lo:[0,1]
	v_pk_add_f32 v[56:57], v[50:51], v[58:59]
	v_pk_add_f32 v[70:71], v[50:51], v[58:59] op_sel:[0,1] op_sel_hi:[1,0] neg_hi:[0,1]
	v_pk_add_f32 v[50:51], v[50:51], v[58:59] op_sel:[0,1] op_sel_hi:[1,0] neg_lo:[0,1]
	v_pk_add_f32 v[58:59], v[52:53], v[60:61]
	v_pk_add_f32 v[74:75], v[52:53], v[60:61] op_sel:[0,1] op_sel_hi:[1,0] neg_hi:[0,1]
	v_pk_add_f32 v[52:53], v[52:53], v[60:61] op_sel:[0,1] op_sel_hi:[1,0] neg_lo:[0,1]
	v_pk_add_f32 v[60:61], v[54:55], v[62:63]
	v_pk_add_f32 v[78:79], v[54:55], v[62:63] op_sel:[0,1] op_sel_hi:[1,0] neg_hi:[0,1]
	v_pk_add_f32 v[54:55], v[54:55], v[62:63] op_sel:[0,1] op_sel_hi:[1,0] neg_lo:[0,1]
	v_pk_fma_f32 v[22:23], v[22:23], v[30:31], v[38:39] op_sel:[1,1,0] op_sel_hi:[1,0,1] neg_lo:[1,0,0]
	v_pk_mul_f32 v[30:31], v[70:71], s[22:23] op_sel_hi:[1,0]
	v_pk_mul_f32 v[38:39], v[74:75], s[24:25] op_sel_hi:[1,0]
	v_pk_mul_f32 v[62:63], v[78:79], s[20:21] op_sel_hi:[1,0]
	v_pk_mul_f32 v[80:81], v[68:69], s[24:25] op_sel_hi:[1,0]
	v_mul_f32_e32 v72, 0x3f3504f3, v76
	v_pk_mul_f32 v[84:85], v[50:51], s[20:21] op_sel_hi:[1,0]
	s_mov_b32 s48, s37
	s_mov_b32 s49, s22
	v_mul_f32_e32 v86, 0x3f3504f3, v52
	v_pk_mul_f32 v[88:89], v[54:55], s[36:37] op_sel:[1,0]
	v_pk_fma_f32 v[92:93], v[70:71], s[20:21], v[30:31] op_sel:[0,0,1] op_sel_hi:[1,0,0] neg_hi:[0,0,1]
	v_pk_fma_f32 v[70:71], v[74:75], s[24:25], v[38:39] op_sel:[0,0,1] op_sel_hi:[1,0,0] neg_hi:[0,0,1]
	v_pk_fma_f32 v[74:75], v[78:79], s[22:23], v[62:63] op_sel:[0,0,1] op_sel_hi:[1,0,0] neg_hi:[0,0,1]
	v_pk_fma_f32 v[78:79], v[68:69], s[24:25], v[80:81] op_sel:[0,0,1] op_sel_hi:[1,0,0] neg_hi:[0,0,1]
	v_mov_b32_e32 v83, v73
	v_pk_fma_f32 v[72:73], v[76:77], s[24:25], v[72:73] op_sel:[1,0,0] op_sel_hi:[1,1,0] neg_lo:[0,0,1] neg_hi:[0,0,1]
	v_pk_fma_f32 v[76:77], v[50:51], s[22:23], v[84:85] op_sel:[0,0,1] op_sel_hi:[1,0,0] neg_hi:[0,0,1]
	v_pk_add_f32 v[90:91], v[42:43], v[58:59]
	v_pk_add_f32 v[42:43], v[42:43], v[58:59] neg_lo:[0,1] neg_hi:[0,1]
	v_pk_add_f32 v[58:59], v[56:57], v[60:61]
	v_pk_add_f32 v[56:57], v[56:57], v[60:61] neg_lo:[0,1] neg_hi:[0,1]
	v_pk_mul_f32 v[60:61], v[22:23], v[22:23] op_sel:[0,0] op_sel_hi:[0,1]
	v_pk_fma_f32 v[52:53], v[52:53], s[24:25], v[86:87] op_sel:[1,0,0] op_sel_hi:[1,1,0] neg_lo:[0,0,1] neg_hi:[0,0,1]
	v_pk_fma_f32 v[54:55], v[54:55], s[48:49], v[88:89] op_sel_hi:[0,1,1]
	v_pk_add_f32 v[80:81], v[90:91], v[58:59] neg_lo:[0,1] neg_hi:[0,1]
	v_pk_add_f32 v[84:85], v[42:43], v[56:57] op_sel:[0,1] op_sel_hi:[1,0] neg_hi:[0,1]
	v_pk_add_f32 v[42:43], v[42:43], v[56:57] op_sel:[0,1] op_sel_hi:[1,0] neg_lo:[0,1]
	v_pk_add_f32 v[56:57], v[90:91], v[58:59]
	v_pk_fma_f32 v[58:59], v[22:23], v[22:23], v[60:61] op_sel:[1,1,0] op_sel_hi:[1,0,1] neg_lo:[1,0,0]
	v_pk_add_f32 v[30:31], v[64:65], v[82:83]
	v_pk_add_f32 v[38:39], v[64:65], v[82:83] neg_lo:[0,1] neg_hi:[0,1]
	v_pk_add_f32 v[50:51], v[48:49], v[52:53]
	v_pk_add_f32 v[48:49], v[48:49], v[52:53] neg_lo:[0,1] neg_hi:[0,1]
	v_pk_mul_f32 v[60:61], v[58:59], v[58:59] op_sel:[0,0] op_sel_hi:[0,1]
	v_pk_add_f32 v[62:63], v[66:67], v[70:71]
	v_pk_add_f32 v[64:65], v[66:67], v[70:71] neg_lo:[0,1] neg_hi:[0,1]
	v_pk_add_f32 v[66:67], v[92:93], v[74:75]
	v_pk_add_f32 v[68:69], v[92:93], v[74:75] neg_lo:[0,1] neg_hi:[0,1]
	v_pk_add_f32 v[70:71], v[78:79], v[72:73]
	v_pk_add_f32 v[72:73], v[78:79], v[72:73] neg_lo:[0,1] neg_hi:[0,1]
	v_pk_add_f32 v[74:75], v[76:77], v[54:55]
	v_pk_add_f32 v[54:55], v[76:77], v[54:55] neg_lo:[0,1] neg_hi:[0,1]
	v_pk_mul_f32 v[52:53], v[58:59], v[22:23] op_sel:[0,0] op_sel_hi:[0,1]
	v_pk_fma_f32 v[60:61], v[58:59], v[58:59], v[60:61] op_sel:[1,1,0] op_sel_hi:[1,0,1] neg_lo:[1,0,0]
	v_pk_add_f32 v[76:77], v[62:63], v[66:67]
	v_pk_add_f32 v[62:63], v[62:63], v[66:67] neg_lo:[0,1] neg_hi:[0,1]
	v_pk_add_f32 v[66:67], v[64:65], v[68:69] op_sel:[0,1] op_sel_hi:[1,0] neg_hi:[0,1]
	v_pk_add_f32 v[64:65], v[64:65], v[68:69] op_sel:[0,1] op_sel_hi:[1,0] neg_lo:[0,1]
	v_pk_add_f32 v[68:69], v[30:31], v[70:71]
	v_pk_add_f32 v[30:31], v[30:31], v[70:71] neg_lo:[0,1] neg_hi:[0,1]
	v_pk_add_f32 v[70:71], v[38:39], v[72:73] op_sel:[0,1] op_sel_hi:[1,0] neg_hi:[0,1]
	v_pk_add_f32 v[38:39], v[38:39], v[72:73] op_sel:[0,1] op_sel_hi:[1,0] neg_lo:[0,1]
; template <bool INV, int LST, bool HALF = false> __device__ __forceinline__ void fft_pass16(LAS cf* z, const LAS cf* Thi, const LAS cf* Tlo, int tid) {
;     ...
;             const int e1 = j0 << (10 - LST);
;             w[1] = cmul(Thi[e1 >> 7], Tlo[e1 & 127]);
;             w[2] = cmul(w[1], w[1]); w[3] = cmul(w[2], w[1]); w[4] = cmul(w[2], w[2]); w[5] = cmul(w[4], w[1]); w[6] = cmul(w[3], w[3]); w[7] = cmul(w[4], w[3]); w[8] = cmul(w[4], w[4]);
; #pragma unroll
;             for (int q = 9; q < 16; ++q) w[q] = cmul(w[8], w[q - 8]);
;         }
;         cf x[16];
;         if (!INV) {
; #pragma unroll
;             for (int m = 0; m < 16; ++m) { if (HALF && m >= 8) x[m] = (cf){0.f, 0.f}; else x[m] = z[pass_pos<LST>(base, phb, m)]; }
;             dft16<false, HALF>(x);
; #pragma unroll
;             for (int q = 0; q < 16; ++q) { cf y = x[4 * (q & 3) + (q >> 2)]; if (q) y = cmul(y, w[q]); z[pass_pos<LST>(base, phb, q)] = y; }
	v_pk_add_f32 v[72:73], v[50:51], v[74:75]
	v_pk_add_f32 v[50:51], v[50:51], v[74:75] neg_lo:[0,1] neg_hi:[0,1]
	v_pk_add_f32 v[74:75], v[48:49], v[54:55] op_sel:[0,1] op_sel_hi:[1,0] neg_hi:[0,1]
	v_pk_add_f32 v[48:49], v[48:49], v[54:55] op_sel:[0,1] op_sel_hi:[1,0] neg_lo:[0,1]
	v_pk_mul_f32 v[54:55], v[60:61], v[22:23] op_sel:[0,0] op_sel_hi:[0,1]
	v_pk_mul_f32 v[86:87], v[60:61], v[60:61] op_sel:[0,0] op_sel_hi:[0,1]
	v_pk_mul_f32 v[88:89], v[76:77], v[22:23] op_sel:[0,0] op_sel_hi:[0,1]
	v_pk_fma_f32 v[52:53], v[58:59], v[22:23], v[52:53] op_sel:[1,1,0] op_sel_hi:[1,0,1] neg_lo:[1,0,0]
	v_pk_mul_f32 v[90:91], v[68:69], v[58:59] op_sel:[0,0] op_sel_hi:[0,1]
	v_pk_mul_f32 v[94:95], v[84:85], v[60:61] op_sel:[0,0] op_sel_hi:[0,1]
	v_pk_fma_f32 v[54:55], v[60:61], v[22:23], v[54:55] op_sel:[1,1,0] op_sel_hi:[1,0,1] neg_lo:[1,0,0]
	v_pk_fma_f32 v[86:87], v[60:61], v[60:61], v[86:87] op_sel:[1,1,0] op_sel_hi:[1,0,1] neg_lo:[1,0,0]
	v_pk_fma_f32 v[76:77], v[76:77], v[22:23], v[88:89] op_sel:[1,1,0] op_sel_hi:[1,0,1] neg_lo:[1,0,0]
	v_pk_mul_f32 v[78:79], v[52:53], v[52:53] op_sel:[0,0] op_sel_hi:[0,1]
	v_pk_fma_f32 v[68:69], v[68:69], v[58:59], v[90:91] op_sel:[1,1,0] op_sel_hi:[1,0,1] neg_lo:[1,0,0]
	v_pk_mul_f32 v[82:83], v[60:61], v[52:53] op_sel:[0,0] op_sel_hi:[0,1]
	v_pk_mul_f32 v[92:93], v[72:73], v[52:53] op_sel:[0,0] op_sel_hi:[0,1]
	v_pk_mul_f32 v[88:89], v[86:87], v[22:23] op_sel:[0,0] op_sel_hi:[0,1]
	v_pk_fma_f32 v[84:85], v[84:85], v[60:61], v[94:95] op_sel:[1,1,0] op_sel_hi:[1,0,1] neg_lo:[1,0,0]
	v_pk_fma_f32 v[78:79], v[52:53], v[52:53], v[78:79] op_sel:[1,1,0] op_sel_hi:[1,0,1] neg_lo:[1,0,0]
	v_pk_mul_f32 v[96:97], v[86:87], v[54:55] op_sel:[0,0] op_sel_hi:[0,1]
	s_and_b64 vcc, exec, s[46:47]
	v_pk_fma_f32 v[72:73], v[72:73], v[52:53], v[92:93] op_sel:[1,1,0] op_sel_hi:[1,0,1] neg_lo:[1,0,0]
	ds_write2st64_b64 v29, v[56:57], v[76:77] offset1:16
	ds_write2st64_b64 v29, v[68:69], v[72:73] offset0:32 offset1:48
	v_pk_mul_f32 v[56:57], v[66:67], v[54:55] op_sel:[0,0] op_sel_hi:[0,1]
	v_pk_mul_f32 v[68:69], v[70:71], v[78:79] op_sel:[0,0] op_sel_hi:[0,1]
	v_pk_fma_f32 v[22:23], v[86:87], v[22:23], v[88:89] op_sel:[1,1,0] op_sel_hi:[1,0,1] neg_lo:[1,0,0]
	v_pk_fma_f32 v[88:89], v[86:87], v[54:55], v[96:97] op_sel:[1,1,0] op_sel_hi:[1,0,1] neg_lo:[1,0,0]
	s_mov_b64 s[46:47], 0
	v_pk_fma_f32 v[54:55], v[66:67], v[54:55], v[56:57] op_sel:[1,1,0] op_sel_hi:[1,0,1] neg_lo:[1,0,0]
	v_add_u32_e32 v21, 0x10000, v29
	v_add_u32_e32 v37, 0x12000, v29
	v_pk_fma_f32 v[82:83], v[60:61], v[52:53], v[82:83] op_sel:[1,1,0] op_sel_hi:[1,0,1] neg_lo:[1,0,0]
	v_pk_mul_f32 v[90:91], v[86:87], v[58:59] op_sel:[0,0] op_sel_hi:[0,1]
	v_pk_mul_f32 v[92:93], v[86:87], v[52:53] op_sel:[0,0] op_sel_hi:[0,1]
	v_pk_mul_f32 v[76:77], v[80:81], v[86:87] op_sel:[0,0] op_sel_hi:[0,1]
	v_pk_fma_f32 v[56:57], v[70:71], v[78:79], v[68:69] op_sel:[1,1,0] op_sel_hi:[1,0,1] neg_lo:[1,0,0]
	v_add_u32_e32 v41, 0x14000, v29
	v_pk_mul_f32 v[72:73], v[74:75], v[82:83] op_sel:[0,0] op_sel_hi:[0,1]
	v_pk_fma_f32 v[52:53], v[86:87], v[52:53], v[92:93] op_sel:[1,1,0] op_sel_hi:[1,0,1] neg_lo:[1,0,0]
	v_pk_fma_f32 v[68:69], v[80:81], v[86:87], v[76:77] op_sel:[1,1,0] op_sel_hi:[1,0,1] neg_lo:[1,0,0]
	v_add_u32_e32 v102, 0x16000, v29
	v_pk_fma_f32 v[66:67], v[74:75], v[82:83], v[72:73] op_sel:[1,1,0] op_sel_hi:[1,0,1] neg_lo:[1,0,0]
	ds_write2st64_b64 v29, v[84:85], v[54:55] offset0:64 offset1:80
	ds_write2st64_b64 v29, v[56:57], v[66:67] offset0:96 offset1:112
	ds_write_b64 v21, v[68:69]
	v_pk_mul_f32 v[54:55], v[62:63], v[22:23] op_sel:[0,0] op_sel_hi:[0,1]
	v_add_u32_e32 v103, 0x18000, v29
	v_pk_fma_f32 v[22:23], v[62:63], v[22:23], v[54:55] op_sel:[1,1,0] op_sel_hi:[1,0,1] neg_lo:[1,0,0]
	v_add_u32_e32 v104, 0x1a000, v29
	v_add_u32_e32 v105, 0x1c000, v29
	v_add_u32_e32 v106, 0x1e000, v29
	v_pk_mul_f32 v[94:95], v[86:87], v[60:61] op_sel:[0,0] op_sel_hi:[0,1]
	v_pk_mul_f32 v[98:99], v[86:87], v[78:79] op_sel:[0,0] op_sel_hi:[0,1]
	v_pk_mul_f32 v[100:101], v[86:87], v[82:83] op_sel:[0,0] op_sel_hi:[0,1]
	v_pk_fma_f32 v[58:59], v[86:87], v[58:59], v[90:91] op_sel:[1,1,0] op_sel_hi:[1,0,1] neg_lo:[1,0,0]
	v_pk_mul_f32 v[66:67], v[50:51], v[52:53] op_sel:[0,0] op_sel_hi:[0,1]
	v_pk_mul_f32 v[70:71], v[64:65], v[88:89] op_sel:[0,0] op_sel_hi:[0,1]
	v_pk_fma_f32 v[60:61], v[86:87], v[60:61], v[94:95] op_sel:[1,1,0] op_sel_hi:[1,0,1] neg_lo:[1,0,0]
	v_pk_fma_f32 v[90:91], v[86:87], v[78:79], v[98:99] op_sel:[1,1,0] op_sel_hi:[1,0,1] neg_lo:[1,0,0]
	v_pk_fma_f32 v[92:93], v[86:87], v[82:83], v[100:101] op_sel:[1,1,0] op_sel_hi:[1,0,1] neg_lo:[1,0,0]
	v_pk_mul_f32 v[56:57], v[30:31], v[58:59] op_sel:[0,0] op_sel_hi:[0,1]
	v_pk_fma_f32 v[50:51], v[50:51], v[52:53], v[66:67] op_sel:[1,1,0] op_sel_hi:[1,0,1] neg_lo:[1,0,0]
	v_pk_fma_f32 v[52:53], v[64:65], v[88:89], v[70:71] op_sel:[1,1,0] op_sel_hi:[1,0,1] neg_lo:[1,0,0]
	v_pk_mul_f32 v[68:69], v[42:43], v[60:61] op_sel:[0,0] op_sel_hi:[0,1]
	v_pk_mul_f32 v[72:73], v[38:39], v[90:91] op_sel:[0,0] op_sel_hi:[0,1]
	v_pk_mul_f32 v[74:75], v[48:49], v[92:93] op_sel:[0,0] op_sel_hi:[0,1]
	v_pk_fma_f32 v[30:31], v[30:31], v[58:59], v[56:57] op_sel:[1,1,0] op_sel_hi:[1,0,1] neg_lo:[1,0,0]
	v_pk_fma_f32 v[42:43], v[42:43], v[60:61], v[68:69] op_sel:[1,1,0] op_sel_hi:[1,0,1] neg_lo:[1,0,0]
	v_pk_fma_f32 v[38:39], v[38:39], v[90:91], v[72:73] op_sel:[1,1,0] op_sel_hi:[1,0,1] neg_lo:[1,0,0]
	v_pk_fma_f32 v[48:49], v[48:49], v[92:93], v[74:75] op_sel:[1,1,0] op_sel_hi:[1,0,1] neg_lo:[1,0,0]
	ds_write_b64 v37, v[22:23]
	ds_write_b64 v41, v[30:31]
	ds_write_b64 v102, v[50:51]
	ds_write_b64 v103, v[42:43]
	ds_write_b64 v104, v[52:53]
	ds_write_b64 v105, v[38:39]
	ds_write_b64 v106, v[48:49]
	s_cbranch_vccnz .LBB0_1020
	s_mov_b32 s21, 0
	s_mov_b64 s[46:47], -1
	s_waitcnt lgkmcnt(0)
	s_barrier
	s_branch .LBB0_1023
; __device__ __forceinline__ cf add_mib(cf a, cf b) { cf r; asm("v_pk_add_f32 %0, %1, %2 op_sel:[0,1] op_sel_hi:[1,0] neg_hi:[0,1]" : "=v"(r) : "v"(a), "v"(b)); return r; }
; __device__ __forceinline__ cf add_pib(cf a, cf b) { cf r; asm("v_pk_add_f32 %0, %1, %2 op_sel:[0,1] op_sel_hi:[1,0] neg_lo:[0,1]" : "=v"(r) : "v"(a), "v"(b)); return r; }
; template <bool INV, bool HALFIN = false> __device__ __forceinline__ void dft16(cf (&x)[16]) {
; #pragma unroll
;     for (int m2 = 0; m2 < 4; ++m2) {
;         if (HALFIN) { const cf a0 = x[m2], a1 = x[4 + m2]; x[m2] = a0 + a1; x[8 + m2] = a0 - a1; x[4 + m2] = add_mib(a0, a1); x[12 + m2] = add_pib(a0, a1); }
;         else dft4<INV>(x[m2], x[4 + m2], x[8 + m2], x[12 + m2]);
;     }
;     constexpr float C1 = 0.9238795325112867f, S1 = 0.3826834323650898f, C2 = 0.7071067811865476f;
;     x[4 * 1 + 1] = tw16<INV>(x[5], C1, S1);  x[4 * 1 + 2] = tw16<INV>(x[6], C2, C2);   x[4 * 1 + 3] = tw16<INV>(x[7], S1, C1);
;     x[4 * 2 + 1] = tw16<INV>(x[9], C2, C2);  x[4 * 2 + 2] = tw16<INV>(x[10], 0.f, 1.f); x[4 * 2 + 3] = tw16<INV>(x[11], -C2, C2);
;     x[4 * 3 + 1] = tw16<INV>(x[13], S1, C1); x[4 * 3 + 2] = tw16<INV>(x[14], -C2, C2); x[4 * 3 + 3] = tw16<INV>(x[15], -C1, -S1);
; template <bool INV, int LST, bool HALF = false> __device__ __forceinline__ void fft_pass16(LAS cf* z, const LAS cf* Thi, const LAS cf* Tlo, int tid) {
;     ...
;         const int g = tid + 512 * it; const int j0 = g & (st - 1); const int base = ((g >> LST) << (LST + 4)) + j0; const int phb = PH(base);
;         if (LST == 10 || it == 0) {
;             const int e1 = j0 << (10 - LST);
;             w[1] = cmul(Thi[e1 >> 7], Tlo[e1 & 127]);
;             w[2] = cmul(w[1], w[1]); w[3] = cmul(w[2], w[1]); w[4] = cmul(w[2], w[2]); w[5] = cmul(w[4], w[1]); w[6] = cmul(w[3], w[3]); w[7] = cmul(w[4], w[3]); w[8] = cmul(w[4], w[4]);
; #pragma unroll
;             for (int q = 9; q < 16; ++q) w[q] = cmul(w[8], w[q - 8]);
;         }
;         cf x[16];
;         if (!INV) {
; #pragma unroll
;             for (int m = 0; m < 16; ++m) { if (HALF && m >= 8) x[m] = (cf){0.f, 0.f}; else x[m] = z[pass_pos<LST>(base, phb, m)]; }
;             dft16<false, HALF>(x);
.LBB0_1022:
	v_add_u32_e32 v21, s21, v169
	v_and_b32_e32 v21, 0x7c00, v21
	v_or_b32_e32 v29, v21, v122
	v_lshl_add_u32 v29, v29, 3, 0
	v_xor_b32_e32 v109, 0x80, v29
	v_xor_b32_e32 v113, 0x100, v29
	v_xor_b32_e32 v110, 0xa0, v29
	v_xor_b32_e32 v114, 0x120, v29
	v_xor_b32_e32 v182, 0x180, v29
	v_xor_b32_e32 v111, 0xc0, v29
	v_xor_b32_e32 v115, 0x140, v29
	v_xor_b32_e32 v183, 0x1a0, v29
	v_xor_b32_e32 v37, 0x20, v29
	v_xor_b32_e32 v41, 0x40, v29
	v_xor_b32_e32 v108, 0x60, v29
	ds_read_b64 v[70:71], v29
	ds_read_b64 v[72:73], v37 offset:512
	ds_read_b64 v[74:75], v41 offset:1024
	ds_read_b64 v[76:77], v108 offset:1536
	v_xor_b32_e32 v112, 0xe0, v29
	ds_read_b64 v[78:79], v109 offset:2048
	ds_read_b64 v[80:81], v110 offset:2560
	ds_read_b64 v[82:83], v111 offset:3072
	ds_read_b64 v[84:85], v112 offset:3584
	v_xor_b32_e32 v125, 0x160, v29
	ds_read_b64 v[86:87], v113 offset:4096
	ds_read_b64 v[88:89], v114 offset:4608
	ds_read_b64 v[90:91], v115 offset:5120
	ds_read_b64 v[92:93], v125 offset:5632
	v_xor_b32_e32 v216, 0x1c0, v29
	v_xor_b32_e32 v21, 0x1e0, v29
	ds_read_b64 v[94:95], v182 offset:6144
	ds_read_b64 v[96:97], v183 offset:6656
	ds_read_b64 v[98:99], v216 offset:7168
	ds_read_b64 v[100:101], v21 offset:7680
	s_waitcnt lgkmcnt(7)
	v_pk_add_f32 v[102:103], v[70:71], v[86:87]
	v_pk_add_f32 v[70:71], v[70:71], v[86:87] neg_lo:[0,1] neg_hi:[0,1]
	s_waitcnt lgkmcnt(3)
	v_pk_add_f32 v[86:87], v[78:79], v[94:95]
	v_pk_add_f32 v[78:79], v[78:79], v[94:95] neg_lo:[0,1] neg_hi:[0,1]
	v_pk_add_f32 v[94:95], v[102:103], v[86:87]
	v_pk_add_f32 v[86:87], v[102:103], v[86:87] neg_lo:[0,1] neg_hi:[0,1]
	v_pk_add_f32 v[102:103], v[70:71], v[78:79] op_sel:[0,1] op_sel_hi:[1,0] neg_hi:[0,1]
	v_pk_add_f32 v[70:71], v[70:71], v[78:79] op_sel:[0,1] op_sel_hi:[1,0] neg_lo:[0,1]
	v_pk_add_f32 v[78:79], v[72:73], v[88:89]
	v_pk_add_f32 v[72:73], v[72:73], v[88:89] neg_lo:[0,1] neg_hi:[0,1]
	s_waitcnt lgkmcnt(2)
	v_pk_add_f32 v[88:89], v[80:81], v[96:97]
	v_pk_add_f32 v[80:81], v[80:81], v[96:97] neg_lo:[0,1] neg_hi:[0,1]
	v_pk_add_f32 v[96:97], v[78:79], v[88:89]
	v_pk_add_f32 v[78:79], v[78:79], v[88:89] neg_lo:[0,1] neg_hi:[0,1]
	v_pk_add_f32 v[88:89], v[72:73], v[80:81] op_sel:[0,1] op_sel_hi:[1,0] neg_hi:[0,1]
	v_pk_add_f32 v[72:73], v[72:73], v[80:81] op_sel:[0,1] op_sel_hi:[1,0] neg_lo:[0,1]
	v_pk_add_f32 v[80:81], v[74:75], v[90:91]
	v_pk_add_f32 v[74:75], v[74:75], v[90:91] neg_lo:[0,1] neg_hi:[0,1]
	s_waitcnt lgkmcnt(1)
	v_pk_add_f32 v[90:91], v[82:83], v[98:99]
	v_pk_add_f32 v[82:83], v[82:83], v[98:99] neg_lo:[0,1] neg_hi:[0,1]
	v_pk_add_f32 v[98:99], v[80:81], v[90:91]
	v_pk_add_f32 v[80:81], v[80:81], v[90:91] neg_lo:[0,1] neg_hi:[0,1]
	v_pk_add_f32 v[90:91], v[74:75], v[82:83] op_sel:[0,1] op_sel_hi:[1,0] neg_hi:[0,1]
	v_pk_add_f32 v[74:75], v[74:75], v[82:83] op_sel:[0,1] op_sel_hi:[1,0] neg_lo:[0,1]
	v_pk_add_f32 v[82:83], v[76:77], v[92:93]
	v_pk_add_f32 v[76:77], v[76:77], v[92:93] neg_lo:[0,1] neg_hi:[0,1]
	s_waitcnt lgkmcnt(0)
	v_pk_add_f32 v[92:93], v[84:85], v[100:101]
	v_pk_add_f32 v[84:85], v[84:85], v[100:101] neg_lo:[0,1] neg_hi:[0,1]
	v_pk_add_f32 v[100:101], v[82:83], v[92:93]
	v_pk_add_f32 v[82:83], v[82:83], v[92:93] neg_lo:[0,1] neg_hi:[0,1]
	v_pk_add_f32 v[92:93], v[76:77], v[84:85] op_sel:[0,1] op_sel_hi:[1,0] neg_hi:[0,1]
	v_pk_add_f32 v[76:77], v[76:77], v[84:85] op_sel:[0,1] op_sel_hi:[1,0] neg_lo:[0,1]
	v_pk_mul_f32 v[84:85], v[88:89], s[22:23] op_sel_hi:[1,0]
	s_mov_b32 s48, s37
	v_pk_fma_f32 v[104:105], v[88:89], s[20:21], v[84:85] op_sel:[0,0,1] op_sel_hi:[1,0,0] neg_hi:[0,0,1]
	s_mov_b32 s49, s22
	v_pk_mul_f32 v[84:85], v[90:91], s[24:25] op_sel_hi:[1,0]
	s_andn2_b64 vcc, exec, s[46:47]
	v_pk_fma_f32 v[88:89], v[90:91], s[24:25], v[84:85] op_sel:[0,0,1] op_sel_hi:[1,0,0] neg_hi:[0,0,1]
	v_pk_mul_f32 v[90:91], v[92:93], s[20:21] op_sel_hi:[1,0]
	s_nop 0
	v_pk_fma_f32 v[106:107], v[92:93], s[22:23], v[90:91] op_sel:[0,0,1] op_sel_hi:[1,0,0] neg_hi:[0,0,1]
	v_pk_add_f32 v[84:85], v[102:103], v[88:89]
	v_pk_mul_f32 v[90:91], v[78:79], s[24:25] op_sel_hi:[1,0]
	v_pk_add_f32 v[88:89], v[102:103], v[88:89] neg_lo:[0,1] neg_hi:[0,1]
	v_pk_fma_f32 v[92:93], v[78:79], s[24:25], v[90:91] op_sel:[0,0,1] op_sel_hi:[1,0,0] neg_hi:[0,0,1]
	v_pk_add_f32 v[102:103], v[104:105], v[106:107] neg_lo:[0,1] neg_hi:[0,1]
	v_pk_fma_f32 v[78:79], v[80:81], 0, v[80:81] op_sel:[0,0,1] op_sel_hi:[1,0,0]
	v_pk_fma_f32 v[80:81], v[80:81], 0, v[80:81] op_sel:[0,0,1] op_sel_hi:[1,0,0] neg_lo:[0,0,1] neg_hi:[0,0,1]
	s_mov_b64 s[46:47], 0
	v_mul_f32_e32 v80, 0x3f3504f3, v82
	v_mov_b32_e32 v79, v81
	v_pk_fma_f32 v[80:81], v[82:83], s[24:25], v[80:81] op_sel:[1,0,0] op_sel_hi:[1,1,0] neg_lo:[0,0,1] neg_hi:[0,0,1]
	v_pk_mul_f32 v[82:83], v[72:73], s[20:21] op_sel_hi:[1,0]
	s_movk_i32 s21, 0x2000
	v_pk_fma_f32 v[90:91], v[72:73], s[22:23], v[82:83] op_sel:[0,0,1] op_sel_hi:[1,0,0]
	v_pk_fma_f32 v[72:73], v[72:73], s[22:23], v[82:83] op_sel:[0,0,1] op_sel_hi:[1,0,0] neg_lo:[0,0,1] neg_hi:[0,0,1]
	v_pk_add_f32 v[82:83], v[94:95], v[98:99] neg_lo:[0,1] neg_hi:[0,1]
	v_mul_f32_e32 v72, 0x3f3504f3, v74
	v_mov_b32_e32 v91, v73
	v_pk_fma_f32 v[72:73], v[74:75], s[24:25], v[72:73] op_sel:[1,0,0] op_sel_hi:[1,1,0] neg_lo:[0,0,1] neg_hi:[0,0,1]
	v_pk_mul_f32 v[74:75], v[76:77], s[36:37] op_sel:[1,0]
	s_nop 0
	v_pk_fma_f32 v[74:75], v[76:77], s[48:49], v[74:75] op_sel_hi:[0,1,1]
	v_pk_add_f32 v[76:77], v[94:95], v[98:99]
	v_pk_add_f32 v[94:95], v[96:97], v[100:101]
	v_pk_add_f32 v[96:97], v[96:97], v[100:101] neg_lo:[0,1] neg_hi:[0,1]
	v_pk_add_f32 v[98:99], v[76:77], v[94:95] neg_lo:[0,1] neg_hi:[0,1]
	v_pk_add_f32 v[100:101], v[82:83], v[96:97] op_sel:[0,1] op_sel_hi:[1,0] neg_hi:[0,1]
; template <bool INV, bool HALFIN = false> __device__ __forceinline__ void dft16(cf (&x)[16]) {
;     ...
;     x[4 * 3 + 1] = tw16<INV>(x[13], S1, C1); x[4 * 3 + 2] = tw16<INV>(x[14], -C2, C2); x[4 * 3 + 3] = tw16<INV>(x[15], -C1, -S1);
; #pragma unroll
;     for (int q1 = 0; q1 < 4; ++q1) dft4<INV>(x[4 * q1], x[4 * q1 + 1], x[4 * q1 + 2], x[4 * q1 + 3]);
; }
; template <bool INV, int LST, bool HALF = false> __device__ __forceinline__ void fft_pass16(LAS cf* z, const LAS cf* Thi, const LAS cf* Tlo, int tid) {
;     ...
;             for (int q = 0; q < 16; ++q) { cf y = x[4 * (q & 3) + (q >> 2)]; if (q) y = cmul(y, w[q]); z[pass_pos<LST>(base, phb, q)] = y; }
	v_pk_add_f32 v[82:83], v[82:83], v[96:97] op_sel:[0,1] op_sel_hi:[1,0] neg_lo:[0,1]
	v_pk_add_f32 v[96:97], v[104:105], v[106:107]
	s_nop 0
	v_pk_add_f32 v[104:105], v[84:85], v[96:97]
	v_pk_add_f32 v[84:85], v[84:85], v[96:97] neg_lo:[0,1] neg_hi:[0,1]
	v_pk_add_f32 v[96:97], v[88:89], v[102:103] op_sel:[0,1] op_sel_hi:[1,0] neg_hi:[0,1]
	v_pk_add_f32 v[88:89], v[88:89], v[102:103] op_sel:[0,1] op_sel_hi:[1,0] neg_lo:[0,1]
	v_pk_add_f32 v[102:103], v[86:87], v[78:79]
	v_pk_add_f32 v[78:79], v[86:87], v[78:79] neg_lo:[0,1] neg_hi:[0,1]
	v_pk_add_f32 v[86:87], v[92:93], v[80:81]
	v_pk_add_f32 v[80:81], v[92:93], v[80:81] neg_lo:[0,1] neg_hi:[0,1]
	v_pk_add_f32 v[92:93], v[102:103], v[86:87]
	v_pk_add_f32 v[86:87], v[102:103], v[86:87] neg_lo:[0,1] neg_hi:[0,1]
	v_pk_add_f32 v[102:103], v[78:79], v[80:81] op_sel:[0,1] op_sel_hi:[1,0] neg_hi:[0,1]
	v_pk_add_f32 v[78:79], v[78:79], v[80:81] op_sel:[0,1] op_sel_hi:[1,0] neg_lo:[0,1]
	v_pk_add_f32 v[80:81], v[70:71], v[72:73]
	v_pk_add_f32 v[70:71], v[70:71], v[72:73] neg_lo:[0,1] neg_hi:[0,1]
	v_pk_add_f32 v[72:73], v[90:91], v[74:75]
	v_pk_add_f32 v[74:75], v[90:91], v[74:75] neg_lo:[0,1] neg_hi:[0,1]
	v_pk_add_f32 v[90:91], v[80:81], v[72:73]
	v_pk_add_f32 v[72:73], v[80:81], v[72:73] neg_lo:[0,1] neg_hi:[0,1]
	v_pk_add_f32 v[80:81], v[70:71], v[74:75] op_sel:[0,1] op_sel_hi:[1,0] neg_hi:[0,1]
	v_pk_add_f32 v[70:71], v[70:71], v[74:75] op_sel:[0,1] op_sel_hi:[1,0] neg_lo:[0,1]
	v_pk_add_f32 v[74:75], v[76:77], v[94:95]
	ds_write_b64 v29, v[74:75]
	v_pk_mul_f32 v[74:75], v[104:105], v[22:23] op_sel:[0,0] op_sel_hi:[0,1]
	v_pk_fma_f32 v[74:75], v[104:105], v[22:23], v[74:75] op_sel:[1,1,0] op_sel_hi:[1,0,1] neg_lo:[1,0,0]
	ds_write_b64 v37, v[74:75] offset:512
	v_pk_mul_f32 v[74:75], v[92:93], v[30:31] op_sel:[0,0] op_sel_hi:[0,1]
	v_pk_fma_f32 v[74:75], v[92:93], v[30:31], v[74:75] op_sel:[1,1,0] op_sel_hi:[1,0,1] neg_lo:[1,0,0]
	ds_write_b64 v41, v[74:75] offset:1024
	v_pk_mul_f32 v[74:75], v[90:91], v[38:39] op_sel:[0,0] op_sel_hi:[0,1]
	v_pk_fma_f32 v[74:75], v[90:91], v[38:39], v[74:75] op_sel:[1,1,0] op_sel_hi:[1,0,1] neg_lo:[1,0,0]
	ds_write_b64 v108, v[74:75] offset:1536
	v_pk_mul_f32 v[74:75], v[100:101], v[42:43] op_sel:[0,0] op_sel_hi:[0,1]
	v_pk_fma_f32 v[74:75], v[100:101], v[42:43], v[74:75] op_sel:[1,1,0] op_sel_hi:[1,0,1] neg_lo:[1,0,0]
	ds_write_b64 v109, v[74:75] offset:2048
	v_pk_mul_f32 v[74:75], v[96:97], v[48:49] op_sel:[0,0] op_sel_hi:[0,1]
	v_pk_fma_f32 v[74:75], v[96:97], v[48:49], v[74:75] op_sel:[1,1,0] op_sel_hi:[1,0,1] neg_lo:[1,0,0]
	ds_write_b64 v110, v[74:75] offset:2560
	v_pk_mul_f32 v[74:75], v[102:103], v[50:51] op_sel:[0,0] op_sel_hi:[0,1]
	v_pk_fma_f32 v[74:75], v[102:103], v[50:51], v[74:75] op_sel:[1,1,0] op_sel_hi:[1,0,1] neg_lo:[1,0,0]
	ds_write_b64 v111, v[74:75] offset:3072
	v_pk_mul_f32 v[74:75], v[80:81], v[52:53] op_sel:[0,0] op_sel_hi:[0,1]
	v_pk_fma_f32 v[74:75], v[80:81], v[52:53], v[74:75] op_sel:[1,1,0] op_sel_hi:[1,0,1] neg_lo:[1,0,0]
	ds_write_b64 v112, v[74:75] offset:3584
	v_pk_mul_f32 v[74:75], v[98:99], v[54:55] op_sel:[0,0] op_sel_hi:[0,1]
	v_pk_fma_f32 v[74:75], v[98:99], v[54:55], v[74:75] op_sel:[1,1,0] op_sel_hi:[1,0,1] neg_lo:[1,0,0]
	ds_write_b64 v113, v[74:75] offset:4096
	v_pk_mul_f32 v[74:75], v[84:85], v[56:57] op_sel:[0,0] op_sel_hi:[0,1]
	v_pk_fma_f32 v[74:75], v[84:85], v[56:57], v[74:75] op_sel:[1,1,0] op_sel_hi:[1,0,1] neg_lo:[1,0,0]
	ds_write_b64 v114, v[74:75] offset:4608
	v_pk_mul_f32 v[74:75], v[86:87], v[58:59] op_sel:[0,0] op_sel_hi:[0,1]
	v_pk_fma_f32 v[74:75], v[86:87], v[58:59], v[74:75] op_sel:[1,1,0] op_sel_hi:[1,0,1] neg_lo:[1,0,0]
	ds_write_b64 v115, v[74:75] offset:5120
	v_pk_mul_f32 v[74:75], v[72:73], v[60:61] op_sel:[0,0] op_sel_hi:[0,1]
	v_pk_fma_f32 v[72:73], v[72:73], v[60:61], v[74:75] op_sel:[1,1,0] op_sel_hi:[1,0,1] neg_lo:[1,0,0]
	ds_write_b64 v125, v[72:73] offset:5632
	v_pk_mul_f32 v[72:73], v[82:83], v[62:63] op_sel:[0,0] op_sel_hi:[0,1]
	v_pk_fma_f32 v[72:73], v[82:83], v[62:63], v[72:73] op_sel:[1,1,0] op_sel_hi:[1,0,1] neg_lo:[1,0,0]
	ds_write_b64 v182, v[72:73] offset:6144
	v_pk_mul_f32 v[72:73], v[88:89], v[64:65] op_sel:[0,0] op_sel_hi:[0,1]
	v_pk_fma_f32 v[72:73], v[88:89], v[64:65], v[72:73] op_sel:[1,1,0] op_sel_hi:[1,0,1] neg_lo:[1,0,0]
	ds_write_b64 v183, v[72:73] offset:6656
	v_pk_mul_f32 v[72:73], v[78:79], v[66:67] op_sel:[0,0] op_sel_hi:[0,1]
	v_pk_fma_f32 v[72:73], v[78:79], v[66:67], v[72:73] op_sel:[1,1,0] op_sel_hi:[1,0,1] neg_lo:[1,0,0]
	ds_write_b64 v216, v[72:73] offset:7168
	v_pk_mul_f32 v[72:73], v[70:71], v[68:69] op_sel:[0,0] op_sel_hi:[0,1]
	v_pk_fma_f32 v[70:71], v[70:71], v[68:69], v[72:73] op_sel:[1,1,0] op_sel_hi:[1,0,1] neg_lo:[1,0,0]
	ds_write_b64 v21, v[70:71] offset:7680
	s_cbranch_vccz .LBB0_1025
; template <bool INV, int LST, bool HALF = false> __device__ __forceinline__ void fft_pass16(LAS cf* z, const LAS cf* Thi, const LAS cf* Tlo, int tid) {
;     ...
;         if (LST == 10 || it == 0) {
;             const int e1 = j0 << (10 - LST);
;             w[1] = cmul(Thi[e1 >> 7], Tlo[e1 & 127]);
;             w[2] = cmul(w[1], w[1]); w[3] = cmul(w[2], w[1]); w[4] = cmul(w[2], w[2]); w[5] = cmul(w[4], w[1]); w[6] = cmul(w[3], w[3]); w[7] = cmul(w[4], w[3]); w[8] = cmul(w[4], w[4]);
; #pragma unroll
;             for (int q = 9; q < 16; ++q) w[q] = cmul(w[8], w[q - 8]);
;         }
.LBB0_1023:
	s_xor_b64 s[46:47], s[46:47], -1
	s_and_b64 vcc, exec, s[46:47]
	s_cbranch_vccnz .LBB0_1022
	ds_read_b64 v[22:23], v170
	ds_read_b64 v[30:31], v171
	s_waitcnt lgkmcnt(0)
	v_pk_mul_f32 v[38:39], v[22:23], v[30:31] op_sel:[0,0] op_sel_hi:[0,1]
	v_pk_fma_f32 v[22:23], v[22:23], v[30:31], v[38:39] op_sel:[1,1,0] op_sel_hi:[1,0,1] neg_lo:[1,0,0]
	v_pk_mul_f32 v[30:31], v[22:23], v[22:23] op_sel:[0,0] op_sel_hi:[0,1]
	v_pk_fma_f32 v[30:31], v[22:23], v[22:23], v[30:31] op_sel:[1,1,0] op_sel_hi:[1,0,1] neg_lo:[1,0,0]
	v_pk_mul_f32 v[38:39], v[30:31], v[22:23] op_sel:[0,0] op_sel_hi:[0,1]
	v_pk_mul_f32 v[42:43], v[30:31], v[30:31] op_sel:[0,0] op_sel_hi:[0,1]
	v_pk_fma_f32 v[38:39], v[30:31], v[22:23], v[38:39] op_sel:[1,1,0] op_sel_hi:[1,0,1] neg_lo:[1,0,0]
	v_pk_fma_f32 v[42:43], v[30:31], v[30:31], v[42:43] op_sel:[1,1,0] op_sel_hi:[1,0,1] neg_lo:[1,0,0]
	v_pk_mul_f32 v[48:49], v[42:43], v[22:23] op_sel:[0,0] op_sel_hi:[0,1]
	v_pk_mul_f32 v[50:51], v[38:39], v[38:39] op_sel:[0,0] op_sel_hi:[0,1]
	v_pk_mul_f32 v[52:53], v[42:43], v[38:39] op_sel:[0,0] op_sel_hi:[0,1]
	v_pk_mul_f32 v[54:55], v[42:43], v[42:43] op_sel:[0,0] op_sel_hi:[0,1]
	v_pk_fma_f32 v[48:49], v[42:43], v[22:23], v[48:49] op_sel:[1,1,0] op_sel_hi:[1,0,1] neg_lo:[1,0,0]
	v_pk_fma_f32 v[50:51], v[38:39], v[38:39], v[50:51] op_sel:[1,1,0] op_sel_hi:[1,0,1] neg_lo:[1,0,0]
	v_pk_fma_f32 v[52:53], v[42:43], v[38:39], v[52:53] op_sel:[1,1,0] op_sel_hi:[1,0,1] neg_lo:[1,0,0]
	v_pk_fma_f32 v[54:55], v[42:43], v[42:43], v[54:55] op_sel:[1,1,0] op_sel_hi:[1,0,1] neg_lo:[1,0,0]
	v_pk_mul_f32 v[56:57], v[54:55], v[22:23] op_sel:[0,0] op_sel_hi:[0,1]
	v_pk_mul_f32 v[58:59], v[54:55], v[30:31] op_sel:[0,0] op_sel_hi:[0,1]
	v_pk_mul_f32 v[60:61], v[54:55], v[38:39] op_sel:[0,0] op_sel_hi:[0,1]
	v_pk_mul_f32 v[62:63], v[54:55], v[42:43] op_sel:[0,0] op_sel_hi:[0,1]
	v_pk_mul_f32 v[64:65], v[54:55], v[48:49] op_sel:[0,0] op_sel_hi:[0,1]
	v_pk_mul_f32 v[66:67], v[54:55], v[50:51] op_sel:[0,0] op_sel_hi:[0,1]
	v_pk_mul_f32 v[68:69], v[54:55], v[52:53] op_sel:[0,0] op_sel_hi:[0,1]
	v_pk_fma_f32 v[56:57], v[54:55], v[22:23], v[56:57] op_sel:[1,1,0] op_sel_hi:[1,0,1] neg_lo:[1,0,0]
	v_pk_fma_f32 v[58:59], v[54:55], v[30:31], v[58:59] op_sel:[1,1,0] op_sel_hi:[1,0,1] neg_lo:[1,0,0]
	v_pk_fma_f32 v[60:61], v[54:55], v[38:39], v[60:61] op_sel:[1,1,0] op_sel_hi:[1,0,1] neg_lo:[1,0,0]
	v_pk_fma_f32 v[62:63], v[54:55], v[42:43], v[62:63] op_sel:[1,1,0] op_sel_hi:[1,0,1] neg_lo:[1,0,0]
	v_pk_fma_f32 v[64:65], v[54:55], v[48:49], v[64:65] op_sel:[1,1,0] op_sel_hi:[1,0,1] neg_lo:[1,0,0]
	v_pk_fma_f32 v[66:67], v[54:55], v[50:51], v[66:67] op_sel:[1,1,0] op_sel_hi:[1,0,1] neg_lo:[1,0,0]
	v_pk_fma_f32 v[68:69], v[54:55], v[52:53], v[68:69] op_sel:[1,1,0] op_sel_hi:[1,0,1] neg_lo:[1,0,0]
	s_branch .LBB0_1022

; __device__ __forceinline__ cf add_mib(cf a, cf b) { cf r; asm("v_pk_add_f32 %0, %1, %2 op_sel:[0,1] op_sel_hi:[1,0] neg_hi:[0,1]" : "=v"(r) : "v"(a), "v"(b)); return r; }
; __device__ __forceinline__ cf add_pib(cf a, cf b) { cf r; asm("v_pk_add_f32 %0, %1, %2 op_sel:[0,1] op_sel_hi:[1,0] neg_lo:[0,1]" : "=v"(r) : "v"(a), "v"(b)); return r; }
; template <bool INV, bool HALFIN = false> __device__ __forceinline__ void dft16(cf (&x)[16]) {
; #pragma unroll
;     for (int m2 = 0; m2 < 4; ++m2) {
;         if (HALFIN) { const cf a0 = x[m2], a1 = x[4 + m2]; x[m2] = a0 + a1; x[8 + m2] = a0 - a1; x[4 + m2] = add_mib(a0, a1); x[12 + m2] = add_pib(a0, a1); }
;         else dft4<INV>(x[m2], x[4 + m2], x[8 + m2], x[12 + m2]);
;     }
;     constexpr float C1 = 0.9238795325112867f, S1 = 0.3826834323650898f, C2 = 0.7071067811865476f;
;     x[4 * 1 + 1] = tw16<INV>(x[5], C1, S1);  x[4 * 1 + 2] = tw16<INV>(x[6], C2, C2);   x[4 * 1 + 3] = tw16<INV>(x[7], S1, C1);
;     x[4 * 2 + 1] = tw16<INV>(x[9], C2, C2);  x[4 * 2 + 2] = tw16<INV>(x[10], 0.f, 1.f); x[4 * 2 + 3] = tw16<INV>(x[11], -C2, C2);
;     x[4 * 3 + 1] = tw16<INV>(x[13], S1, C1); x[4 * 3 + 2] = tw16<INV>(x[14], -C2, C2); x[4 * 3 + 3] = tw16<INV>(x[15], -C1, -S1);
; #pragma unroll
;     for (int q1 = 0; q1 < 4; ++q1) dft4<INV>(x[4 * q1], x[4 * q1 + 1], x[4 * q1 + 2], x[4 * q1 + 3]);
; }
; template <bool INV, int LST, bool HALF = false> __device__ __forceinline__ void fft_pass16(LAS cf* z, const LAS cf* Thi, const LAS cf* Tlo, int tid) {
;     ...
;         const int g = tid + 512 * it; const int j0 = g & (st - 1); const int base = ((g >> LST) << (LST + 4)) + j0; const int phb = PH(base);
;         if (LST == 10 || it == 0) {
;             const int e1 = j0 << (10 - LST);
;             w[1] = cmul(Thi[e1 >> 7], Tlo[e1 & 127]);
;             w[2] = cmul(w[1], w[1]); w[3] = cmul(w[2], w[1]); w[4] = cmul(w[2], w[2]); w[5] = cmul(w[4], w[1]); w[6] = cmul(w[3], w[3]); w[7] = cmul(w[4], w[3]); w[8] = cmul(w[4], w[4]);
; #pragma unroll
;             for (int q = 9; q < 16; ++q) w[q] = cmul(w[8], w[q - 8]);
;         }
;         cf x[16];
;         if (!INV) {
; #pragma unroll
;             for (int m = 0; m < 16; ++m) { if (HALF && m >= 8) x[m] = (cf){0.f, 0.f}; else x[m] = z[pass_pos<LST>(base, phb, m)]; }
;             dft16<false, HALF>(x);
.LBB0_1026:
	v_add_u32_e32 v29, s21, v169
	v_and_or_b32 v29, v29, s71, v172
	v_lshl_add_u32 v37, v29, 3, v174
	v_xor_b32_e32 v110, 0x80, v37
	v_xor_b32_e32 v114, 0x100, v37
	v_xor_b32_e32 v111, 0xa0, v37
	v_xor_b32_e32 v115, 0x120, v37
	v_xor_b32_e32 v183, 0x180, v37
	v_xor_b32_e32 v108, 0x40, v37
	v_xor_b32_e32 v112, 0xc0, v37
	v_xor_b32_e32 v125, 0x140, v37
	v_xor_b32_e32 v216, 0x1a0, v37
	v_xor_b32_e32 v41, 0x20, v37
	v_xor_b32_e32 v109, 0x60, v37
	ds_read_b64 v[70:71], v37
	ds_read_b64 v[72:73], v41
	ds_read_b64 v[74:75], v108
	ds_read_b64 v[76:77], v109
	v_xor_b32_e32 v113, 0xe0, v37
	ds_read_b64 v[78:79], v110
	ds_read_b64 v[80:81], v111
	ds_read_b64 v[82:83], v112
	ds_read_b64 v[84:85], v113
	v_xor_b32_e32 v182, 0x160, v37
	ds_read_b64 v[86:87], v114
	ds_read_b64 v[88:89], v115
	ds_read_b64 v[90:91], v125
	ds_read_b64 v[92:93], v182
	v_xor_b32_e32 v217, 0x1c0, v37
	v_xor_b32_e32 v29, 0x1e0, v37
	ds_read_b64 v[94:95], v183
	ds_read_b64 v[96:97], v216
	ds_read_b64 v[98:99], v217
	ds_read_b64 v[100:101], v29
	s_waitcnt lgkmcnt(7)
	v_pk_add_f32 v[102:103], v[70:71], v[86:87]
	v_pk_add_f32 v[70:71], v[70:71], v[86:87] neg_lo:[0,1] neg_hi:[0,1]
	s_waitcnt lgkmcnt(3)
	v_pk_add_f32 v[86:87], v[78:79], v[94:95]
	v_pk_add_f32 v[78:79], v[78:79], v[94:95] neg_lo:[0,1] neg_hi:[0,1]
	v_pk_add_f32 v[94:95], v[102:103], v[86:87]
	v_pk_add_f32 v[86:87], v[102:103], v[86:87] neg_lo:[0,1] neg_hi:[0,1]
	v_pk_add_f32 v[102:103], v[70:71], v[78:79] op_sel:[0,1] op_sel_hi:[1,0] neg_hi:[0,1]
	v_pk_add_f32 v[70:71], v[70:71], v[78:79] op_sel:[0,1] op_sel_hi:[1,0] neg_lo:[0,1]
	v_pk_add_f32 v[78:79], v[72:73], v[88:89]
	v_pk_add_f32 v[72:73], v[72:73], v[88:89] neg_lo:[0,1] neg_hi:[0,1]
	s_waitcnt lgkmcnt(2)
	v_pk_add_f32 v[88:89], v[80:81], v[96:97]
	v_pk_add_f32 v[80:81], v[80:81], v[96:97] neg_lo:[0,1] neg_hi:[0,1]
	v_pk_add_f32 v[96:97], v[78:79], v[88:89]
	v_pk_add_f32 v[78:79], v[78:79], v[88:89] neg_lo:[0,1] neg_hi:[0,1]
	v_pk_add_f32 v[88:89], v[72:73], v[80:81] op_sel:[0,1] op_sel_hi:[1,0] neg_hi:[0,1]
	v_pk_add_f32 v[72:73], v[72:73], v[80:81] op_sel:[0,1] op_sel_hi:[1,0] neg_lo:[0,1]
	v_pk_add_f32 v[80:81], v[74:75], v[90:91]
	v_pk_add_f32 v[74:75], v[74:75], v[90:91] neg_lo:[0,1] neg_hi:[0,1]
	s_waitcnt lgkmcnt(1)
	v_pk_add_f32 v[90:91], v[82:83], v[98:99]
	v_pk_add_f32 v[82:83], v[82:83], v[98:99] neg_lo:[0,1] neg_hi:[0,1]
	v_pk_add_f32 v[98:99], v[80:81], v[90:91]
	v_pk_add_f32 v[80:81], v[80:81], v[90:91] neg_lo:[0,1] neg_hi:[0,1]
	v_pk_add_f32 v[90:91], v[74:75], v[82:83] op_sel:[0,1] op_sel_hi:[1,0] neg_hi:[0,1]
	v_pk_add_f32 v[74:75], v[74:75], v[82:83] op_sel:[0,1] op_sel_hi:[1,0] neg_lo:[0,1]
	v_pk_add_f32 v[82:83], v[76:77], v[92:93]
	v_pk_add_f32 v[76:77], v[76:77], v[92:93] neg_lo:[0,1] neg_hi:[0,1]
	s_waitcnt lgkmcnt(0)
	v_pk_add_f32 v[92:93], v[84:85], v[100:101]
	v_pk_add_f32 v[84:85], v[84:85], v[100:101] neg_lo:[0,1] neg_hi:[0,1]
	v_pk_add_f32 v[100:101], v[82:83], v[92:93]
	v_pk_add_f32 v[82:83], v[82:83], v[92:93] neg_lo:[0,1] neg_hi:[0,1]
	v_pk_add_f32 v[92:93], v[76:77], v[84:85] op_sel:[0,1] op_sel_hi:[1,0] neg_hi:[0,1]
	v_pk_add_f32 v[76:77], v[76:77], v[84:85] op_sel:[0,1] op_sel_hi:[1,0] neg_lo:[0,1]
	v_pk_mul_f32 v[84:85], v[88:89], s[22:23] op_sel_hi:[1,0]
	s_mov_b32 s48, s37
	v_pk_fma_f32 v[104:105], v[88:89], s[20:21], v[84:85] op_sel:[0,0,1] op_sel_hi:[1,0,0] neg_hi:[0,0,1]
	s_mov_b32 s49, s22
	v_pk_mul_f32 v[84:85], v[90:91], s[24:25] op_sel_hi:[1,0]
	s_andn2_b64 vcc, exec, s[46:47]
	v_pk_fma_f32 v[88:89], v[90:91], s[24:25], v[84:85] op_sel:[0,0,1] op_sel_hi:[1,0,0] neg_hi:[0,0,1]
	v_pk_mul_f32 v[90:91], v[92:93], s[20:21] op_sel_hi:[1,0]
	s_nop 0
	v_pk_fma_f32 v[106:107], v[92:93], s[22:23], v[90:91] op_sel:[0,0,1] op_sel_hi:[1,0,0] neg_hi:[0,0,1]
	v_pk_add_f32 v[84:85], v[102:103], v[88:89]
	v_pk_mul_f32 v[90:91], v[78:79], s[24:25] op_sel_hi:[1,0]
	v_pk_add_f32 v[88:89], v[102:103], v[88:89] neg_lo:[0,1] neg_hi:[0,1]
	v_pk_fma_f32 v[92:93], v[78:79], s[24:25], v[90:91] op_sel:[0,0,1] op_sel_hi:[1,0,0] neg_hi:[0,0,1]
	v_pk_add_f32 v[102:103], v[104:105], v[106:107] neg_lo:[0,1] neg_hi:[0,1]
	v_pk_fma_f32 v[78:79], v[80:81], 0, v[80:81] op_sel:[0,0,1] op_sel_hi:[1,0,0]
	v_pk_fma_f32 v[80:81], v[80:81], 0, v[80:81] op_sel:[0,0,1] op_sel_hi:[1,0,0] neg_lo:[0,0,1] neg_hi:[0,0,1]
	s_mov_b64 s[46:47], 0
	v_mul_f32_e32 v80, 0x3f3504f3, v82
	v_mov_b32_e32 v79, v81
	v_pk_fma_f32 v[80:81], v[82:83], s[24:25], v[80:81] op_sel:[1,0,0] op_sel_hi:[1,1,0] neg_lo:[0,0,1] neg_hi:[0,0,1]
	v_pk_mul_f32 v[82:83], v[72:73], s[20:21] op_sel_hi:[1,0]
	s_movk_i32 s21, 0x2000
	v_pk_fma_f32 v[90:91], v[72:73], s[22:23], v[82:83] op_sel:[0,0,1] op_sel_hi:[1,0,0]
	v_pk_fma_f32 v[72:73], v[72:73], s[22:23], v[82:83] op_sel:[0,0,1] op_sel_hi:[1,0,0] neg_lo:[0,0,1] neg_hi:[0,0,1]
	v_pk_add_f32 v[82:83], v[94:95], v[98:99] neg_lo:[0,1] neg_hi:[0,1]
	v_mul_f32_e32 v72, 0x3f3504f3, v74
	v_mov_b32_e32 v91, v73
	v_pk_fma_f32 v[72:73], v[74:75], s[24:25], v[72:73] op_sel:[1,0,0] op_sel_hi:[1,1,0] neg_lo:[0,0,1] neg_hi:[0,0,1]
	v_pk_mul_f32 v[74:75], v[76:77], s[36:37] op_sel:[1,0]
	s_nop 0
	v_pk_fma_f32 v[74:75], v[76:77], s[48:49], v[74:75] op_sel_hi:[0,1,1]
	v_pk_add_f32 v[76:77], v[94:95], v[98:99]
	v_pk_add_f32 v[94:95], v[96:97], v[100:101]
	v_pk_add_f32 v[96:97], v[96:97], v[100:101] neg_lo:[0,1] neg_hi:[0,1]
	v_pk_add_f32 v[98:99], v[76:77], v[94:95] neg_lo:[0,1] neg_hi:[0,1]
	v_pk_add_f32 v[100:101], v[82:83], v[96:97] op_sel:[0,1] op_sel_hi:[1,0] neg_hi:[0,1]
	v_pk_add_f32 v[82:83], v[82:83], v[96:97] op_sel:[0,1] op_sel_hi:[1,0] neg_lo:[0,1]
	v_pk_add_f32 v[96:97], v[104:105], v[106:107]
	s_nop 0
	v_pk_add_f32 v[104:105], v[84:85], v[96:97]
; template <bool INV, bool HALFIN = false> __device__ __forceinline__ void dft16(cf (&x)[16]) {
;     ...
;     x[4 * 3 + 1] = tw16<INV>(x[13], S1, C1); x[4 * 3 + 2] = tw16<INV>(x[14], -C2, C2); x[4 * 3 + 3] = tw16<INV>(x[15], -C1, -S1);
; #pragma unroll
;     for (int q1 = 0; q1 < 4; ++q1) dft4<INV>(x[4 * q1], x[4 * q1 + 1], x[4 * q1 + 2], x[4 * q1 + 3]);
; }
; template <bool INV, int LST, bool HALF = false> __device__ __forceinline__ void fft_pass16(LAS cf* z, const LAS cf* Thi, const LAS cf* Tlo, int tid) {
;     ...
;             for (int q = 0; q < 16; ++q) { cf y = x[4 * (q & 3) + (q >> 2)]; if (q) y = cmul(y, w[q]); z[pass_pos<LST>(base, phb, q)] = y; }
	v_pk_add_f32 v[84:85], v[84:85], v[96:97] neg_lo:[0,1] neg_hi:[0,1]
	v_pk_add_f32 v[96:97], v[88:89], v[102:103] op_sel:[0,1] op_sel_hi:[1,0] neg_hi:[0,1]
	v_pk_add_f32 v[88:89], v[88:89], v[102:103] op_sel:[0,1] op_sel_hi:[1,0] neg_lo:[0,1]
	v_pk_add_f32 v[102:103], v[86:87], v[78:79]
	v_pk_add_f32 v[78:79], v[86:87], v[78:79] neg_lo:[0,1] neg_hi:[0,1]
	v_pk_add_f32 v[86:87], v[92:93], v[80:81]
	v_pk_add_f32 v[80:81], v[92:93], v[80:81] neg_lo:[0,1] neg_hi:[0,1]
	v_pk_add_f32 v[92:93], v[102:103], v[86:87]
	v_pk_add_f32 v[86:87], v[102:103], v[86:87] neg_lo:[0,1] neg_hi:[0,1]
	v_pk_add_f32 v[102:103], v[78:79], v[80:81] op_sel:[0,1] op_sel_hi:[1,0] neg_hi:[0,1]
	v_pk_add_f32 v[78:79], v[78:79], v[80:81] op_sel:[0,1] op_sel_hi:[1,0] neg_lo:[0,1]
	v_pk_add_f32 v[80:81], v[70:71], v[72:73]
	v_pk_add_f32 v[70:71], v[70:71], v[72:73] neg_lo:[0,1] neg_hi:[0,1]
	v_pk_add_f32 v[72:73], v[90:91], v[74:75]
	v_pk_add_f32 v[74:75], v[90:91], v[74:75] neg_lo:[0,1] neg_hi:[0,1]
	v_pk_add_f32 v[90:91], v[80:81], v[72:73]
	v_pk_add_f32 v[72:73], v[80:81], v[72:73] neg_lo:[0,1] neg_hi:[0,1]
	v_pk_add_f32 v[80:81], v[70:71], v[74:75] op_sel:[0,1] op_sel_hi:[1,0] neg_hi:[0,1]
	v_pk_add_f32 v[70:71], v[70:71], v[74:75] op_sel:[0,1] op_sel_hi:[1,0] neg_lo:[0,1]
	v_pk_add_f32 v[74:75], v[76:77], v[94:95]
	ds_write_b64 v37, v[74:75]
	v_pk_mul_f32 v[74:75], v[104:105], v[22:23] op_sel:[0,0] op_sel_hi:[0,1]
	v_pk_fma_f32 v[74:75], v[104:105], v[22:23], v[74:75] op_sel:[1,1,0] op_sel_hi:[1,0,1] neg_lo:[1,0,0]
	ds_write_b64 v41, v[74:75]
	v_pk_mul_f32 v[74:75], v[92:93], v[30:31] op_sel:[0,0] op_sel_hi:[0,1]
	v_pk_fma_f32 v[74:75], v[92:93], v[30:31], v[74:75] op_sel:[1,1,0] op_sel_hi:[1,0,1] neg_lo:[1,0,0]
	ds_write_b64 v108, v[74:75]
	v_pk_mul_f32 v[74:75], v[90:91], v[38:39] op_sel:[0,0] op_sel_hi:[0,1]
	v_pk_fma_f32 v[74:75], v[90:91], v[38:39], v[74:75] op_sel:[1,1,0] op_sel_hi:[1,0,1] neg_lo:[1,0,0]
	ds_write_b64 v109, v[74:75]
	v_pk_mul_f32 v[74:75], v[100:101], v[42:43] op_sel:[0,0] op_sel_hi:[0,1]
	v_pk_fma_f32 v[74:75], v[100:101], v[42:43], v[74:75] op_sel:[1,1,0] op_sel_hi:[1,0,1] neg_lo:[1,0,0]
	ds_write_b64 v110, v[74:75]
	v_pk_mul_f32 v[74:75], v[96:97], v[48:49] op_sel:[0,0] op_sel_hi:[0,1]
	v_pk_fma_f32 v[74:75], v[96:97], v[48:49], v[74:75] op_sel:[1,1,0] op_sel_hi:[1,0,1] neg_lo:[1,0,0]
	ds_write_b64 v111, v[74:75]
	v_pk_mul_f32 v[74:75], v[102:103], v[50:51] op_sel:[0,0] op_sel_hi:[0,1]
	v_pk_fma_f32 v[74:75], v[102:103], v[50:51], v[74:75] op_sel:[1,1,0] op_sel_hi:[1,0,1] neg_lo:[1,0,0]
	ds_write_b64 v112, v[74:75]
	v_pk_mul_f32 v[74:75], v[80:81], v[52:53] op_sel:[0,0] op_sel_hi:[0,1]
	v_pk_fma_f32 v[74:75], v[80:81], v[52:53], v[74:75] op_sel:[1,1,0] op_sel_hi:[1,0,1] neg_lo:[1,0,0]
	ds_write_b64 v113, v[74:75]
	v_pk_mul_f32 v[74:75], v[98:99], v[54:55] op_sel:[0,0] op_sel_hi:[0,1]
	v_pk_fma_f32 v[74:75], v[98:99], v[54:55], v[74:75] op_sel:[1,1,0] op_sel_hi:[1,0,1] neg_lo:[1,0,0]
	ds_write_b64 v114, v[74:75]
	v_pk_mul_f32 v[74:75], v[84:85], v[56:57] op_sel:[0,0] op_sel_hi:[0,1]
	v_pk_fma_f32 v[74:75], v[84:85], v[56:57], v[74:75] op_sel:[1,1,0] op_sel_hi:[1,0,1] neg_lo:[1,0,0]
	ds_write_b64 v115, v[74:75]
	v_pk_mul_f32 v[74:75], v[86:87], v[58:59] op_sel:[0,0] op_sel_hi:[0,1]
	v_pk_fma_f32 v[74:75], v[86:87], v[58:59], v[74:75] op_sel:[1,1,0] op_sel_hi:[1,0,1] neg_lo:[1,0,0]
	ds_write_b64 v125, v[74:75]
	v_pk_mul_f32 v[74:75], v[72:73], v[60:61] op_sel:[0,0] op_sel_hi:[0,1]
	v_pk_fma_f32 v[72:73], v[72:73], v[60:61], v[74:75] op_sel:[1,1,0] op_sel_hi:[1,0,1] neg_lo:[1,0,0]
	ds_write_b64 v182, v[72:73]
	v_pk_mul_f32 v[72:73], v[82:83], v[62:63] op_sel:[0,0] op_sel_hi:[0,1]
	v_pk_fma_f32 v[72:73], v[82:83], v[62:63], v[72:73] op_sel:[1,1,0] op_sel_hi:[1,0,1] neg_lo:[1,0,0]
	ds_write_b64 v183, v[72:73]
	v_pk_mul_f32 v[72:73], v[88:89], v[64:65] op_sel:[0,0] op_sel_hi:[0,1]
	v_pk_fma_f32 v[72:73], v[88:89], v[64:65], v[72:73] op_sel:[1,1,0] op_sel_hi:[1,0,1] neg_lo:[1,0,0]
	ds_write_b64 v216, v[72:73]
	v_pk_mul_f32 v[72:73], v[78:79], v[66:67] op_sel:[0,0] op_sel_hi:[0,1]
	v_pk_fma_f32 v[72:73], v[78:79], v[66:67], v[72:73] op_sel:[1,1,0] op_sel_hi:[1,0,1] neg_lo:[1,0,0]
	ds_write_b64 v217, v[72:73]
	v_pk_mul_f32 v[72:73], v[70:71], v[68:69] op_sel:[0,0] op_sel_hi:[0,1]
	v_pk_fma_f32 v[70:71], v[70:71], v[68:69], v[72:73] op_sel:[1,1,0] op_sel_hi:[1,0,1] neg_lo:[1,0,0]
	ds_write_b64 v29, v[70:71]
	s_cbranch_vccz .LBB0_1029
; template <bool INV, int LST, bool HALF = false> __device__ __forceinline__ void fft_pass16(LAS cf* z, const LAS cf* Thi, const LAS cf* Tlo, int tid) {
;     ...
;         if (LST == 10 || it == 0) {
;             const int e1 = j0 << (10 - LST);
;             w[1] = cmul(Thi[e1 >> 7], Tlo[e1 & 127]);
;             w[2] = cmul(w[1], w[1]); w[3] = cmul(w[2], w[1]); w[4] = cmul(w[2], w[2]); w[5] = cmul(w[4], w[1]); w[6] = cmul(w[3], w[3]); w[7] = cmul(w[4], w[3]); w[8] = cmul(w[4], w[4]);
; #pragma unroll
;             for (int q = 9; q < 16; ++q) w[q] = cmul(w[8], w[q - 8]);
;         }
.LBB0_1027:
	s_xor_b64 s[46:47], s[46:47], -1
	s_and_b64 vcc, exec, s[46:47]
	v_add_u32_e32 v21, 0x20000, v228
	s_cbranch_vccnz .LBB0_1026
	v_mov_b32_e32 v22, s70
	ds_read_b64 v[22:23], v22
	ds_read_b64 v[30:31], v21
	s_waitcnt lgkmcnt(0)
	v_pk_mul_f32 v[38:39], v[30:31], v[22:23] op_sel:[0,0] op_sel_hi:[0,1]
	v_pk_fma_f32 v[22:23], v[30:31], v[22:23], v[38:39] op_sel:[1,1,0] op_sel_hi:[1,0,1] neg_lo:[1,0,0]
	v_pk_mul_f32 v[30:31], v[22:23], v[22:23] op_sel:[0,0] op_sel_hi:[0,1]
	v_pk_fma_f32 v[30:31], v[22:23], v[22:23], v[30:31] op_sel:[1,1,0] op_sel_hi:[1,0,1] neg_lo:[1,0,0]
	v_pk_mul_f32 v[38:39], v[30:31], v[22:23] op_sel:[0,0] op_sel_hi:[0,1]
	v_pk_mul_f32 v[42:43], v[30:31], v[30:31] op_sel:[0,0] op_sel_hi:[0,1]
	v_pk_fma_f32 v[38:39], v[30:31], v[22:23], v[38:39] op_sel:[1,1,0] op_sel_hi:[1,0,1] neg_lo:[1,0,0]
	v_pk_fma_f32 v[42:43], v[30:31], v[30:31], v[42:43] op_sel:[1,1,0] op_sel_hi:[1,0,1] neg_lo:[1,0,0]
	v_pk_mul_f32 v[48:49], v[42:43], v[22:23] op_sel:[0,0] op_sel_hi:[0,1]
	v_pk_mul_f32 v[50:51], v[38:39], v[38:39] op_sel:[0,0] op_sel_hi:[0,1]
	v_pk_mul_f32 v[52:53], v[42:43], v[38:39] op_sel:[0,0] op_sel_hi:[0,1]
	v_pk_mul_f32 v[54:55], v[42:43], v[42:43] op_sel:[0,0] op_sel_hi:[0,1]
	v_pk_fma_f32 v[48:49], v[42:43], v[22:23], v[48:49] op_sel:[1,1,0] op_sel_hi:[1,0,1] neg_lo:[1,0,0]
	v_pk_fma_f32 v[50:51], v[38:39], v[38:39], v[50:51] op_sel:[1,1,0] op_sel_hi:[1,0,1] neg_lo:[1,0,0]
	v_pk_fma_f32 v[52:53], v[42:43], v[38:39], v[52:53] op_sel:[1,1,0] op_sel_hi:[1,0,1] neg_lo:[1,0,0]
	v_pk_fma_f32 v[54:55], v[42:43], v[42:43], v[54:55] op_sel:[1,1,0] op_sel_hi:[1,0,1] neg_lo:[1,0,0]
	v_pk_mul_f32 v[56:57], v[54:55], v[22:23] op_sel:[0,0] op_sel_hi:[0,1]
	v_pk_mul_f32 v[58:59], v[54:55], v[30:31] op_sel:[0,0] op_sel_hi:[0,1]
	v_pk_mul_f32 v[60:61], v[54:55], v[38:39] op_sel:[0,0] op_sel_hi:[0,1]
	v_pk_mul_f32 v[62:63], v[54:55], v[42:43] op_sel:[0,0] op_sel_hi:[0,1]
	v_pk_mul_f32 v[64:65], v[54:55], v[48:49] op_sel:[0,0] op_sel_hi:[0,1]
	v_pk_mul_f32 v[66:67], v[54:55], v[50:51] op_sel:[0,0] op_sel_hi:[0,1]
	v_pk_mul_f32 v[68:69], v[54:55], v[52:53] op_sel:[0,0] op_sel_hi:[0,1]
	v_pk_fma_f32 v[56:57], v[54:55], v[22:23], v[56:57] op_sel:[1,1,0] op_sel_hi:[1,0,1] neg_lo:[1,0,0]
	v_pk_fma_f32 v[58:59], v[54:55], v[30:31], v[58:59] op_sel:[1,1,0] op_sel_hi:[1,0,1] neg_lo:[1,0,0]
	v_pk_fma_f32 v[60:61], v[54:55], v[38:39], v[60:61] op_sel:[1,1,0] op_sel_hi:[1,0,1] neg_lo:[1,0,0]
	v_pk_fma_f32 v[62:63], v[54:55], v[42:43], v[62:63] op_sel:[1,1,0] op_sel_hi:[1,0,1] neg_lo:[1,0,0]
	v_pk_fma_f32 v[64:65], v[54:55], v[48:49], v[64:65] op_sel:[1,1,0] op_sel_hi:[1,0,1] neg_lo:[1,0,0]
	v_pk_fma_f32 v[66:67], v[54:55], v[50:51], v[66:67] op_sel:[1,1,0] op_sel_hi:[1,0,1] neg_lo:[1,0,0]
	v_pk_fma_f32 v[68:69], v[54:55], v[52:53], v[68:69] op_sel:[1,1,0] op_sel_hi:[1,0,1] neg_lo:[1,0,0]
	s_branch .LBB0_1026

; #define LAS __attribute__((address_space(3)))
; __device__ __forceinline__ cf cconj(cf a) { return (cf){a.x, -a.y}; }
; __device__ __forceinline__ int p_of_k(int k) { return ((k & 15) << 10) | (((k >> 4) & 15) << 6) | (((k >> 8) & 15) << 2) | (k >> 12); }
; template <bool INV> __device__ __forceinline__ void fft_pass4(LAS cf* z, int tid) {
; #pragma unroll 2
;     for (int it = 0; it < 8; ++it) {
;         const int g = tid + 512 * it; const int pb = PH(4 * g);
;         f32x4 v0 = *(LAS f32x4*)(z + pb), v1 = *(LAS f32x4*)(z + pb + 2);
;         cf a0 = {v0[0], v0[1]}, a1 = {v0[2], v0[3]}, a2 = {v1[0], v1[1]}, a3 = {v1[2], v1[3]};
;         dft4<INV>(a0, a1, a2, a3);
;         *(LAS f32x4*)(z + pb) = (f32x4){a0.x, a0.y, a1.x, a1.y}; *(LAS f32x4*)(z + pb + 2) = (f32x4){a2.x, a2.y, a3.x, a3.y};
;     }
;     __syncthreads();
; }
; __device__ __forceinline__ void hyena_phase(LAS unsigned char* L, const Args& a, int vcu, int G) {
;     ...
;         {
; #pragma unroll
;             for (int i = 0; i < 8; ++i) {
;                 const int g = tid + 512 * i;
;                 const int kg = (g >> 8) | (((g >> 4) & 15) << 4) | ((g & 15) << 8);
;                 const int pp0 = p_of_k((NFFT - kg) & (NFFT - 1)), pp1 = p_of_k(12288 - kg);
;                 const int p0 = PH(4 * g);
;                 const f32x4 zz = *(LAS f32x4*)(z + p0);
;                 const cf zk0 = {zz[0], zz[1]}, zk1 = {zz[2], zz[3]};
;                 const cf zn0 = z[PH(pp0)], zn1 = z[PH(pp1)];
;                 const f32x4 s0 = sd[2 * i], s1 = sd[2 * i + 1];
;                 const cf S0 = {s0[0], s0[1]}, D0 = {s0[2], s0[3]}, S1 = {s1[0], s1[1]}, D1 = {s1[2], s1[3]};
;                 const cf w0 = cmul(zk0, S0) + cmul(cconj(zn0), D0), w1 = cmul(zk1, S1) + cmul(cconj(zn1), D1);
;                 *(LAS f32x4*)(z + p0) = (f32x4){w0.x, w0.y, w1.x, w1.y};
;                 if (kg != 0) z[PH(pp0)] = cmulc(zn0, S0) + cconj(cmul(zk0, D0));
;                 z[PH(pp1)] = cmulc(zn1, S1) + cconj(cmul(zk1, D1));
;             }
.LBB0_1030:
	v_add_u32_e32 v22, s21, v160
	v_xor_b32_e32 v23, v22, v176
	v_lshl_add_u32 v29, v23, 3, 0
	ds_read_b128 v[112:115], v29
	ds_read_b128 v[230:233], v29 offset:16
	v_add_u32_e32 v22, 0x800, v22
	v_xor_b32_e32 v22, v22, v176
	v_lshl_add_u32 v37, v22, 3, 0
	s_addk_i32 s21, 0x1000
	s_waitcnt lgkmcnt(0)
	v_pk_add_f32 v[22:23], v[112:113], v[230:231]
	v_pk_add_f32 v[38:39], v[114:115], v[232:233]
	v_pk_add_f32 v[30:31], v[112:113], v[230:231] neg_lo:[0,1] neg_hi:[0,1]
	v_pk_add_f32 v[42:43], v[114:115], v[232:233] neg_lo:[0,1] neg_hi:[0,1]
	v_pk_add_f32 v[112:113], v[22:23], v[38:39]
	v_pk_add_f32 v[114:115], v[30:31], v[42:43] op_sel:[0,1] op_sel_hi:[1,0] neg_hi:[0,1]
	v_pk_add_f32 v[230:231], v[22:23], v[38:39] neg_lo:[0,1] neg_hi:[0,1]
	v_pk_add_f32 v[232:233], v[30:31], v[42:43] op_sel:[0,1] op_sel_hi:[1,0] neg_lo:[0,1]
	ds_write_b128 v29, v[112:115]
	ds_write_b128 v29, v[230:233] offset:16
	ds_read_b128 v[112:115], v37
	ds_read_b128 v[230:233], v37 offset:16
	s_cmpk_lg_i32 s21, 0x4000
	s_waitcnt lgkmcnt(0)
	v_pk_add_f32 v[22:23], v[112:113], v[230:231]
	v_pk_add_f32 v[38:39], v[114:115], v[232:233]
	v_pk_add_f32 v[30:31], v[112:113], v[230:231] neg_lo:[0,1] neg_hi:[0,1]
	v_pk_add_f32 v[42:43], v[114:115], v[232:233] neg_lo:[0,1] neg_hi:[0,1]
	v_pk_add_f32 v[112:113], v[22:23], v[38:39]
	v_pk_add_f32 v[114:115], v[30:31], v[42:43] op_sel:[0,1] op_sel_hi:[1,0] neg_hi:[0,1]
	v_pk_add_f32 v[230:231], v[22:23], v[38:39] neg_lo:[0,1] neg_hi:[0,1]
	v_pk_add_f32 v[232:233], v[30:31], v[42:43] op_sel:[0,1] op_sel_hi:[1,0] neg_lo:[0,1]
	ds_write_b128 v37, v[112:115]
	ds_write_b128 v37, v[230:233] offset:16
	s_cbranch_scc1 .LBB0_1030
	s_waitcnt lgkmcnt(0)
	s_barrier
	ds_read_b128 v[112:115], v186
	ds_read_b64 v[30:31], v187
	ds_read_b64 v[22:23], v188
	s_waitcnt vmcnt(14) lgkmcnt(2)
	v_pk_mul_f32 v[38:39], v[112:113], v[108:109] op_sel:[0,0] op_sel_hi:[0,1]
	s_waitcnt lgkmcnt(1)
	v_pk_add_f32 v[42:43], v[30:31], 0 neg_lo:[1,1] neg_hi:[1,1]
	v_pk_fma_f32 v[38:39], v[112:113], v[108:109], v[38:39] op_sel:[1,1,0] op_sel_hi:[1,0,1] neg_lo:[1,0,0]
	v_mov_b32_e32 v42, v30
	v_pk_mul_f32 v[230:231], v[42:43], v[110:111] op_sel:[0,0] op_sel_hi:[0,1]
	v_pk_fma_f32 v[42:43], v[42:43], v[110:111], v[230:231] op_sel:[1,1,0] op_sel_hi:[1,0,1] neg_lo:[1,0,0]
	v_pk_mul_f32 v[230:231], v[114:115], v[104:105] op_sel:[0,0] op_sel_hi:[0,1]
	v_pk_fma_f32 v[232:233], v[114:115], v[104:105], v[230:231] op_sel:[1,1,0] op_sel_hi:[1,0,1] neg_lo:[1,0,0]
	s_waitcnt lgkmcnt(0)
	v_pk_add_f32 v[230:231], v[22:23], 0 neg_lo:[1,1] neg_hi:[1,1]
	s_nop 0
	v_mov_b32_e32 v230, v22
	v_pk_mul_f32 v[234:235], v[230:231], v[106:107] op_sel:[0,0] op_sel_hi:[0,1]
	v_pk_fma_f32 v[234:235], v[230:231], v[106:107], v[234:235] op_sel:[1,1,0] op_sel_hi:[1,0,1] neg_lo:[1,0,0]
	v_pk_add_f32 v[230:231], v[38:39], v[42:43]
	v_pk_add_f32 v[232:233], v[232:233], v[234:235]
	ds_write_b128 v186, v[230:233]
	s_and_saveexec_b64 s[46:47], s[8:9]
	s_cbranch_execz .LBB0_1033
	v_pk_mul_f32 v[38:39], v[30:31], v[108:109] op_sel:[0,0] op_sel_hi:[0,1] neg_hi:[0,1]
	v_pk_fma_f32 v[30:31], v[30:31], v[108:109], v[38:39] op_sel:[1,1,0] op_sel_hi:[1,0,1]
	v_pk_mul_f32 v[38:39], v[112:113], v[110:111] op_sel:[0,0] op_sel_hi:[0,1]
	v_pk_fma_f32 v[38:39], v[112:113], v[110:111], v[38:39] op_sel:[1,1,0] op_sel_hi:[1,0,1] neg_lo:[1,0,0]
	v_pk_add_f32 v[42:43], v[38:39], 0 neg_lo:[1,1] neg_hi:[1,1]
	s_nop 0
	v_mov_b32_e32 v39, v43
	v_pk_add_f32 v[30:31], v[30:31], v[38:39]
	ds_write_b64 v187, v[30:31]
.LBB0_1033:
	s_or_b64 exec, exec, s[46:47]
	v_pk_mul_f32 v[30:31], v[22:23], v[104:105] op_sel:[0,0] op_sel_hi:[0,1] neg_hi:[0,1]
	v_pk_fma_f32 v[22:23], v[22:23], v[104:105], v[30:31] op_sel:[1,1,0] op_sel_hi:[1,0,1]
	v_pk_mul_f32 v[30:31], v[114:115], v[106:107] op_sel:[0,0] op_sel_hi:[0,1]
	v_pk_fma_f32 v[30:31], v[114:115], v[106:107], v[30:31] op_sel:[1,1,0] op_sel_hi:[1,0,1] neg_lo:[1,0,0]
	v_pk_add_f32 v[38:39], v[30:31], 0 neg_lo:[1,1] neg_hi:[1,1]
	s_nop 0
	v_mov_b32_e32 v31, v39
	v_pk_add_f32 v[22:23], v[22:23], v[30:31]
	ds_write_b64 v188, v[22:23]
	ds_read_b128 v[104:107], v189
	ds_read_b64 v[22:23], v190
	ds_read_b64 v[30:31], v191
	s_waitcnt vmcnt(12) lgkmcnt(2)
	v_pk_mul_f32 v[38:39], v[104:105], v[100:101] op_sel:[0,0] op_sel_hi:[0,1]
	s_waitcnt lgkmcnt(1)
	v_pk_add_f32 v[42:43], v[22:23], 0 neg_lo:[1,1] neg_hi:[1,1]
	v_pk_fma_f32 v[38:39], v[104:105], v[100:101], v[38:39] op_sel:[1,1,0] op_sel_hi:[1,0,1] neg_lo:[1,0,0]
	v_mov_b32_e32 v42, v22
	v_pk_mul_f32 v[108:109], v[42:43], v[102:103] op_sel:[0,0] op_sel_hi:[0,1]
	v_pk_fma_f32 v[42:43], v[42:43], v[102:103], v[108:109] op_sel:[1,1,0] op_sel_hi:[1,0,1] neg_lo:[1,0,0]
	v_pk_mul_f32 v[108:109], v[106:107], v[96:97] op_sel:[0,0] op_sel_hi:[0,1]
	v_pk_fma_f32 v[110:111], v[106:107], v[96:97], v[108:109] op_sel:[1,1,0] op_sel_hi:[1,0,1] neg_lo:[1,0,0]
	s_waitcnt lgkmcnt(0)
	v_pk_add_f32 v[108:109], v[30:31], 0 neg_lo:[1,1] neg_hi:[1,1]
	s_nop 0
	v_mov_b32_e32 v108, v30
	v_pk_mul_f32 v[112:113], v[108:109], v[98:99] op_sel:[0,0] op_sel_hi:[0,1]
	v_pk_fma_f32 v[112:113], v[108:109], v[98:99], v[112:113] op_sel:[1,1,0] op_sel_hi:[1,0,1] neg_lo:[1,0,0]
	v_pk_add_f32 v[108:109], v[38:39], v[42:43]
	v_pk_mul_f32 v[38:39], v[22:23], v[100:101] op_sel:[0,0] op_sel_hi:[0,1] neg_hi:[0,1]
	v_pk_add_f32 v[110:111], v[110:111], v[112:113]
	v_pk_fma_f32 v[22:23], v[22:23], v[100:101], v[38:39] op_sel:[1,1,0] op_sel_hi:[1,0,1]
	v_pk_mul_f32 v[38:39], v[104:105], v[102:103] op_sel:[0,0] op_sel_hi:[0,1]
	ds_write_b128 v189, v[108:111]
	v_pk_fma_f32 v[38:39], v[104:105], v[102:103], v[38:39] op_sel:[1,1,0] op_sel_hi:[1,0,1] neg_lo:[1,0,0]
	v_pk_add_f32 v[42:43], v[38:39], 0 neg_lo:[1,1] neg_hi:[1,1]
	s_nop 0
	v_mov_b32_e32 v39, v43
	v_pk_add_f32 v[22:23], v[22:23], v[38:39]
	ds_write_b64 v190, v[22:23]
	v_pk_mul_f32 v[22:23], v[30:31], v[96:97] op_sel:[0,0] op_sel_hi:[0,1] neg_hi:[0,1]
	v_pk_fma_f32 v[22:23], v[30:31], v[96:97], v[22:23] op_sel:[1,1,0] op_sel_hi:[1,0,1]
	v_pk_mul_f32 v[30:31], v[106:107], v[98:99] op_sel:[0,0] op_sel_hi:[0,1]
	v_pk_fma_f32 v[30:31], v[106:107], v[98:99], v[30:31] op_sel:[1,1,0] op_sel_hi:[1,0,1] neg_lo:[1,0,0]
	v_pk_add_f32 v[38:39], v[30:31], 0 neg_lo:[1,1] neg_hi:[1,1]
	s_nop 0
	v_mov_b32_e32 v31, v39
	v_pk_add_f32 v[22:23], v[22:23], v[30:31]
	ds_write_b64 v191, v[22:23]
	ds_read_b128 v[96:99], v192
	ds_read_b64 v[22:23], v193
	ds_read_b64 v[30:31], v194
	s_waitcnt vmcnt(10) lgkmcnt(2)
; #define LAS __attribute__((address_space(3)))
; __device__ __forceinline__ cf cconj(cf a) { return (cf){a.x, -a.y}; }
; __device__ __forceinline__ int p_of_k(int k) { return ((k & 15) << 10) | (((k >> 4) & 15) << 6) | (((k >> 8) & 15) << 2) | (k >> 12); }
; __device__ __forceinline__ void hyena_phase(LAS unsigned char* L, const Args& a, int vcu, int G) {
;     ...
;             for (int i = 0; i < 8; ++i) {
;                 const int g = tid + 512 * i;
;                 const int kg = (g >> 8) | (((g >> 4) & 15) << 4) | ((g & 15) << 8);
;                 const int pp0 = p_of_k((NFFT - kg) & (NFFT - 1)), pp1 = p_of_k(12288 - kg);
;                 const int p0 = PH(4 * g);
;                 const f32x4 zz = *(LAS f32x4*)(z + p0);
;                 const cf zk0 = {zz[0], zz[1]}, zk1 = {zz[2], zz[3]};
;                 const cf zn0 = z[PH(pp0)], zn1 = z[PH(pp1)];
;                 const f32x4 s0 = sd[2 * i], s1 = sd[2 * i + 1];
;                 const cf S0 = {s0[0], s0[1]}, D0 = {s0[2], s0[3]}, S1 = {s1[0], s1[1]}, D1 = {s1[2], s1[3]};
;                 const cf w0 = cmul(zk0, S0) + cmul(cconj(zn0), D0), w1 = cmul(zk1, S1) + cmul(cconj(zn1), D1);
;                 *(LAS f32x4*)(z + p0) = (f32x4){w0.x, w0.y, w1.x, w1.y};
;                 if (kg != 0) z[PH(pp0)] = cmulc(zn0, S0) + cconj(cmul(zk0, D0));
;                 z[PH(pp1)] = cmulc(zn1, S1) + cconj(cmul(zk1, D1));
;             }
	v_pk_mul_f32 v[38:39], v[96:97], v[92:93] op_sel:[0,0] op_sel_hi:[0,1]
	s_waitcnt lgkmcnt(1)
	v_pk_add_f32 v[42:43], v[22:23], 0 neg_lo:[1,1] neg_hi:[1,1]
	v_pk_fma_f32 v[38:39], v[96:97], v[92:93], v[38:39] op_sel:[1,1,0] op_sel_hi:[1,0,1] neg_lo:[1,0,0]
	v_mov_b32_e32 v42, v22
	v_pk_mul_f32 v[100:101], v[42:43], v[94:95] op_sel:[0,0] op_sel_hi:[0,1]
	v_pk_fma_f32 v[42:43], v[42:43], v[94:95], v[100:101] op_sel:[1,1,0] op_sel_hi:[1,0,1] neg_lo:[1,0,0]
	v_pk_mul_f32 v[100:101], v[98:99], v[88:89] op_sel:[0,0] op_sel_hi:[0,1]
	v_pk_fma_f32 v[102:103], v[98:99], v[88:89], v[100:101] op_sel:[1,1,0] op_sel_hi:[1,0,1] neg_lo:[1,0,0]
	s_waitcnt lgkmcnt(0)
	v_pk_add_f32 v[100:101], v[30:31], 0 neg_lo:[1,1] neg_hi:[1,1]
	s_nop 0
	v_mov_b32_e32 v100, v30
	v_pk_mul_f32 v[104:105], v[100:101], v[90:91] op_sel:[0,0] op_sel_hi:[0,1]
	v_pk_fma_f32 v[104:105], v[100:101], v[90:91], v[104:105] op_sel:[1,1,0] op_sel_hi:[1,0,1] neg_lo:[1,0,0]
	v_pk_add_f32 v[100:101], v[38:39], v[42:43]
	v_pk_mul_f32 v[38:39], v[22:23], v[92:93] op_sel:[0,0] op_sel_hi:[0,1] neg_hi:[0,1]
	v_pk_add_f32 v[102:103], v[102:103], v[104:105]
	v_pk_fma_f32 v[22:23], v[22:23], v[92:93], v[38:39] op_sel:[1,1,0] op_sel_hi:[1,0,1]
	v_pk_mul_f32 v[38:39], v[96:97], v[94:95] op_sel:[0,0] op_sel_hi:[0,1]
	ds_write_b128 v192, v[100:103]
	v_pk_fma_f32 v[38:39], v[96:97], v[94:95], v[38:39] op_sel:[1,1,0] op_sel_hi:[1,0,1] neg_lo:[1,0,0]
	v_pk_add_f32 v[42:43], v[38:39], 0 neg_lo:[1,1] neg_hi:[1,1]
	s_nop 0
	v_mov_b32_e32 v39, v43
	v_pk_add_f32 v[22:23], v[22:23], v[38:39]
	ds_write_b64 v193, v[22:23]
	v_pk_mul_f32 v[22:23], v[30:31], v[88:89] op_sel:[0,0] op_sel_hi:[0,1] neg_hi:[0,1]
	v_pk_fma_f32 v[22:23], v[30:31], v[88:89], v[22:23] op_sel:[1,1,0] op_sel_hi:[1,0,1]
	v_pk_mul_f32 v[30:31], v[98:99], v[90:91] op_sel:[0,0] op_sel_hi:[0,1]
	v_pk_fma_f32 v[30:31], v[98:99], v[90:91], v[30:31] op_sel:[1,1,0] op_sel_hi:[1,0,1] neg_lo:[1,0,0]
	v_pk_add_f32 v[38:39], v[30:31], 0 neg_lo:[1,1] neg_hi:[1,1]
	s_nop 0
	v_mov_b32_e32 v31, v39
	v_pk_add_f32 v[22:23], v[22:23], v[30:31]
	ds_write_b64 v194, v[22:23]
	ds_read_b128 v[88:91], v195
	ds_read_b64 v[22:23], v196
	ds_read_b64 v[30:31], v197
	s_waitcnt vmcnt(8) lgkmcnt(2)
	v_pk_mul_f32 v[38:39], v[88:89], v[84:85] op_sel:[0,0] op_sel_hi:[0,1]
	s_waitcnt lgkmcnt(1)
	v_pk_add_f32 v[42:43], v[22:23], 0 neg_lo:[1,1] neg_hi:[1,1]
	v_pk_fma_f32 v[38:39], v[88:89], v[84:85], v[38:39] op_sel:[1,1,0] op_sel_hi:[1,0,1] neg_lo:[1,0,0]
	v_mov_b32_e32 v42, v22
	v_pk_mul_f32 v[92:93], v[42:43], v[86:87] op_sel:[0,0] op_sel_hi:[0,1]
	v_pk_fma_f32 v[42:43], v[42:43], v[86:87], v[92:93] op_sel:[1,1,0] op_sel_hi:[1,0,1] neg_lo:[1,0,0]
	v_pk_mul_f32 v[92:93], v[90:91], v[80:81] op_sel:[0,0] op_sel_hi:[0,1]
	v_pk_fma_f32 v[94:95], v[90:91], v[80:81], v[92:93] op_sel:[1,1,0] op_sel_hi:[1,0,1] neg_lo:[1,0,0]
	s_waitcnt lgkmcnt(0)
	v_pk_add_f32 v[92:93], v[30:31], 0 neg_lo:[1,1] neg_hi:[1,1]
	s_nop 0
	v_mov_b32_e32 v92, v30
	v_pk_mul_f32 v[96:97], v[92:93], v[82:83] op_sel:[0,0] op_sel_hi:[0,1]
	v_pk_fma_f32 v[96:97], v[92:93], v[82:83], v[96:97] op_sel:[1,1,0] op_sel_hi:[1,0,1] neg_lo:[1,0,0]
	v_pk_add_f32 v[92:93], v[38:39], v[42:43]
	v_pk_mul_f32 v[38:39], v[22:23], v[84:85] op_sel:[0,0] op_sel_hi:[0,1] neg_hi:[0,1]
	v_pk_add_f32 v[94:95], v[94:95], v[96:97]
	v_pk_fma_f32 v[22:23], v[22:23], v[84:85], v[38:39] op_sel:[1,1,0] op_sel_hi:[1,0,1]
	v_pk_mul_f32 v[38:39], v[88:89], v[86:87] op_sel:[0,0] op_sel_hi:[0,1]
	ds_write_b128 v195, v[92:95]
	v_pk_fma_f32 v[38:39], v[88:89], v[86:87], v[38:39] op_sel:[1,1,0] op_sel_hi:[1,0,1] neg_lo:[1,0,0]
	v_pk_add_f32 v[42:43], v[38:39], 0 neg_lo:[1,1] neg_hi:[1,1]
	s_nop 0
	v_mov_b32_e32 v39, v43
	v_pk_add_f32 v[22:23], v[22:23], v[38:39]
	ds_write_b64 v196, v[22:23]
	v_pk_mul_f32 v[22:23], v[30:31], v[80:81] op_sel:[0,0] op_sel_hi:[0,1] neg_hi:[0,1]
	v_pk_fma_f32 v[22:23], v[30:31], v[80:81], v[22:23] op_sel:[1,1,0] op_sel_hi:[1,0,1]
	v_pk_mul_f32 v[30:31], v[90:91], v[82:83] op_sel:[0,0] op_sel_hi:[0,1]
	v_pk_fma_f32 v[30:31], v[90:91], v[82:83], v[30:31] op_sel:[1,1,0] op_sel_hi:[1,0,1] neg_lo:[1,0,0]
	v_pk_add_f32 v[38:39], v[30:31], 0 neg_lo:[1,1] neg_hi:[1,1]
	s_nop 0
	v_mov_b32_e32 v31, v39
	v_pk_add_f32 v[22:23], v[22:23], v[30:31]
	ds_write_b64 v197, v[22:23]
	ds_read_b128 v[80:83], v198
	ds_read_b64 v[22:23], v199
	ds_read_b64 v[30:31], v200
	s_waitcnt vmcnt(6) lgkmcnt(2)
	v_pk_mul_f32 v[38:39], v[80:81], v[76:77] op_sel:[0,0] op_sel_hi:[0,1]
	s_waitcnt lgkmcnt(1)
	v_pk_add_f32 v[42:43], v[22:23], 0 neg_lo:[1,1] neg_hi:[1,1]
	v_pk_fma_f32 v[38:39], v[80:81], v[76:77], v[38:39] op_sel:[1,1,0] op_sel_hi:[1,0,1] neg_lo:[1,0,0]
	v_mov_b32_e32 v42, v22
	v_pk_mul_f32 v[84:85], v[42:43], v[78:79] op_sel:[0,0] op_sel_hi:[0,1]
	v_pk_fma_f32 v[42:43], v[42:43], v[78:79], v[84:85] op_sel:[1,1,0] op_sel_hi:[1,0,1] neg_lo:[1,0,0]
	v_pk_mul_f32 v[84:85], v[82:83], v[72:73] op_sel:[0,0] op_sel_hi:[0,1]
	v_pk_fma_f32 v[86:87], v[82:83], v[72:73], v[84:85] op_sel:[1,1,0] op_sel_hi:[1,0,1] neg_lo:[1,0,0]
	s_waitcnt lgkmcnt(0)
; #define LAS __attribute__((address_space(3)))
; __device__ __forceinline__ cf cconj(cf a) { return (cf){a.x, -a.y}; }
; __device__ __forceinline__ int p_of_k(int k) { return ((k & 15) << 10) | (((k >> 4) & 15) << 6) | (((k >> 8) & 15) << 2) | (k >> 12); }
; __device__ __forceinline__ void hyena_phase(LAS unsigned char* L, const Args& a, int vcu, int G) {
;     ...
;             for (int i = 0; i < 8; ++i) {
;                 const int g = tid + 512 * i;
;                 const int kg = (g >> 8) | (((g >> 4) & 15) << 4) | ((g & 15) << 8);
;                 const int pp0 = p_of_k((NFFT - kg) & (NFFT - 1)), pp1 = p_of_k(12288 - kg);
;                 const int p0 = PH(4 * g);
;                 const f32x4 zz = *(LAS f32x4*)(z + p0);
;                 const cf zk0 = {zz[0], zz[1]}, zk1 = {zz[2], zz[3]};
;                 const cf zn0 = z[PH(pp0)], zn1 = z[PH(pp1)];
;                 const f32x4 s0 = sd[2 * i], s1 = sd[2 * i + 1];
;                 const cf S0 = {s0[0], s0[1]}, D0 = {s0[2], s0[3]}, S1 = {s1[0], s1[1]}, D1 = {s1[2], s1[3]};
;                 const cf w0 = cmul(zk0, S0) + cmul(cconj(zn0), D0), w1 = cmul(zk1, S1) + cmul(cconj(zn1), D1);
;                 *(LAS f32x4*)(z + p0) = (f32x4){w0.x, w0.y, w1.x, w1.y};
;                 if (kg != 0) z[PH(pp0)] = cmulc(zn0, S0) + cconj(cmul(zk0, D0));
;                 z[PH(pp1)] = cmulc(zn1, S1) + cconj(cmul(zk1, D1));
;             }
	v_pk_add_f32 v[84:85], v[30:31], 0 neg_lo:[1,1] neg_hi:[1,1]
	s_nop 0
	v_mov_b32_e32 v84, v30
	v_pk_mul_f32 v[88:89], v[84:85], v[74:75] op_sel:[0,0] op_sel_hi:[0,1]
	v_pk_fma_f32 v[88:89], v[84:85], v[74:75], v[88:89] op_sel:[1,1,0] op_sel_hi:[1,0,1] neg_lo:[1,0,0]
	v_pk_add_f32 v[84:85], v[38:39], v[42:43]
	v_pk_mul_f32 v[38:39], v[22:23], v[76:77] op_sel:[0,0] op_sel_hi:[0,1] neg_hi:[0,1]
	v_pk_add_f32 v[86:87], v[86:87], v[88:89]
	v_pk_fma_f32 v[22:23], v[22:23], v[76:77], v[38:39] op_sel:[1,1,0] op_sel_hi:[1,0,1]
	v_pk_mul_f32 v[38:39], v[80:81], v[78:79] op_sel:[0,0] op_sel_hi:[0,1]
	ds_write_b128 v198, v[84:87]
	v_pk_fma_f32 v[38:39], v[80:81], v[78:79], v[38:39] op_sel:[1,1,0] op_sel_hi:[1,0,1] neg_lo:[1,0,0]
	v_pk_add_f32 v[42:43], v[38:39], 0 neg_lo:[1,1] neg_hi:[1,1]
	s_nop 0
	v_mov_b32_e32 v39, v43
	v_pk_add_f32 v[22:23], v[22:23], v[38:39]
	ds_write_b64 v199, v[22:23]
	v_pk_mul_f32 v[22:23], v[30:31], v[72:73] op_sel:[0,0] op_sel_hi:[0,1] neg_hi:[0,1]
	v_pk_fma_f32 v[22:23], v[30:31], v[72:73], v[22:23] op_sel:[1,1,0] op_sel_hi:[1,0,1]
	v_pk_mul_f32 v[30:31], v[82:83], v[74:75] op_sel:[0,0] op_sel_hi:[0,1]
	v_pk_fma_f32 v[30:31], v[82:83], v[74:75], v[30:31] op_sel:[1,1,0] op_sel_hi:[1,0,1] neg_lo:[1,0,0]
	v_pk_add_f32 v[38:39], v[30:31], 0 neg_lo:[1,1] neg_hi:[1,1]
	s_nop 0
	v_mov_b32_e32 v31, v39
	v_pk_add_f32 v[22:23], v[22:23], v[30:31]
	ds_write_b64 v200, v[22:23]
	ds_read_b128 v[72:75], v201
	ds_read_b64 v[22:23], v202
	ds_read_b64 v[30:31], v203
	s_waitcnt vmcnt(4) lgkmcnt(2)
	v_pk_mul_f32 v[38:39], v[72:73], v[68:69] op_sel:[0,0] op_sel_hi:[0,1]
	s_waitcnt lgkmcnt(1)
	v_pk_add_f32 v[42:43], v[22:23], 0 neg_lo:[1,1] neg_hi:[1,1]
	v_pk_fma_f32 v[38:39], v[72:73], v[68:69], v[38:39] op_sel:[1,1,0] op_sel_hi:[1,0,1] neg_lo:[1,0,0]
	v_mov_b32_e32 v42, v22
	v_pk_mul_f32 v[76:77], v[42:43], v[70:71] op_sel:[0,0] op_sel_hi:[0,1]
	v_pk_fma_f32 v[42:43], v[42:43], v[70:71], v[76:77] op_sel:[1,1,0] op_sel_hi:[1,0,1] neg_lo:[1,0,0]
	v_pk_mul_f32 v[76:77], v[74:75], v[64:65] op_sel:[0,0] op_sel_hi:[0,1]
	v_pk_fma_f32 v[78:79], v[74:75], v[64:65], v[76:77] op_sel:[1,1,0] op_sel_hi:[1,0,1] neg_lo:[1,0,0]
	s_waitcnt lgkmcnt(0)
	v_pk_add_f32 v[76:77], v[30:31], 0 neg_lo:[1,1] neg_hi:[1,1]
	s_nop 0
	v_mov_b32_e32 v76, v30
	v_pk_mul_f32 v[80:81], v[76:77], v[66:67] op_sel:[0,0] op_sel_hi:[0,1]
	v_pk_fma_f32 v[80:81], v[76:77], v[66:67], v[80:81] op_sel:[1,1,0] op_sel_hi:[1,0,1] neg_lo:[1,0,0]
	v_pk_add_f32 v[76:77], v[38:39], v[42:43]
	v_pk_mul_f32 v[38:39], v[22:23], v[68:69] op_sel:[0,0] op_sel_hi:[0,1] neg_hi:[0,1]
	v_pk_add_f32 v[78:79], v[78:79], v[80:81]
	v_pk_fma_f32 v[22:23], v[22:23], v[68:69], v[38:39] op_sel:[1,1,0] op_sel_hi:[1,0,1]
	v_pk_mul_f32 v[38:39], v[72:73], v[70:71] op_sel:[0,0] op_sel_hi:[0,1]
	ds_write_b128 v201, v[76:79]
	v_pk_fma_f32 v[38:39], v[72:73], v[70:71], v[38:39] op_sel:[1,1,0] op_sel_hi:[1,0,1] neg_lo:[1,0,0]
	v_pk_add_f32 v[42:43], v[38:39], 0 neg_lo:[1,1] neg_hi:[1,1]
	s_nop 0
	v_mov_b32_e32 v39, v43
	v_pk_add_f32 v[22:23], v[22:23], v[38:39]
	ds_write_b64 v202, v[22:23]
	v_pk_mul_f32 v[22:23], v[30:31], v[64:65] op_sel:[0,0] op_sel_hi:[0,1] neg_hi:[0,1]
	v_pk_fma_f32 v[22:23], v[30:31], v[64:65], v[22:23] op_sel:[1,1,0] op_sel_hi:[1,0,1]
	v_pk_mul_f32 v[30:31], v[74:75], v[66:67] op_sel:[0,0] op_sel_hi:[0,1]
	v_pk_fma_f32 v[30:31], v[74:75], v[66:67], v[30:31] op_sel:[1,1,0] op_sel_hi:[1,0,1] neg_lo:[1,0,0]
	v_pk_add_f32 v[38:39], v[30:31], 0 neg_lo:[1,1] neg_hi:[1,1]
	s_nop 0
	v_mov_b32_e32 v31, v39
	v_pk_add_f32 v[22:23], v[22:23], v[30:31]
	ds_write_b64 v203, v[22:23]
	ds_read_b128 v[64:67], v204
	ds_read_b64 v[22:23], v205
	ds_read_b64 v[30:31], v206
	s_waitcnt vmcnt(2) lgkmcnt(2)
	v_pk_mul_f32 v[38:39], v[64:65], v[60:61] op_sel:[0,0] op_sel_hi:[0,1]
	s_waitcnt lgkmcnt(1)
	v_pk_add_f32 v[42:43], v[22:23], 0 neg_lo:[1,1] neg_hi:[1,1]
	v_pk_fma_f32 v[38:39], v[64:65], v[60:61], v[38:39] op_sel:[1,1,0] op_sel_hi:[1,0,1] neg_lo:[1,0,0]
	v_mov_b32_e32 v42, v22
	v_pk_mul_f32 v[68:69], v[42:43], v[62:63] op_sel:[0,0] op_sel_hi:[0,1]
	v_pk_fma_f32 v[42:43], v[42:43], v[62:63], v[68:69] op_sel:[1,1,0] op_sel_hi:[1,0,1] neg_lo:[1,0,0]
	v_pk_mul_f32 v[68:69], v[66:67], v[56:57] op_sel:[0,0] op_sel_hi:[0,1]
	v_pk_fma_f32 v[70:71], v[66:67], v[56:57], v[68:69] op_sel:[1,1,0] op_sel_hi:[1,0,1] neg_lo:[1,0,0]
	s_waitcnt lgkmcnt(0)
; #define LAS __attribute__((address_space(3)))
; __device__ __forceinline__ cf cconj(cf a) { return (cf){a.x, -a.y}; }
; __device__ __forceinline__ int p_of_k(int k) { return ((k & 15) << 10) | (((k >> 4) & 15) << 6) | (((k >> 8) & 15) << 2) | (k >> 12); }
; __device__ __forceinline__ void hyena_phase(LAS unsigned char* L, const Args& a, int vcu, int G) {
;     ...
;             for (int i = 0; i < 8; ++i) {
;                 const int g = tid + 512 * i;
;                 const int kg = (g >> 8) | (((g >> 4) & 15) << 4) | ((g & 15) << 8);
;                 const int pp0 = p_of_k((NFFT - kg) & (NFFT - 1)), pp1 = p_of_k(12288 - kg);
;                 const int p0 = PH(4 * g);
;                 const f32x4 zz = *(LAS f32x4*)(z + p0);
;                 const cf zk0 = {zz[0], zz[1]}, zk1 = {zz[2], zz[3]};
;                 const cf zn0 = z[PH(pp0)], zn1 = z[PH(pp1)];
;                 const f32x4 s0 = sd[2 * i], s1 = sd[2 * i + 1];
;                 const cf S0 = {s0[0], s0[1]}, D0 = {s0[2], s0[3]}, S1 = {s1[0], s1[1]}, D1 = {s1[2], s1[3]};
;                 const cf w0 = cmul(zk0, S0) + cmul(cconj(zn0), D0), w1 = cmul(zk1, S1) + cmul(cconj(zn1), D1);
;                 *(LAS f32x4*)(z + p0) = (f32x4){w0.x, w0.y, w1.x, w1.y};
;                 if (kg != 0) z[PH(pp0)] = cmulc(zn0, S0) + cconj(cmul(zk0, D0));
;                 z[PH(pp1)] = cmulc(zn1, S1) + cconj(cmul(zk1, D1));
;             }
;             if (tid == 0) { const f32x4 s8 = SD8[pair]; const cf S = {s8[0], s8[1]}, Dd = {s8[2], s8[3]}; const cf zk = z[PH(2)]; z[PH(2)] = cmul(zk, S) + cmul(cconj(zk), Dd); }
	v_pk_add_f32 v[68:69], v[30:31], 0 neg_lo:[1,1] neg_hi:[1,1]
	s_nop 0
	v_mov_b32_e32 v68, v30
	v_pk_mul_f32 v[72:73], v[68:69], v[58:59] op_sel:[0,0] op_sel_hi:[0,1]
	v_pk_fma_f32 v[72:73], v[68:69], v[58:59], v[72:73] op_sel:[1,1,0] op_sel_hi:[1,0,1] neg_lo:[1,0,0]
	v_pk_add_f32 v[68:69], v[38:39], v[42:43]
	v_pk_mul_f32 v[38:39], v[22:23], v[60:61] op_sel:[0,0] op_sel_hi:[0,1] neg_hi:[0,1]
	v_pk_add_f32 v[70:71], v[70:71], v[72:73]
	v_pk_fma_f32 v[22:23], v[22:23], v[60:61], v[38:39] op_sel:[1,1,0] op_sel_hi:[1,0,1]
	v_pk_mul_f32 v[38:39], v[64:65], v[62:63] op_sel:[0,0] op_sel_hi:[0,1]
	ds_write_b128 v204, v[68:71]
	v_pk_fma_f32 v[38:39], v[64:65], v[62:63], v[38:39] op_sel:[1,1,0] op_sel_hi:[1,0,1] neg_lo:[1,0,0]
	v_pk_add_f32 v[42:43], v[38:39], 0 neg_lo:[1,1] neg_hi:[1,1]
	s_nop 0
	v_mov_b32_e32 v39, v43
	v_pk_add_f32 v[22:23], v[22:23], v[38:39]
	ds_write_b64 v205, v[22:23]
	v_pk_mul_f32 v[22:23], v[30:31], v[56:57] op_sel:[0,0] op_sel_hi:[0,1] neg_hi:[0,1]
	v_pk_fma_f32 v[22:23], v[30:31], v[56:57], v[22:23] op_sel:[1,1,0] op_sel_hi:[1,0,1]
	v_pk_mul_f32 v[30:31], v[66:67], v[58:59] op_sel:[0,0] op_sel_hi:[0,1]
	v_pk_fma_f32 v[30:31], v[66:67], v[58:59], v[30:31] op_sel:[1,1,0] op_sel_hi:[1,0,1] neg_lo:[1,0,0]
	v_pk_add_f32 v[38:39], v[30:31], 0 neg_lo:[1,1] neg_hi:[1,1]
	s_nop 0
	v_mov_b32_e32 v31, v39
	v_pk_add_f32 v[22:23], v[22:23], v[30:31]
	ds_write_b64 v206, v[22:23]
	ds_read_b128 v[56:59], v207
	ds_read_b64 v[22:23], v208
	ds_read_b64 v[30:31], v209
	s_waitcnt vmcnt(0) lgkmcnt(2)
	v_pk_mul_f32 v[38:39], v[56:57], v[52:53] op_sel:[0,0] op_sel_hi:[0,1]
	s_waitcnt lgkmcnt(1)
	v_pk_add_f32 v[42:43], v[22:23], 0 neg_lo:[1,1] neg_hi:[1,1]
	v_pk_fma_f32 v[38:39], v[56:57], v[52:53], v[38:39] op_sel:[1,1,0] op_sel_hi:[1,0,1] neg_lo:[1,0,0]
	v_mov_b32_e32 v42, v22
	v_pk_mul_f32 v[60:61], v[42:43], v[54:55] op_sel:[0,0] op_sel_hi:[0,1]
	v_pk_fma_f32 v[42:43], v[42:43], v[54:55], v[60:61] op_sel:[1,1,0] op_sel_hi:[1,0,1] neg_lo:[1,0,0]
	v_pk_mul_f32 v[60:61], v[58:59], v[48:49] op_sel:[0,0] op_sel_hi:[0,1]
	v_pk_fma_f32 v[62:63], v[58:59], v[48:49], v[60:61] op_sel:[1,1,0] op_sel_hi:[1,0,1] neg_lo:[1,0,0]
	s_waitcnt lgkmcnt(0)
	v_pk_add_f32 v[60:61], v[30:31], 0 neg_lo:[1,1] neg_hi:[1,1]
	s_nop 0
	v_mov_b32_e32 v60, v30
	v_pk_mul_f32 v[64:65], v[60:61], v[50:51] op_sel:[0,0] op_sel_hi:[0,1]
	v_pk_fma_f32 v[64:65], v[60:61], v[50:51], v[64:65] op_sel:[1,1,0] op_sel_hi:[1,0,1] neg_lo:[1,0,0]
	v_pk_add_f32 v[60:61], v[38:39], v[42:43]
	v_pk_mul_f32 v[38:39], v[22:23], v[52:53] op_sel:[0,0] op_sel_hi:[0,1] neg_hi:[0,1]
	v_pk_add_f32 v[62:63], v[62:63], v[64:65]
	v_pk_fma_f32 v[22:23], v[22:23], v[52:53], v[38:39] op_sel:[1,1,0] op_sel_hi:[1,0,1]
	v_pk_mul_f32 v[38:39], v[56:57], v[54:55] op_sel:[0,0] op_sel_hi:[0,1]
	ds_write_b128 v207, v[60:63]
	v_pk_fma_f32 v[38:39], v[56:57], v[54:55], v[38:39] op_sel:[1,1,0] op_sel_hi:[1,0,1] neg_lo:[1,0,0]
	v_pk_add_f32 v[42:43], v[38:39], 0 neg_lo:[1,1] neg_hi:[1,1]
	s_nop 0
	v_mov_b32_e32 v39, v43
	v_pk_add_f32 v[22:23], v[22:23], v[38:39]
	ds_write_b64 v208, v[22:23]
	v_pk_mul_f32 v[22:23], v[30:31], v[48:49] op_sel:[0,0] op_sel_hi:[0,1] neg_hi:[0,1]
	v_pk_fma_f32 v[22:23], v[30:31], v[48:49], v[22:23] op_sel:[1,1,0] op_sel_hi:[1,0,1]
	v_pk_mul_f32 v[30:31], v[58:59], v[50:51] op_sel:[0,0] op_sel_hi:[0,1]
	v_pk_fma_f32 v[30:31], v[58:59], v[50:51], v[30:31] op_sel:[1,1,0] op_sel_hi:[1,0,1] neg_lo:[1,0,0]
	v_pk_add_f32 v[38:39], v[30:31], 0 neg_lo:[1,1] neg_hi:[1,1]
	s_nop 0
	v_mov_b32_e32 v31, v39
	v_pk_add_f32 v[22:23], v[22:23], v[30:31]
	ds_write_b64 v209, v[22:23]
	s_and_saveexec_b64 s[46:47], s[0:1]
	s_cbranch_execz .LBB0_1035
	ds_read_b64 v[22:23], v117 offset:16
	s_waitcnt vmcnt(0) lgkmcnt(0)
	v_pk_mul_f32 v[30:31], v[22:23], v[236:237] op_sel:[0,0] op_sel_hi:[0,1]
	v_pk_fma_f32 v[30:31], v[22:23], v[236:237], v[30:31] op_sel:[1,1,0] op_sel_hi:[1,0,1] neg_lo:[1,0,0]
	v_xor_b32_e32 v23, 0x80000000, v23
	v_pk_mul_f32 v[38:39], v[22:23], v[238:239] op_sel:[0,0] op_sel_hi:[0,1]
	v_pk_fma_f32 v[22:23], v[22:23], v[238:239], v[38:39] op_sel:[1,1,0] op_sel_hi:[1,0,1] neg_lo:[1,0,0]
	v_pk_add_f32 v[22:23], v[30:31], v[22:23]
	ds_write_b64 v117, v[22:23] offset:16

; __device__ __forceinline__ cf add_mib(cf a, cf b) { cf r; asm("v_pk_add_f32 %0, %1, %2 op_sel:[0,1] op_sel_hi:[1,0] neg_hi:[0,1]" : "=v"(r) : "v"(a), "v"(b)); return r; }
; __device__ __forceinline__ cf add_pib(cf a, cf b) { cf r; asm("v_pk_add_f32 %0, %1, %2 op_sel:[0,1] op_sel_hi:[1,0] neg_lo:[0,1]" : "=v"(r) : "v"(a), "v"(b)); return r; }
; template <bool INV, bool HALFIN = false> __device__ __forceinline__ void dft16(cf (&x)[16]) {
; #pragma unroll
;     for (int m2 = 0; m2 < 4; ++m2) {
;         if (HALFIN) { const cf a0 = x[m2], a1 = x[4 + m2]; x[m2] = a0 + a1; x[8 + m2] = a0 - a1; x[4 + m2] = add_mib(a0, a1); x[12 + m2] = add_pib(a0, a1); }
;         else dft4<INV>(x[m2], x[4 + m2], x[8 + m2], x[12 + m2]);
;     }
;     constexpr float C1 = 0.9238795325112867f, S1 = 0.3826834323650898f, C2 = 0.7071067811865476f;
;     x[4 * 1 + 1] = tw16<INV>(x[5], C1, S1);  x[4 * 1 + 2] = tw16<INV>(x[6], C2, C2);   x[4 * 1 + 3] = tw16<INV>(x[7], S1, C1);
;     x[4 * 2 + 1] = tw16<INV>(x[9], C2, C2);  x[4 * 2 + 2] = tw16<INV>(x[10], 0.f, 1.f); x[4 * 2 + 3] = tw16<INV>(x[11], -C2, C2);
;     x[4 * 3 + 1] = tw16<INV>(x[13], S1, C1); x[4 * 3 + 2] = tw16<INV>(x[14], -C2, C2); x[4 * 3 + 3] = tw16<INV>(x[15], -C1, -S1);
; #pragma unroll
;     for (int q1 = 0; q1 < 4; ++q1) dft4<INV>(x[4 * q1], x[4 * q1 + 1], x[4 * q1 + 2], x[4 * q1 + 3]);
; }
; template <bool INV, int LST, bool HALF = false> __device__ __forceinline__ void fft_pass16(LAS cf* z, const LAS cf* Thi, const LAS cf* Tlo, int tid) {
;     ...
; #pragma unroll
;             for (int q = 0; q < 16; ++q) { cf y = z[pass_pos<LST>(base, phb, q)]; if (q) y = cmulc(y, w[q]); x[q] = y; }
;             dft16<true>(x);
; #pragma unroll
;             for (int m = 0; m < (HALF ? 8 : 16); ++m) z[pass_pos<LST>(base, phb, m)] = x[4 * (m & 3) + (m >> 2)];
.LBB0_1038:
	v_add_u32_e32 v29, s21, v169
	v_and_or_b32 v29, v29, s71, v172
	v_lshl_add_u32 v37, v29, 3, v174
	v_xor_b32_e32 v41, 0x20, v37
	v_xor_b32_e32 v108, 0x40, v37
	ds_read_b64 v[70:71], v41
	v_xor_b32_e32 v109, 0x60, v37
	ds_read_b64 v[72:73], v108
	ds_read_b64 v[74:75], v37
	ds_read_b64 v[76:77], v109
	s_waitcnt lgkmcnt(3)
	v_pk_mul_f32 v[78:79], v[70:71], v[22:23] op_sel:[0,0] op_sel_hi:[0,1] neg_hi:[0,1]
	v_pk_fma_f32 v[70:71], v[70:71], v[22:23], v[78:79] op_sel:[1,1,0] op_sel_hi:[1,0,1]
	s_waitcnt lgkmcnt(2)
	v_pk_mul_f32 v[78:79], v[72:73], v[30:31] op_sel:[0,0] op_sel_hi:[0,1] neg_hi:[0,1]
	v_xor_b32_e32 v111, 0xa0, v37
	v_pk_fma_f32 v[72:73], v[72:73], v[30:31], v[78:79] op_sel:[1,1,0] op_sel_hi:[1,0,1]
	s_waitcnt lgkmcnt(0)
	v_pk_mul_f32 v[78:79], v[76:77], v[38:39] op_sel:[0,0] op_sel_hi:[0,1] neg_hi:[0,1]
	v_pk_fma_f32 v[76:77], v[76:77], v[38:39], v[78:79] op_sel:[1,1,0] op_sel_hi:[1,0,1]
	v_xor_b32_e32 v110, 0x80, v37
	v_xor_b32_e32 v112, 0xc0, v37
	ds_read_b64 v[78:79], v110
	v_xor_b32_e32 v113, 0xe0, v37
	ds_read_b64 v[80:81], v111
	ds_read_b64 v[82:83], v112
	ds_read_b64 v[84:85], v113
	s_waitcnt lgkmcnt(3)
	v_pk_mul_f32 v[86:87], v[78:79], v[42:43] op_sel:[0,0] op_sel_hi:[0,1] neg_hi:[0,1]
	v_pk_fma_f32 v[78:79], v[78:79], v[42:43], v[86:87] op_sel:[1,1,0] op_sel_hi:[1,0,1]
	s_waitcnt lgkmcnt(2)
	v_pk_mul_f32 v[86:87], v[80:81], v[48:49] op_sel:[0,0] op_sel_hi:[0,1] neg_hi:[0,1]
	v_xor_b32_e32 v115, 0x120, v37
	v_pk_fma_f32 v[80:81], v[80:81], v[48:49], v[86:87] op_sel:[1,1,0] op_sel_hi:[1,0,1]
	s_waitcnt lgkmcnt(1)
	v_pk_mul_f32 v[86:87], v[82:83], v[50:51] op_sel:[0,0] op_sel_hi:[0,1] neg_hi:[0,1]
	v_pk_fma_f32 v[82:83], v[82:83], v[50:51], v[86:87] op_sel:[1,1,0] op_sel_hi:[1,0,1]
	s_waitcnt lgkmcnt(0)
	v_pk_mul_f32 v[86:87], v[84:85], v[52:53] op_sel:[0,0] op_sel_hi:[0,1] neg_hi:[0,1]
	v_xor_b32_e32 v125, 0x140, v37
	v_pk_fma_f32 v[84:85], v[84:85], v[52:53], v[86:87] op_sel:[1,1,0] op_sel_hi:[1,0,1]
	v_xor_b32_e32 v114, 0x100, v37
	ds_read_b64 v[86:87], v114
	v_xor_b32_e32 v182, 0x160, v37
	ds_read_b64 v[88:89], v115
	ds_read_b64 v[90:91], v125
	ds_read_b64 v[92:93], v182
	s_waitcnt lgkmcnt(3)
	v_pk_mul_f32 v[94:95], v[86:87], v[54:55] op_sel:[0,0] op_sel_hi:[0,1] neg_hi:[0,1]
	v_pk_fma_f32 v[86:87], v[86:87], v[54:55], v[94:95] op_sel:[1,1,0] op_sel_hi:[1,0,1]
	s_waitcnt lgkmcnt(2)
	v_pk_mul_f32 v[94:95], v[88:89], v[56:57] op_sel:[0,0] op_sel_hi:[0,1] neg_hi:[0,1]
	v_xor_b32_e32 v216, 0x1a0, v37
	v_pk_fma_f32 v[88:89], v[88:89], v[56:57], v[94:95] op_sel:[1,1,0] op_sel_hi:[1,0,1]
	s_waitcnt lgkmcnt(1)
	v_pk_mul_f32 v[94:95], v[90:91], v[58:59] op_sel:[0,0] op_sel_hi:[0,1] neg_hi:[0,1]
	v_pk_fma_f32 v[90:91], v[90:91], v[58:59], v[94:95] op_sel:[1,1,0] op_sel_hi:[1,0,1]
	s_waitcnt lgkmcnt(0)
	v_pk_mul_f32 v[94:95], v[92:93], v[60:61] op_sel:[0,0] op_sel_hi:[0,1] neg_hi:[0,1]
	v_xor_b32_e32 v217, 0x1c0, v37
	v_pk_fma_f32 v[92:93], v[92:93], v[60:61], v[94:95] op_sel:[1,1,0] op_sel_hi:[1,0,1]
	v_xor_b32_e32 v183, 0x180, v37
	ds_read_b64 v[94:95], v183
	v_xor_b32_e32 v29, 0x1e0, v37
	ds_read_b64 v[96:97], v216
	ds_read_b64 v[98:99], v217
	ds_read_b64 v[100:101], v29
	s_waitcnt lgkmcnt(3)
	v_pk_mul_f32 v[102:103], v[94:95], v[62:63] op_sel:[0,0] op_sel_hi:[0,1] neg_hi:[0,1]
	s_mov_b32 s46, s25
	v_pk_fma_f32 v[94:95], v[94:95], v[62:63], v[102:103] op_sel:[1,1,0] op_sel_hi:[1,0,1]
	s_waitcnt lgkmcnt(2)
	v_pk_mul_f32 v[102:103], v[96:97], v[64:65] op_sel:[0,0] op_sel_hi:[0,1] neg_hi:[0,1]
	s_mov_b32 s47, s24
	v_pk_fma_f32 v[96:97], v[96:97], v[64:65], v[102:103] op_sel:[1,1,0] op_sel_hi:[1,0,1]
	s_waitcnt lgkmcnt(1)
	v_pk_mul_f32 v[102:103], v[98:99], v[66:67] op_sel:[0,0] op_sel_hi:[0,1] neg_hi:[0,1]
	s_andn2_b64 vcc, exec, s[44:45]
	v_pk_fma_f32 v[98:99], v[98:99], v[66:67], v[102:103] op_sel:[1,1,0] op_sel_hi:[1,0,1]
	s_waitcnt lgkmcnt(0)
	v_pk_mul_f32 v[102:103], v[100:101], v[68:69] op_sel:[0,0] op_sel_hi:[0,1] neg_hi:[0,1]
	s_mov_b64 s[44:45], 0
	v_pk_fma_f32 v[100:101], v[100:101], v[68:69], v[102:103] op_sel:[1,1,0] op_sel_hi:[1,0,1]
	v_pk_add_f32 v[102:103], v[74:75], v[86:87]
	v_pk_add_f32 v[74:75], v[74:75], v[86:87] neg_lo:[0,1] neg_hi:[0,1]
	v_pk_add_f32 v[86:87], v[78:79], v[94:95]
	v_pk_add_f32 v[78:79], v[78:79], v[94:95] neg_lo:[0,1] neg_hi:[0,1]
	v_pk_add_f32 v[94:95], v[102:103], v[86:87]
	v_pk_add_f32 v[86:87], v[102:103], v[86:87] neg_lo:[0,1] neg_hi:[0,1]
	v_pk_add_f32 v[102:103], v[74:75], v[78:79] op_sel:[0,1] op_sel_hi:[1,0] neg_lo:[0,1]
	v_pk_add_f32 v[74:75], v[74:75], v[78:79] op_sel:[0,1] op_sel_hi:[1,0] neg_hi:[0,1]
	v_pk_add_f32 v[78:79], v[70:71], v[88:89]
	v_pk_add_f32 v[70:71], v[70:71], v[88:89] neg_lo:[0,1] neg_hi:[0,1]
	v_pk_add_f32 v[88:89], v[80:81], v[96:97]
	v_pk_add_f32 v[80:81], v[80:81], v[96:97] neg_lo:[0,1] neg_hi:[0,1]
	v_pk_add_f32 v[96:97], v[78:79], v[88:89]
	v_pk_add_f32 v[78:79], v[78:79], v[88:89] neg_lo:[0,1] neg_hi:[0,1]
	v_pk_add_f32 v[88:89], v[70:71], v[80:81] op_sel:[0,1] op_sel_hi:[1,0] neg_lo:[0,1]
	v_pk_add_f32 v[70:71], v[70:71], v[80:81] op_sel:[0,1] op_sel_hi:[1,0] neg_hi:[0,1]
	v_pk_add_f32 v[80:81], v[72:73], v[90:91]
	v_pk_add_f32 v[72:73], v[72:73], v[90:91] neg_lo:[0,1] neg_hi:[0,1]
	v_pk_add_f32 v[90:91], v[82:83], v[98:99]
	v_pk_add_f32 v[82:83], v[82:83], v[98:99] neg_lo:[0,1] neg_hi:[0,1]
	v_pk_add_f32 v[98:99], v[80:81], v[90:91]
	v_pk_add_f32 v[80:81], v[80:81], v[90:91] neg_lo:[0,1] neg_hi:[0,1]
	v_pk_add_f32 v[90:91], v[72:73], v[82:83] op_sel:[0,1] op_sel_hi:[1,0] neg_lo:[0,1]
	v_pk_add_f32 v[72:73], v[72:73], v[82:83] op_sel:[0,1] op_sel_hi:[1,0] neg_hi:[0,1]
	v_pk_add_f32 v[82:83], v[76:77], v[92:93]
; __device__ __forceinline__ cf add_mib(cf a, cf b) { cf r; asm("v_pk_add_f32 %0, %1, %2 op_sel:[0,1] op_sel_hi:[1,0] neg_hi:[0,1]" : "=v"(r) : "v"(a), "v"(b)); return r; }
; __device__ __forceinline__ cf add_pib(cf a, cf b) { cf r; asm("v_pk_add_f32 %0, %1, %2 op_sel:[0,1] op_sel_hi:[1,0] neg_lo:[0,1]" : "=v"(r) : "v"(a), "v"(b)); return r; }
; template <bool INV, bool HALFIN = false> __device__ __forceinline__ void dft16(cf (&x)[16]) {
; #pragma unroll
;     for (int m2 = 0; m2 < 4; ++m2) {
;         if (HALFIN) { const cf a0 = x[m2], a1 = x[4 + m2]; x[m2] = a0 + a1; x[8 + m2] = a0 - a1; x[4 + m2] = add_mib(a0, a1); x[12 + m2] = add_pib(a0, a1); }
;         else dft4<INV>(x[m2], x[4 + m2], x[8 + m2], x[12 + m2]);
;     }
;     constexpr float C1 = 0.9238795325112867f, S1 = 0.3826834323650898f, C2 = 0.7071067811865476f;
;     x[4 * 1 + 1] = tw16<INV>(x[5], C1, S1);  x[4 * 1 + 2] = tw16<INV>(x[6], C2, C2);   x[4 * 1 + 3] = tw16<INV>(x[7], S1, C1);
;     x[4 * 2 + 1] = tw16<INV>(x[9], C2, C2);  x[4 * 2 + 2] = tw16<INV>(x[10], 0.f, 1.f); x[4 * 2 + 3] = tw16<INV>(x[11], -C2, C2);
;     x[4 * 3 + 1] = tw16<INV>(x[13], S1, C1); x[4 * 3 + 2] = tw16<INV>(x[14], -C2, C2); x[4 * 3 + 3] = tw16<INV>(x[15], -C1, -S1);
; #pragma unroll
;     for (int q1 = 0; q1 < 4; ++q1) dft4<INV>(x[4 * q1], x[4 * q1 + 1], x[4 * q1 + 2], x[4 * q1 + 3]);
; }
	v_pk_add_f32 v[76:77], v[76:77], v[92:93] neg_lo:[0,1] neg_hi:[0,1]
	v_pk_add_f32 v[92:93], v[84:85], v[100:101]
	v_pk_add_f32 v[84:85], v[84:85], v[100:101] neg_lo:[0,1] neg_hi:[0,1]
	v_pk_add_f32 v[100:101], v[82:83], v[92:93]
	v_pk_add_f32 v[82:83], v[82:83], v[92:93] neg_lo:[0,1] neg_hi:[0,1]
	v_pk_add_f32 v[92:93], v[76:77], v[84:85] op_sel:[0,1] op_sel_hi:[1,0] neg_lo:[0,1]
	v_pk_add_f32 v[76:77], v[76:77], v[84:85] op_sel:[0,1] op_sel_hi:[1,0] neg_hi:[0,1]
	v_pk_mul_f32 v[84:85], v[88:89], s[22:23] op_sel_hi:[1,0]
	s_nop 0
	v_pk_fma_f32 v[104:105], v[88:89], s[20:21], v[84:85] op_sel:[0,0,1] op_sel_hi:[1,0,0] neg_lo:[0,0,1]
	s_nop 0
	v_pk_mul_f32 v[84:85], v[90:91], s[24:25] op_sel_hi:[1,0]
	s_nop 0
	v_pk_fma_f32 v[88:89], v[90:91], s[24:25], v[84:85] op_sel:[0,0,1] op_sel_hi:[1,0,0] neg_lo:[0,0,1]
	v_pk_mul_f32 v[90:91], v[92:93], s[20:21] op_sel_hi:[1,0]
	s_nop 0
	v_pk_fma_f32 v[106:107], v[92:93], s[22:23], v[90:91] op_sel:[0,0,1] op_sel_hi:[1,0,0] neg_lo:[0,0,1]
	v_pk_add_f32 v[84:85], v[102:103], v[88:89]
	v_pk_mul_f32 v[90:91], v[78:79], s[24:25] op_sel_hi:[1,0]
	v_pk_add_f32 v[88:89], v[102:103], v[88:89] neg_lo:[0,1] neg_hi:[0,1]
	v_pk_fma_f32 v[92:93], v[78:79], s[24:25], v[90:91] op_sel:[0,0,1] op_sel_hi:[1,0,0] neg_lo:[0,0,1]
	s_nop 0
	v_pk_fma_f32 v[78:79], v[80:81], 0, v[80:81] op_sel:[0,0,1] op_sel_hi:[1,0,0] neg_lo:[0,0,1] neg_hi:[0,0,1]
	v_pk_fma_f32 v[80:81], v[80:81], 0, v[80:81] op_sel:[0,0,1] op_sel_hi:[1,0,0]
	s_nop 0
	v_mul_f32_e32 v80, 0x3f3504f3, v83
	v_mov_b32_e32 v79, v81
	v_pk_fma_f32 v[80:81], v[82:83], s[46:47], v[80:81] op_sel_hi:[0,1,0] neg_lo:[0,0,1] neg_hi:[0,0,1]
	v_pk_mul_f32 v[82:83], v[70:71], s[20:21] op_sel_hi:[1,0]
	s_movk_i32 s21, 0x2000
	v_pk_fma_f32 v[90:91], v[70:71], s[22:23], v[82:83] op_sel:[0,0,1] op_sel_hi:[1,0,0] neg_lo:[0,0,1] neg_hi:[0,0,1]
	v_pk_fma_f32 v[70:71], v[70:71], s[22:23], v[82:83] op_sel:[0,0,1] op_sel_hi:[1,0,0]
	s_mov_b32 s23, s37
	v_mul_f32_e32 v70, 0x3f3504f3, v73
	v_mov_b32_e32 v91, v71
	v_pk_fma_f32 v[70:71], v[72:73], s[46:47], v[70:71] op_sel_hi:[0,1,0] neg_lo:[0,0,1] neg_hi:[0,0,1]
	s_mov_b32 s46, s37
	s_mov_b32 s47, s36
	v_pk_mul_f32 v[72:73], v[76:77], s[46:47] op_sel_hi:[0,1]
	v_pk_fma_f32 v[72:73], v[76:77], s[22:23], v[72:73] op_sel:[1,0,0]
	v_pk_add_f32 v[76:77], v[94:95], v[98:99]
	v_pk_add_f32 v[82:83], v[94:95], v[98:99] neg_lo:[0,1] neg_hi:[0,1]
	v_pk_add_f32 v[94:95], v[96:97], v[100:101]
	v_pk_add_f32 v[96:97], v[96:97], v[100:101] neg_lo:[0,1] neg_hi:[0,1]
	v_pk_add_f32 v[98:99], v[76:77], v[94:95]
	v_pk_add_f32 v[76:77], v[76:77], v[94:95] neg_lo:[0,1] neg_hi:[0,1]
	v_pk_add_f32 v[94:95], v[82:83], v[96:97] op_sel:[0,1] op_sel_hi:[1,0] neg_lo:[0,1]
	v_pk_add_f32 v[82:83], v[82:83], v[96:97] op_sel:[0,1] op_sel_hi:[1,0] neg_hi:[0,1]
	v_pk_add_f32 v[96:97], v[104:105], v[106:107]
	v_pk_add_f32 v[100:101], v[104:105], v[106:107] neg_lo:[0,1] neg_hi:[0,1]
	v_pk_add_f32 v[102:103], v[84:85], v[96:97]
	v_pk_add_f32 v[84:85], v[84:85], v[96:97] neg_lo:[0,1] neg_hi:[0,1]
	v_pk_add_f32 v[96:97], v[88:89], v[100:101] op_sel:[0,1] op_sel_hi:[1,0] neg_lo:[0,1]
	v_pk_add_f32 v[88:89], v[88:89], v[100:101] op_sel:[0,1] op_sel_hi:[1,0] neg_hi:[0,1]
	v_pk_add_f32 v[100:101], v[86:87], v[78:79]
	v_pk_add_f32 v[78:79], v[86:87], v[78:79] neg_lo:[0,1] neg_hi:[0,1]
	v_pk_add_f32 v[86:87], v[92:93], v[80:81]
	v_pk_add_f32 v[80:81], v[92:93], v[80:81] neg_lo:[0,1] neg_hi:[0,1]
	v_pk_add_f32 v[92:93], v[100:101], v[86:87]
	v_pk_add_f32 v[86:87], v[100:101], v[86:87] neg_lo:[0,1] neg_hi:[0,1]
	v_pk_add_f32 v[100:101], v[78:79], v[80:81] op_sel:[0,1] op_sel_hi:[1,0] neg_lo:[0,1]
	v_pk_add_f32 v[78:79], v[78:79], v[80:81] op_sel:[0,1] op_sel_hi:[1,0] neg_hi:[0,1]
	v_pk_add_f32 v[80:81], v[74:75], v[70:71]
	v_pk_add_f32 v[70:71], v[74:75], v[70:71] neg_lo:[0,1] neg_hi:[0,1]
	v_pk_add_f32 v[74:75], v[90:91], v[72:73]
	v_pk_add_f32 v[72:73], v[90:91], v[72:73] neg_lo:[0,1] neg_hi:[0,1]
	v_pk_add_f32 v[90:91], v[80:81], v[74:75]
	v_pk_add_f32 v[74:75], v[80:81], v[74:75] neg_lo:[0,1] neg_hi:[0,1]
	v_pk_add_f32 v[80:81], v[70:71], v[72:73] op_sel:[0,1] op_sel_hi:[1,0] neg_lo:[0,1]
	v_pk_add_f32 v[70:71], v[70:71], v[72:73] op_sel:[0,1] op_sel_hi:[1,0] neg_hi:[0,1]
	ds_write_b64 v37, v[98:99]
	ds_write_b64 v41, v[102:103]
	ds_write_b64 v108, v[92:93]
	ds_write_b64 v109, v[90:91]
	ds_write_b64 v110, v[94:95]
	ds_write_b64 v111, v[96:97]
	ds_write_b64 v112, v[100:101]
	ds_write_b64 v113, v[80:81]
	ds_write_b64 v114, v[76:77]
	ds_write_b64 v115, v[84:85]
	ds_write_b64 v125, v[86:87]
	ds_write_b64 v182, v[74:75]
	ds_write_b64 v183, v[82:83]
	ds_write_b64 v216, v[88:89]
	ds_write_b64 v217, v[78:79]
	ds_write_b64 v29, v[70:71]
	s_cbranch_vccz .LBB0_1041
; template <bool INV, int LST, bool HALF = false> __device__ __forceinline__ void fft_pass16(LAS cf* z, const LAS cf* Thi, const LAS cf* Tlo, int tid) {
;     ...
;         if (LST == 10 || it == 0) {
;             const int e1 = j0 << (10 - LST);
;             w[1] = cmul(Thi[e1 >> 7], Tlo[e1 & 127]);
;             w[2] = cmul(w[1], w[1]); w[3] = cmul(w[2], w[1]); w[4] = cmul(w[2], w[2]); w[5] = cmul(w[4], w[1]); w[6] = cmul(w[3], w[3]); w[7] = cmul(w[4], w[3]); w[8] = cmul(w[4], w[4]);
; #pragma unroll
;             for (int q = 9; q < 16; ++q) w[q] = cmul(w[8], w[q - 8]);
;         }
.LBB0_1039:
	s_xor_b64 s[44:45], s[44:45], -1
	s_and_b64 vcc, exec, s[44:45]
	s_cbranch_vccnz .LBB0_1038
	v_mov_b32_e32 v22, s70
	ds_read_b64 v[22:23], v22
	ds_read_b64 v[30:31], v21
	s_waitcnt lgkmcnt(0)
	v_pk_mul_f32 v[38:39], v[30:31], v[22:23] op_sel:[0,0] op_sel_hi:[0,1]
	v_pk_fma_f32 v[22:23], v[30:31], v[22:23], v[38:39] op_sel:[1,1,0] op_sel_hi:[1,0,1] neg_lo:[1,0,0]
	v_pk_mul_f32 v[30:31], v[22:23], v[22:23] op_sel:[0,0] op_sel_hi:[0,1]
	v_pk_fma_f32 v[30:31], v[22:23], v[22:23], v[30:31] op_sel:[1,1,0] op_sel_hi:[1,0,1] neg_lo:[1,0,0]
	v_pk_mul_f32 v[38:39], v[30:31], v[22:23] op_sel:[0,0] op_sel_hi:[0,1]
	v_pk_mul_f32 v[42:43], v[30:31], v[30:31] op_sel:[0,0] op_sel_hi:[0,1]
	v_pk_fma_f32 v[38:39], v[30:31], v[22:23], v[38:39] op_sel:[1,1,0] op_sel_hi:[1,0,1] neg_lo:[1,0,0]
	v_pk_fma_f32 v[42:43], v[30:31], v[30:31], v[42:43] op_sel:[1,1,0] op_sel_hi:[1,0,1] neg_lo:[1,0,0]
	v_pk_mul_f32 v[48:49], v[42:43], v[22:23] op_sel:[0,0] op_sel_hi:[0,1]
	v_pk_mul_f32 v[50:51], v[38:39], v[38:39] op_sel:[0,0] op_sel_hi:[0,1]
	v_pk_mul_f32 v[52:53], v[42:43], v[38:39] op_sel:[0,0] op_sel_hi:[0,1]
	v_pk_mul_f32 v[54:55], v[42:43], v[42:43] op_sel:[0,0] op_sel_hi:[0,1]
	v_pk_fma_f32 v[48:49], v[42:43], v[22:23], v[48:49] op_sel:[1,1,0] op_sel_hi:[1,0,1] neg_lo:[1,0,0]
	v_pk_fma_f32 v[50:51], v[38:39], v[38:39], v[50:51] op_sel:[1,1,0] op_sel_hi:[1,0,1] neg_lo:[1,0,0]
	v_pk_fma_f32 v[52:53], v[42:43], v[38:39], v[52:53] op_sel:[1,1,0] op_sel_hi:[1,0,1] neg_lo:[1,0,0]
	v_pk_fma_f32 v[54:55], v[42:43], v[42:43], v[54:55] op_sel:[1,1,0] op_sel_hi:[1,0,1] neg_lo:[1,0,0]
	v_pk_mul_f32 v[56:57], v[54:55], v[22:23] op_sel:[0,0] op_sel_hi:[0,1]
	v_pk_mul_f32 v[58:59], v[54:55], v[30:31] op_sel:[0,0] op_sel_hi:[0,1]
	v_pk_mul_f32 v[60:61], v[54:55], v[38:39] op_sel:[0,0] op_sel_hi:[0,1]
	v_pk_mul_f32 v[62:63], v[54:55], v[42:43] op_sel:[0,0] op_sel_hi:[0,1]
	v_pk_mul_f32 v[64:65], v[54:55], v[48:49] op_sel:[0,0] op_sel_hi:[0,1]
	v_pk_mul_f32 v[66:67], v[54:55], v[50:51] op_sel:[0,0] op_sel_hi:[0,1]
	v_pk_mul_f32 v[68:69], v[54:55], v[52:53] op_sel:[0,0] op_sel_hi:[0,1]
	v_pk_fma_f32 v[56:57], v[54:55], v[22:23], v[56:57] op_sel:[1,1,0] op_sel_hi:[1,0,1] neg_lo:[1,0,0]
	v_pk_fma_f32 v[58:59], v[54:55], v[30:31], v[58:59] op_sel:[1,1,0] op_sel_hi:[1,0,1] neg_lo:[1,0,0]
	v_pk_fma_f32 v[60:61], v[54:55], v[38:39], v[60:61] op_sel:[1,1,0] op_sel_hi:[1,0,1] neg_lo:[1,0,0]
	v_pk_fma_f32 v[62:63], v[54:55], v[42:43], v[62:63] op_sel:[1,1,0] op_sel_hi:[1,0,1] neg_lo:[1,0,0]
	v_pk_fma_f32 v[64:65], v[54:55], v[48:49], v[64:65] op_sel:[1,1,0] op_sel_hi:[1,0,1] neg_lo:[1,0,0]
	v_pk_fma_f32 v[66:67], v[54:55], v[50:51], v[66:67] op_sel:[1,1,0] op_sel_hi:[1,0,1] neg_lo:[1,0,0]
	v_pk_fma_f32 v[68:69], v[54:55], v[52:53], v[68:69] op_sel:[1,1,0] op_sel_hi:[1,0,1] neg_lo:[1,0,0]
	s_branch .LBB0_1038

; __device__ __forceinline__ cf add_mib(cf a, cf b) { cf r; asm("v_pk_add_f32 %0, %1, %2 op_sel:[0,1] op_sel_hi:[1,0] neg_hi:[0,1]" : "=v"(r) : "v"(a), "v"(b)); return r; }
; __device__ __forceinline__ cf add_pib(cf a, cf b) { cf r; asm("v_pk_add_f32 %0, %1, %2 op_sel:[0,1] op_sel_hi:[1,0] neg_lo:[0,1]" : "=v"(r) : "v"(a), "v"(b)); return r; }
; template <bool INV, bool HALFIN = false> __device__ __forceinline__ void dft16(cf (&x)[16]) {
; #pragma unroll
;     for (int m2 = 0; m2 < 4; ++m2) {
;         if (HALFIN) { const cf a0 = x[m2], a1 = x[4 + m2]; x[m2] = a0 + a1; x[8 + m2] = a0 - a1; x[4 + m2] = add_mib(a0, a1); x[12 + m2] = add_pib(a0, a1); }
;         else dft4<INV>(x[m2], x[4 + m2], x[8 + m2], x[12 + m2]);
;     }
;     constexpr float C1 = 0.9238795325112867f, S1 = 0.3826834323650898f, C2 = 0.7071067811865476f;
;     x[4 * 1 + 1] = tw16<INV>(x[5], C1, S1);  x[4 * 1 + 2] = tw16<INV>(x[6], C2, C2);   x[4 * 1 + 3] = tw16<INV>(x[7], S1, C1);
;     x[4 * 2 + 1] = tw16<INV>(x[9], C2, C2);  x[4 * 2 + 2] = tw16<INV>(x[10], 0.f, 1.f); x[4 * 2 + 3] = tw16<INV>(x[11], -C2, C2);
;     x[4 * 3 + 1] = tw16<INV>(x[13], S1, C1); x[4 * 3 + 2] = tw16<INV>(x[14], -C2, C2); x[4 * 3 + 3] = tw16<INV>(x[15], -C1, -S1);
; #pragma unroll
;     for (int q1 = 0; q1 < 4; ++q1) dft4<INV>(x[4 * q1], x[4 * q1 + 1], x[4 * q1 + 2], x[4 * q1 + 3]);
; }
; template <bool INV, int LST, bool HALF = false> __device__ __forceinline__ void fft_pass16(LAS cf* z, const LAS cf* Thi, const LAS cf* Tlo, int tid) {
;     ...
; #pragma unroll
;             for (int q = 0; q < 16; ++q) { cf y = z[pass_pos<LST>(base, phb, q)]; if (q) y = cmulc(y, w[q]); x[q] = y; }
;             dft16<true>(x);
; #pragma unroll
;             for (int m = 0; m < (HALF ? 8 : 16); ++m) z[pass_pos<LST>(base, phb, m)] = x[4 * (m & 3) + (m >> 2)];
.LBB0_1042:
	v_add_u32_e32 v21, s21, v169
	v_and_b32_e32 v21, 0x7c00, v21
	v_or_b32_e32 v29, v21, v122
	v_lshl_add_u32 v29, v29, 3, 0
	v_xor_b32_e32 v37, 0x20, v29
	v_xor_b32_e32 v41, 0x40, v29
	ds_read_b64 v[70:71], v37 offset:512
	v_xor_b32_e32 v108, 0x60, v29
	ds_read_b64 v[72:73], v41 offset:1024
	ds_read_b64 v[74:75], v29
	ds_read_b64 v[76:77], v108 offset:1536
	s_waitcnt lgkmcnt(3)
	v_pk_mul_f32 v[78:79], v[70:71], v[22:23] op_sel:[0,0] op_sel_hi:[0,1] neg_hi:[0,1]
	v_pk_fma_f32 v[70:71], v[70:71], v[22:23], v[78:79] op_sel:[1,1,0] op_sel_hi:[1,0,1]
	s_waitcnt lgkmcnt(2)
	v_pk_mul_f32 v[78:79], v[72:73], v[30:31] op_sel:[0,0] op_sel_hi:[0,1] neg_hi:[0,1]
	v_xor_b32_e32 v110, 0xa0, v29
	v_pk_fma_f32 v[72:73], v[72:73], v[30:31], v[78:79] op_sel:[1,1,0] op_sel_hi:[1,0,1]
	s_waitcnt lgkmcnt(0)
	v_pk_mul_f32 v[78:79], v[76:77], v[38:39] op_sel:[0,0] op_sel_hi:[0,1] neg_hi:[0,1]
	v_pk_fma_f32 v[76:77], v[76:77], v[38:39], v[78:79] op_sel:[1,1,0] op_sel_hi:[1,0,1]
	v_xor_b32_e32 v109, 0x80, v29
	v_xor_b32_e32 v111, 0xc0, v29
	ds_read_b64 v[78:79], v109 offset:2048
	v_xor_b32_e32 v112, 0xe0, v29
	ds_read_b64 v[80:81], v110 offset:2560
	ds_read_b64 v[82:83], v111 offset:3072
	ds_read_b64 v[84:85], v112 offset:3584
	s_waitcnt lgkmcnt(3)
	v_pk_mul_f32 v[86:87], v[78:79], v[42:43] op_sel:[0,0] op_sel_hi:[0,1] neg_hi:[0,1]
	v_pk_fma_f32 v[78:79], v[78:79], v[42:43], v[86:87] op_sel:[1,1,0] op_sel_hi:[1,0,1]
	s_waitcnt lgkmcnt(2)
	v_pk_mul_f32 v[86:87], v[80:81], v[48:49] op_sel:[0,0] op_sel_hi:[0,1] neg_hi:[0,1]
	v_xor_b32_e32 v114, 0x120, v29
	v_pk_fma_f32 v[80:81], v[80:81], v[48:49], v[86:87] op_sel:[1,1,0] op_sel_hi:[1,0,1]
	s_waitcnt lgkmcnt(1)
	v_pk_mul_f32 v[86:87], v[82:83], v[50:51] op_sel:[0,0] op_sel_hi:[0,1] neg_hi:[0,1]
	v_pk_fma_f32 v[82:83], v[82:83], v[50:51], v[86:87] op_sel:[1,1,0] op_sel_hi:[1,0,1]
	s_waitcnt lgkmcnt(0)
	v_pk_mul_f32 v[86:87], v[84:85], v[52:53] op_sel:[0,0] op_sel_hi:[0,1] neg_hi:[0,1]
	v_xor_b32_e32 v115, 0x140, v29
	v_pk_fma_f32 v[84:85], v[84:85], v[52:53], v[86:87] op_sel:[1,1,0] op_sel_hi:[1,0,1]
	v_xor_b32_e32 v113, 0x100, v29
	ds_read_b64 v[86:87], v113 offset:4096
	v_xor_b32_e32 v125, 0x160, v29
	ds_read_b64 v[88:89], v114 offset:4608
	ds_read_b64 v[90:91], v115 offset:5120
	ds_read_b64 v[92:93], v125 offset:5632
	s_waitcnt lgkmcnt(3)
	v_pk_mul_f32 v[94:95], v[86:87], v[54:55] op_sel:[0,0] op_sel_hi:[0,1] neg_hi:[0,1]
	v_pk_fma_f32 v[86:87], v[86:87], v[54:55], v[94:95] op_sel:[1,1,0] op_sel_hi:[1,0,1]
	s_waitcnt lgkmcnt(2)
	v_pk_mul_f32 v[94:95], v[88:89], v[56:57] op_sel:[0,0] op_sel_hi:[0,1] neg_hi:[0,1]
	v_xor_b32_e32 v183, 0x1a0, v29
	v_pk_fma_f32 v[88:89], v[88:89], v[56:57], v[94:95] op_sel:[1,1,0] op_sel_hi:[1,0,1]
	s_waitcnt lgkmcnt(1)
	v_pk_mul_f32 v[94:95], v[90:91], v[58:59] op_sel:[0,0] op_sel_hi:[0,1] neg_hi:[0,1]
	v_pk_fma_f32 v[90:91], v[90:91], v[58:59], v[94:95] op_sel:[1,1,0] op_sel_hi:[1,0,1]
	s_waitcnt lgkmcnt(0)
	v_pk_mul_f32 v[94:95], v[92:93], v[60:61] op_sel:[0,0] op_sel_hi:[0,1] neg_hi:[0,1]
	v_xor_b32_e32 v216, 0x1c0, v29
	v_pk_fma_f32 v[92:93], v[92:93], v[60:61], v[94:95] op_sel:[1,1,0] op_sel_hi:[1,0,1]
	v_xor_b32_e32 v182, 0x180, v29
	ds_read_b64 v[94:95], v182 offset:6144
	v_xor_b32_e32 v21, 0x1e0, v29
	ds_read_b64 v[96:97], v183 offset:6656
	ds_read_b64 v[98:99], v216 offset:7168
	ds_read_b64 v[100:101], v21 offset:7680
	s_waitcnt lgkmcnt(3)
	v_pk_mul_f32 v[102:103], v[94:95], v[62:63] op_sel:[0,0] op_sel_hi:[0,1] neg_hi:[0,1]
	s_mov_b32 s46, s25
	v_pk_fma_f32 v[94:95], v[94:95], v[62:63], v[102:103] op_sel:[1,1,0] op_sel_hi:[1,0,1]
	s_waitcnt lgkmcnt(2)
	v_pk_mul_f32 v[102:103], v[96:97], v[64:65] op_sel:[0,0] op_sel_hi:[0,1] neg_hi:[0,1]
	s_mov_b32 s47, s24
	v_pk_fma_f32 v[96:97], v[96:97], v[64:65], v[102:103] op_sel:[1,1,0] op_sel_hi:[1,0,1]
	s_waitcnt lgkmcnt(1)
	v_pk_mul_f32 v[102:103], v[98:99], v[66:67] op_sel:[0,0] op_sel_hi:[0,1] neg_hi:[0,1]
	s_andn2_b64 vcc, exec, s[44:45]
	v_pk_fma_f32 v[98:99], v[98:99], v[66:67], v[102:103] op_sel:[1,1,0] op_sel_hi:[1,0,1]
	s_waitcnt lgkmcnt(0)
	v_pk_mul_f32 v[102:103], v[100:101], v[68:69] op_sel:[0,0] op_sel_hi:[0,1] neg_hi:[0,1]
	s_mov_b64 s[44:45], 0
	v_pk_fma_f32 v[100:101], v[100:101], v[68:69], v[102:103] op_sel:[1,1,0] op_sel_hi:[1,0,1]
	v_pk_add_f32 v[102:103], v[74:75], v[86:87]
	v_pk_add_f32 v[74:75], v[74:75], v[86:87] neg_lo:[0,1] neg_hi:[0,1]
	v_pk_add_f32 v[86:87], v[78:79], v[94:95]
	v_pk_add_f32 v[78:79], v[78:79], v[94:95] neg_lo:[0,1] neg_hi:[0,1]
	v_pk_add_f32 v[94:95], v[102:103], v[86:87]
	v_pk_add_f32 v[86:87], v[102:103], v[86:87] neg_lo:[0,1] neg_hi:[0,1]
	v_pk_add_f32 v[102:103], v[74:75], v[78:79] op_sel:[0,1] op_sel_hi:[1,0] neg_lo:[0,1]
	v_pk_add_f32 v[74:75], v[74:75], v[78:79] op_sel:[0,1] op_sel_hi:[1,0] neg_hi:[0,1]
	v_pk_add_f32 v[78:79], v[70:71], v[88:89]
	v_pk_add_f32 v[70:71], v[70:71], v[88:89] neg_lo:[0,1] neg_hi:[0,1]
	v_pk_add_f32 v[88:89], v[80:81], v[96:97]
	v_pk_add_f32 v[80:81], v[80:81], v[96:97] neg_lo:[0,1] neg_hi:[0,1]
	v_pk_add_f32 v[96:97], v[78:79], v[88:89]
	v_pk_add_f32 v[78:79], v[78:79], v[88:89] neg_lo:[0,1] neg_hi:[0,1]
	v_pk_add_f32 v[88:89], v[70:71], v[80:81] op_sel:[0,1] op_sel_hi:[1,0] neg_lo:[0,1]
	v_pk_add_f32 v[70:71], v[70:71], v[80:81] op_sel:[0,1] op_sel_hi:[1,0] neg_hi:[0,1]
	v_pk_add_f32 v[80:81], v[72:73], v[90:91]
	v_pk_add_f32 v[72:73], v[72:73], v[90:91] neg_lo:[0,1] neg_hi:[0,1]
	v_pk_add_f32 v[90:91], v[82:83], v[98:99]
	v_pk_add_f32 v[82:83], v[82:83], v[98:99] neg_lo:[0,1] neg_hi:[0,1]
	v_pk_add_f32 v[98:99], v[80:81], v[90:91]
	v_pk_add_f32 v[80:81], v[80:81], v[90:91] neg_lo:[0,1] neg_hi:[0,1]
; __device__ __forceinline__ cf add_mib(cf a, cf b) { cf r; asm("v_pk_add_f32 %0, %1, %2 op_sel:[0,1] op_sel_hi:[1,0] neg_hi:[0,1]" : "=v"(r) : "v"(a), "v"(b)); return r; }
; __device__ __forceinline__ cf add_pib(cf a, cf b) { cf r; asm("v_pk_add_f32 %0, %1, %2 op_sel:[0,1] op_sel_hi:[1,0] neg_lo:[0,1]" : "=v"(r) : "v"(a), "v"(b)); return r; }
; template <bool INV, bool HALFIN = false> __device__ __forceinline__ void dft16(cf (&x)[16]) {
; #pragma unroll
;     for (int m2 = 0; m2 < 4; ++m2) {
;         if (HALFIN) { const cf a0 = x[m2], a1 = x[4 + m2]; x[m2] = a0 + a1; x[8 + m2] = a0 - a1; x[4 + m2] = add_mib(a0, a1); x[12 + m2] = add_pib(a0, a1); }
;         else dft4<INV>(x[m2], x[4 + m2], x[8 + m2], x[12 + m2]);
;     }
;     constexpr float C1 = 0.9238795325112867f, S1 = 0.3826834323650898f, C2 = 0.7071067811865476f;
;     x[4 * 1 + 1] = tw16<INV>(x[5], C1, S1);  x[4 * 1 + 2] = tw16<INV>(x[6], C2, C2);   x[4 * 1 + 3] = tw16<INV>(x[7], S1, C1);
;     x[4 * 2 + 1] = tw16<INV>(x[9], C2, C2);  x[4 * 2 + 2] = tw16<INV>(x[10], 0.f, 1.f); x[4 * 2 + 3] = tw16<INV>(x[11], -C2, C2);
;     x[4 * 3 + 1] = tw16<INV>(x[13], S1, C1); x[4 * 3 + 2] = tw16<INV>(x[14], -C2, C2); x[4 * 3 + 3] = tw16<INV>(x[15], -C1, -S1);
; #pragma unroll
;     for (int q1 = 0; q1 < 4; ++q1) dft4<INV>(x[4 * q1], x[4 * q1 + 1], x[4 * q1 + 2], x[4 * q1 + 3]);
; }
	v_pk_add_f32 v[90:91], v[72:73], v[82:83] op_sel:[0,1] op_sel_hi:[1,0] neg_lo:[0,1]
	v_pk_add_f32 v[72:73], v[72:73], v[82:83] op_sel:[0,1] op_sel_hi:[1,0] neg_hi:[0,1]
	v_pk_add_f32 v[82:83], v[76:77], v[92:93]
	v_pk_add_f32 v[76:77], v[76:77], v[92:93] neg_lo:[0,1] neg_hi:[0,1]
	v_pk_add_f32 v[92:93], v[84:85], v[100:101]
	v_pk_add_f32 v[84:85], v[84:85], v[100:101] neg_lo:[0,1] neg_hi:[0,1]
	v_pk_add_f32 v[100:101], v[82:83], v[92:93]
	v_pk_add_f32 v[82:83], v[82:83], v[92:93] neg_lo:[0,1] neg_hi:[0,1]
	v_pk_add_f32 v[92:93], v[76:77], v[84:85] op_sel:[0,1] op_sel_hi:[1,0] neg_lo:[0,1]
	v_pk_add_f32 v[76:77], v[76:77], v[84:85] op_sel:[0,1] op_sel_hi:[1,0] neg_hi:[0,1]
	v_pk_mul_f32 v[84:85], v[88:89], s[22:23] op_sel_hi:[1,0]
	s_nop 0
	v_pk_fma_f32 v[104:105], v[88:89], s[20:21], v[84:85] op_sel:[0,0,1] op_sel_hi:[1,0,0] neg_lo:[0,0,1]
	s_nop 0
	v_pk_mul_f32 v[84:85], v[90:91], s[24:25] op_sel_hi:[1,0]
	s_nop 0
	v_pk_fma_f32 v[88:89], v[90:91], s[24:25], v[84:85] op_sel:[0,0,1] op_sel_hi:[1,0,0] neg_lo:[0,0,1]
	v_pk_mul_f32 v[90:91], v[92:93], s[20:21] op_sel_hi:[1,0]
	s_nop 0
	v_pk_fma_f32 v[106:107], v[92:93], s[22:23], v[90:91] op_sel:[0,0,1] op_sel_hi:[1,0,0] neg_lo:[0,0,1]
	v_pk_add_f32 v[84:85], v[102:103], v[88:89]
	v_pk_mul_f32 v[90:91], v[78:79], s[24:25] op_sel_hi:[1,0]
	v_pk_add_f32 v[88:89], v[102:103], v[88:89] neg_lo:[0,1] neg_hi:[0,1]
	v_pk_fma_f32 v[92:93], v[78:79], s[24:25], v[90:91] op_sel:[0,0,1] op_sel_hi:[1,0,0] neg_lo:[0,0,1]
	s_nop 0
	v_pk_fma_f32 v[78:79], v[80:81], 0, v[80:81] op_sel:[0,0,1] op_sel_hi:[1,0,0] neg_lo:[0,0,1] neg_hi:[0,0,1]
	v_pk_fma_f32 v[80:81], v[80:81], 0, v[80:81] op_sel:[0,0,1] op_sel_hi:[1,0,0]
	s_nop 0
	v_mul_f32_e32 v80, 0x3f3504f3, v83
	v_mov_b32_e32 v79, v81
	v_pk_fma_f32 v[80:81], v[82:83], s[46:47], v[80:81] op_sel_hi:[0,1,0] neg_lo:[0,0,1] neg_hi:[0,0,1]
	v_pk_mul_f32 v[82:83], v[70:71], s[20:21] op_sel_hi:[1,0]
	s_movk_i32 s21, 0x2000
	v_pk_fma_f32 v[90:91], v[70:71], s[22:23], v[82:83] op_sel:[0,0,1] op_sel_hi:[1,0,0] neg_lo:[0,0,1] neg_hi:[0,0,1]
	v_pk_fma_f32 v[70:71], v[70:71], s[22:23], v[82:83] op_sel:[0,0,1] op_sel_hi:[1,0,0]
	s_mov_b32 s23, s37
	v_mul_f32_e32 v70, 0x3f3504f3, v73
	v_mov_b32_e32 v91, v71
	v_pk_fma_f32 v[70:71], v[72:73], s[46:47], v[70:71] op_sel_hi:[0,1,0] neg_lo:[0,0,1] neg_hi:[0,0,1]
	s_mov_b32 s46, s37
	s_mov_b32 s47, s36
	v_pk_mul_f32 v[72:73], v[76:77], s[46:47] op_sel_hi:[0,1]
	v_pk_fma_f32 v[72:73], v[76:77], s[22:23], v[72:73] op_sel:[1,0,0]
	v_pk_add_f32 v[76:77], v[94:95], v[98:99]
	v_pk_add_f32 v[82:83], v[94:95], v[98:99] neg_lo:[0,1] neg_hi:[0,1]
	v_pk_add_f32 v[94:95], v[96:97], v[100:101]
	v_pk_add_f32 v[96:97], v[96:97], v[100:101] neg_lo:[0,1] neg_hi:[0,1]
	v_pk_add_f32 v[98:99], v[76:77], v[94:95]
	v_pk_add_f32 v[76:77], v[76:77], v[94:95] neg_lo:[0,1] neg_hi:[0,1]
	v_pk_add_f32 v[94:95], v[82:83], v[96:97] op_sel:[0,1] op_sel_hi:[1,0] neg_lo:[0,1]
	v_pk_add_f32 v[82:83], v[82:83], v[96:97] op_sel:[0,1] op_sel_hi:[1,0] neg_hi:[0,1]
	v_pk_add_f32 v[96:97], v[104:105], v[106:107]
	v_pk_add_f32 v[100:101], v[104:105], v[106:107] neg_lo:[0,1] neg_hi:[0,1]
	v_pk_add_f32 v[102:103], v[84:85], v[96:97]
	v_pk_add_f32 v[84:85], v[84:85], v[96:97] neg_lo:[0,1] neg_hi:[0,1]
	v_pk_add_f32 v[96:97], v[88:89], v[100:101] op_sel:[0,1] op_sel_hi:[1,0] neg_lo:[0,1]
	v_pk_add_f32 v[88:89], v[88:89], v[100:101] op_sel:[0,1] op_sel_hi:[1,0] neg_hi:[0,1]
	v_pk_add_f32 v[100:101], v[86:87], v[78:79]
	v_pk_add_f32 v[78:79], v[86:87], v[78:79] neg_lo:[0,1] neg_hi:[0,1]
	v_pk_add_f32 v[86:87], v[92:93], v[80:81]
	v_pk_add_f32 v[80:81], v[92:93], v[80:81] neg_lo:[0,1] neg_hi:[0,1]
	v_pk_add_f32 v[92:93], v[100:101], v[86:87]
	v_pk_add_f32 v[86:87], v[100:101], v[86:87] neg_lo:[0,1] neg_hi:[0,1]
	v_pk_add_f32 v[100:101], v[78:79], v[80:81] op_sel:[0,1] op_sel_hi:[1,0] neg_lo:[0,1]
	v_pk_add_f32 v[78:79], v[78:79], v[80:81] op_sel:[0,1] op_sel_hi:[1,0] neg_hi:[0,1]
	v_pk_add_f32 v[80:81], v[74:75], v[70:71]
	v_pk_add_f32 v[70:71], v[74:75], v[70:71] neg_lo:[0,1] neg_hi:[0,1]
	v_pk_add_f32 v[74:75], v[90:91], v[72:73]
	v_pk_add_f32 v[72:73], v[90:91], v[72:73] neg_lo:[0,1] neg_hi:[0,1]
	v_pk_add_f32 v[90:91], v[80:81], v[74:75]
	v_pk_add_f32 v[74:75], v[80:81], v[74:75] neg_lo:[0,1] neg_hi:[0,1]
	v_pk_add_f32 v[80:81], v[70:71], v[72:73] op_sel:[0,1] op_sel_hi:[1,0] neg_lo:[0,1]
	v_pk_add_f32 v[70:71], v[70:71], v[72:73] op_sel:[0,1] op_sel_hi:[1,0] neg_hi:[0,1]
	ds_write_b64 v29, v[98:99]
	ds_write_b64 v37, v[102:103] offset:512
	ds_write_b64 v41, v[92:93] offset:1024
	ds_write_b64 v108, v[90:91] offset:1536
	ds_write_b64 v109, v[94:95] offset:2048
	ds_write_b64 v110, v[96:97] offset:2560
	ds_write_b64 v111, v[100:101] offset:3072
	ds_write_b64 v112, v[80:81] offset:3584
	ds_write_b64 v113, v[76:77] offset:4096
	ds_write_b64 v114, v[84:85] offset:4608
	ds_write_b64 v115, v[86:87] offset:5120
	ds_write_b64 v125, v[74:75] offset:5632
	ds_write_b64 v182, v[82:83] offset:6144
	ds_write_b64 v183, v[88:89] offset:6656
	ds_write_b64 v216, v[78:79] offset:7168
	ds_write_b64 v21, v[70:71] offset:7680
	s_cbranch_vccz .LBB0_1045
; template <bool INV, int LST, bool HALF = false> __device__ __forceinline__ void fft_pass16(LAS cf* z, const LAS cf* Thi, const LAS cf* Tlo, int tid) {
;     ...
;         if (LST == 10 || it == 0) {
;             const int e1 = j0 << (10 - LST);
;             w[1] = cmul(Thi[e1 >> 7], Tlo[e1 & 127]);
;             w[2] = cmul(w[1], w[1]); w[3] = cmul(w[2], w[1]); w[4] = cmul(w[2], w[2]); w[5] = cmul(w[4], w[1]); w[6] = cmul(w[3], w[3]); w[7] = cmul(w[4], w[3]); w[8] = cmul(w[4], w[4]);
; #pragma unroll
;             for (int q = 9; q < 16; ++q) w[q] = cmul(w[8], w[q - 8]);
;         }
.LBB0_1043:
	s_xor_b64 s[44:45], s[44:45], -1
	s_and_b64 vcc, exec, s[44:45]
	s_cbranch_vccnz .LBB0_1042
	ds_read_b64 v[22:23], v170
	ds_read_b64 v[30:31], v171
	s_waitcnt lgkmcnt(0)
	v_pk_mul_f32 v[38:39], v[22:23], v[30:31] op_sel:[0,0] op_sel_hi:[0,1]
	v_pk_fma_f32 v[22:23], v[22:23], v[30:31], v[38:39] op_sel:[1,1,0] op_sel_hi:[1,0,1] neg_lo:[1,0,0]
	v_pk_mul_f32 v[30:31], v[22:23], v[22:23] op_sel:[0,0] op_sel_hi:[0,1]
	v_pk_fma_f32 v[30:31], v[22:23], v[22:23], v[30:31] op_sel:[1,1,0] op_sel_hi:[1,0,1] neg_lo:[1,0,0]
	v_pk_mul_f32 v[38:39], v[30:31], v[22:23] op_sel:[0,0] op_sel_hi:[0,1]
	v_pk_mul_f32 v[42:43], v[30:31], v[30:31] op_sel:[0,0] op_sel_hi:[0,1]
	v_pk_fma_f32 v[38:39], v[30:31], v[22:23], v[38:39] op_sel:[1,1,0] op_sel_hi:[1,0,1] neg_lo:[1,0,0]
	v_pk_fma_f32 v[42:43], v[30:31], v[30:31], v[42:43] op_sel:[1,1,0] op_sel_hi:[1,0,1] neg_lo:[1,0,0]
	v_pk_mul_f32 v[48:49], v[42:43], v[22:23] op_sel:[0,0] op_sel_hi:[0,1]
	v_pk_mul_f32 v[50:51], v[38:39], v[38:39] op_sel:[0,0] op_sel_hi:[0,1]
	v_pk_mul_f32 v[52:53], v[42:43], v[38:39] op_sel:[0,0] op_sel_hi:[0,1]
	v_pk_mul_f32 v[54:55], v[42:43], v[42:43] op_sel:[0,0] op_sel_hi:[0,1]
	v_pk_fma_f32 v[48:49], v[42:43], v[22:23], v[48:49] op_sel:[1,1,0] op_sel_hi:[1,0,1] neg_lo:[1,0,0]
	v_pk_fma_f32 v[50:51], v[38:39], v[38:39], v[50:51] op_sel:[1,1,0] op_sel_hi:[1,0,1] neg_lo:[1,0,0]
	v_pk_fma_f32 v[52:53], v[42:43], v[38:39], v[52:53] op_sel:[1,1,0] op_sel_hi:[1,0,1] neg_lo:[1,0,0]
	v_pk_fma_f32 v[54:55], v[42:43], v[42:43], v[54:55] op_sel:[1,1,0] op_sel_hi:[1,0,1] neg_lo:[1,0,0]
	v_pk_mul_f32 v[56:57], v[54:55], v[22:23] op_sel:[0,0] op_sel_hi:[0,1]
	v_pk_mul_f32 v[58:59], v[54:55], v[30:31] op_sel:[0,0] op_sel_hi:[0,1]
	v_pk_mul_f32 v[60:61], v[54:55], v[38:39] op_sel:[0,0] op_sel_hi:[0,1]
	v_pk_mul_f32 v[62:63], v[54:55], v[42:43] op_sel:[0,0] op_sel_hi:[0,1]
	v_pk_mul_f32 v[64:65], v[54:55], v[48:49] op_sel:[0,0] op_sel_hi:[0,1]
	v_pk_mul_f32 v[66:67], v[54:55], v[50:51] op_sel:[0,0] op_sel_hi:[0,1]
	v_pk_mul_f32 v[68:69], v[54:55], v[52:53] op_sel:[0,0] op_sel_hi:[0,1]
	v_pk_fma_f32 v[56:57], v[54:55], v[22:23], v[56:57] op_sel:[1,1,0] op_sel_hi:[1,0,1] neg_lo:[1,0,0]
	v_pk_fma_f32 v[58:59], v[54:55], v[30:31], v[58:59] op_sel:[1,1,0] op_sel_hi:[1,0,1] neg_lo:[1,0,0]
	v_pk_fma_f32 v[60:61], v[54:55], v[38:39], v[60:61] op_sel:[1,1,0] op_sel_hi:[1,0,1] neg_lo:[1,0,0]
	v_pk_fma_f32 v[62:63], v[54:55], v[42:43], v[62:63] op_sel:[1,1,0] op_sel_hi:[1,0,1] neg_lo:[1,0,0]
	v_pk_fma_f32 v[64:65], v[54:55], v[48:49], v[64:65] op_sel:[1,1,0] op_sel_hi:[1,0,1] neg_lo:[1,0,0]
	v_pk_fma_f32 v[66:67], v[54:55], v[50:51], v[66:67] op_sel:[1,1,0] op_sel_hi:[1,0,1] neg_lo:[1,0,0]
	v_pk_fma_f32 v[68:69], v[54:55], v[52:53], v[68:69] op_sel:[1,1,0] op_sel_hi:[1,0,1] neg_lo:[1,0,0]
	s_branch .LBB0_1042

; template <bool INV, int LST, bool HALF = false> __device__ __forceinline__ void fft_pass16(LAS cf* z, const LAS cf* Thi, const LAS cf* Tlo, int tid) {
;     ...
;     for (int it = 0; it < 2; ++it) {
;         const int g = tid + 512 * it; const int j0 = g & (st - 1); const int base = ((g >> LST) << (LST + 4)) + j0; const int phb = PH(base);
;         if (LST == 10 || it == 0) {
;             const int e1 = j0 << (10 - LST);
;             w[1] = cmul(Thi[e1 >> 7], Tlo[e1 & 127]);
;             w[2] = cmul(w[1], w[1]); w[3] = cmul(w[2], w[1]); w[4] = cmul(w[2], w[2]); w[5] = cmul(w[4], w[1]); w[6] = cmul(w[3], w[3]); w[7] = cmul(w[4], w[3]); w[8] = cmul(w[4], w[4]);
; #pragma unroll
;             for (int q = 9; q < 16; ++q) w[q] = cmul(w[8], w[q - 8]);
;         }
;         cf x[16];
;         if (!INV) {
; #pragma unroll
;             for (int m = 0; m < 16; ++m) { if (HALF && m >= 8) x[m] = (cf){0.f, 0.f}; else x[m] = z[pass_pos<LST>(base, phb, m)]; }
;             dft16<false, HALF>(x);
; #pragma unroll
;             for (int q = 0; q < 16; ++q) { cf y = x[4 * (q & 3) + (q >> 2)]; if (q) y = cmul(y, w[q]); z[pass_pos<LST>(base, phb, q)] = y; }
;         } else {
; #pragma unroll
;             for (int q = 0; q < 16; ++q) { cf y = z[pass_pos<LST>(base, phb, q)]; if (q) y = cmulc(y, w[q]); x[q] = y; }
;             dft16<true>(x);
.LBB0_1084:
	v_add_u32_e32 v21, s52, v152
	v_and_b32_e32 v22, 0x3ff, v21
	v_lshlrev_b32_e32 v23, 4, v21
	v_lshrrev_b32_e32 v21, 4, v21
	v_and_b32_e32 v23, 0x4000, v23
	v_and_b32_e32 v29, 60, v21
	v_and_b32_e32 v21, 56, v21
	v_bitop3_b32 v22, v23, v29, v22 bitop3:0x36
	v_add_u32_e32 v21, 0, v21
	v_lshl_add_u32 v29, v22, 3, 0
	v_add_u32_e32 v21, 0x20000, v21
	ds_read2st64_b64 v[84:87], v29 offset1:16
	ds_read2st64_b64 v[88:91], v29 offset0:32 offset1:48
	ds_read2st64_b64 v[92:95], v29 offset0:64 offset1:80
	ds_read2st64_b64 v[96:99], v29 offset0:96 offset1:112
	v_add_u32_e32 v30, 0x10000, v29
	v_add_u32_e32 v110, 0x1e000, v29
	v_add_u32_e32 v37, 0x12000, v29
	v_add_u32_e32 v41, 0x14000, v29
	v_add_u32_e32 v76, 0x16000, v29
	v_add_u32_e32 v78, 0x18000, v29
	v_add_u32_e32 v80, 0x1a000, v29
	v_add_u32_e32 v82, 0x1c000, v29
	ds_read_b64 v[22:23], v21
	ds_read_b64 v[30:31], v30
	ds_read_b64 v[38:39], v37
	ds_read_b64 v[42:43], v120
	ds_read_b64 v[100:101], v41
	ds_read_b64 v[102:103], v76
	ds_read_b64 v[104:105], v78
	ds_read_b64 v[106:107], v80
	ds_read_b64 v[108:109], v82
	ds_read_b64 v[110:111], v110
	s_waitcnt lgkmcnt(6)
	v_pk_mul_f32 v[112:113], v[22:23], v[42:43] op_sel:[0,0] op_sel_hi:[0,1]
	s_mov_b32 s21, s22
	v_pk_fma_f32 v[22:23], v[22:23], v[42:43], v[112:113] op_sel:[1,1,0] op_sel_hi:[1,0,1] neg_lo:[1,0,0]
	s_mov_b32 s23, s20
	v_pk_mul_f32 v[42:43], v[22:23], v[22:23] op_sel:[0,0] op_sel_hi:[0,1]
	v_pk_mul_f32 v[112:113], v[86:87], v[22:23] op_sel:[0,0] op_sel_hi:[0,1] neg_hi:[0,1]
	s_mov_b32 s48, s25
	v_pk_fma_f32 v[42:43], v[22:23], v[22:23], v[42:43] op_sel:[1,1,0] op_sel_hi:[1,0,1] neg_lo:[1,0,0]
	v_pk_fma_f32 v[86:87], v[86:87], v[22:23], v[112:113] op_sel:[1,1,0] op_sel_hi:[1,0,1]
	s_mov_b32 s49, s24
	v_pk_mul_f32 v[112:113], v[42:43], v[22:23] op_sel:[0,0] op_sel_hi:[0,1]
	v_pk_mul_f32 v[114:115], v[42:43], v[42:43] op_sel:[0,0] op_sel_hi:[0,1]
	v_pk_mul_f32 v[230:231], v[88:89], v[42:43] op_sel:[0,0] op_sel_hi:[0,1] neg_hi:[0,1]
	s_movk_i32 s52, 0x200
	v_pk_fma_f32 v[112:113], v[42:43], v[22:23], v[112:113] op_sel:[1,1,0] op_sel_hi:[1,0,1] neg_lo:[1,0,0]
	v_pk_fma_f32 v[114:115], v[42:43], v[42:43], v[114:115] op_sel:[1,1,0] op_sel_hi:[1,0,1] neg_lo:[1,0,0]
	v_pk_fma_f32 v[88:89], v[88:89], v[42:43], v[230:231] op_sel:[1,1,0] op_sel_hi:[1,0,1]
	s_and_b64 vcc, exec, s[46:47]
	v_pk_mul_f32 v[230:231], v[114:115], v[22:23] op_sel:[0,0] op_sel_hi:[0,1]
	v_pk_mul_f32 v[232:233], v[112:113], v[112:113] op_sel:[0,0] op_sel_hi:[0,1]
	v_pk_mul_f32 v[234:235], v[114:115], v[112:113] op_sel:[0,0] op_sel_hi:[0,1]
	v_pk_mul_f32 v[236:237], v[114:115], v[114:115] op_sel:[0,0] op_sel_hi:[0,1]
	v_pk_mul_f32 v[238:239], v[90:91], v[112:113] op_sel:[0,0] op_sel_hi:[0,1] neg_hi:[0,1]
	v_pk_mul_f32 v[240:241], v[92:93], v[114:115] op_sel:[0,0] op_sel_hi:[0,1] neg_hi:[0,1]
	v_pk_fma_f32 v[230:231], v[114:115], v[22:23], v[230:231] op_sel:[1,1,0] op_sel_hi:[1,0,1] neg_lo:[1,0,0]
	v_pk_fma_f32 v[232:233], v[112:113], v[112:113], v[232:233] op_sel:[1,1,0] op_sel_hi:[1,0,1] neg_lo:[1,0,0]
	v_pk_fma_f32 v[234:235], v[114:115], v[112:113], v[234:235] op_sel:[1,1,0] op_sel_hi:[1,0,1] neg_lo:[1,0,0]
	v_pk_fma_f32 v[236:237], v[114:115], v[114:115], v[236:237] op_sel:[1,1,0] op_sel_hi:[1,0,1] neg_lo:[1,0,0]
	v_pk_fma_f32 v[90:91], v[90:91], v[112:113], v[238:239] op_sel:[1,1,0] op_sel_hi:[1,0,1]
	v_pk_fma_f32 v[92:93], v[92:93], v[114:115], v[240:241] op_sel:[1,1,0] op_sel_hi:[1,0,1]
	v_pk_mul_f32 v[252:253], v[94:95], v[230:231] op_sel:[0,0] op_sel_hi:[0,1] neg_hi:[0,1]
	v_pk_mul_f32 v[216:217], v[96:97], v[232:233] op_sel:[0,0] op_sel_hi:[0,1] neg_hi:[0,1]
	v_pk_mul_f32 v[226:227], v[98:99], v[234:235] op_sel:[0,0] op_sel_hi:[0,1] neg_hi:[0,1]
	v_pk_mul_f32 v[238:239], v[236:237], v[22:23] op_sel:[0,0] op_sel_hi:[0,1]
	v_pk_mul_f32 v[240:241], v[236:237], v[42:43] op_sel:[0,0] op_sel_hi:[0,1]
	v_pk_mul_f32 v[242:243], v[236:237], v[112:113] op_sel:[0,0] op_sel_hi:[0,1]
	v_pk_mul_f32 v[244:245], v[236:237], v[114:115] op_sel:[0,0] op_sel_hi:[0,1]
	v_pk_mul_f32 v[182:183], v[30:31], v[236:237] op_sel:[0,0] op_sel_hi:[0,1] neg_hi:[0,1]
	v_pk_mul_f32 v[246:247], v[236:237], v[230:231] op_sel:[0,0] op_sel_hi:[0,1]
	v_pk_fma_f32 v[22:23], v[236:237], v[22:23], v[238:239] op_sel:[1,1,0] op_sel_hi:[1,0,1] neg_lo:[1,0,0]
	v_pk_fma_f32 v[42:43], v[236:237], v[42:43], v[240:241] op_sel:[1,1,0] op_sel_hi:[1,0,1] neg_lo:[1,0,0]
	v_pk_mul_f32 v[248:249], v[236:237], v[232:233] op_sel:[0,0] op_sel_hi:[0,1]
	v_pk_mul_f32 v[250:251], v[236:237], v[234:235] op_sel:[0,0] op_sel_hi:[0,1]
	v_pk_fma_f32 v[30:31], v[30:31], v[236:237], v[182:183] op_sel:[1,1,0] op_sel_hi:[1,0,1]
	v_pk_fma_f32 v[112:113], v[236:237], v[112:113], v[242:243] op_sel:[1,1,0] op_sel_hi:[1,0,1] neg_lo:[1,0,0]
	v_pk_fma_f32 v[114:115], v[236:237], v[114:115], v[244:245] op_sel:[1,1,0] op_sel_hi:[1,0,1] neg_lo:[1,0,0]
	v_pk_fma_f32 v[238:239], v[236:237], v[230:231], v[246:247] op_sel:[1,1,0] op_sel_hi:[1,0,1] neg_lo:[1,0,0]
	v_pk_fma_f32 v[240:241], v[236:237], v[232:233], v[248:249] op_sel:[1,1,0] op_sel_hi:[1,0,1] neg_lo:[1,0,0]
	v_pk_fma_f32 v[242:243], v[236:237], v[234:235], v[250:251] op_sel:[1,1,0] op_sel_hi:[1,0,1] neg_lo:[1,0,0]
	v_pk_fma_f32 v[94:95], v[94:95], v[230:231], v[252:253] op_sel:[1,1,0] op_sel_hi:[1,0,1]
	v_pk_fma_f32 v[96:97], v[96:97], v[232:233], v[216:217] op_sel:[1,1,0] op_sel_hi:[1,0,1]
	v_pk_fma_f32 v[98:99], v[98:99], v[234:235], v[226:227] op_sel:[1,1,0] op_sel_hi:[1,0,1]
	v_pk_mul_f32 v[182:183], v[38:39], v[22:23] op_sel:[0,0] op_sel_hi:[0,1] neg_hi:[0,1]
	s_waitcnt lgkmcnt(5)
	v_pk_mul_f32 v[216:217], v[100:101], v[42:43] op_sel:[0,0] op_sel_hi:[0,1] neg_hi:[0,1]
	s_waitcnt lgkmcnt(4)
; __device__ __forceinline__ cf add_mib(cf a, cf b) { cf r; asm("v_pk_add_f32 %0, %1, %2 op_sel:[0,1] op_sel_hi:[1,0] neg_hi:[0,1]" : "=v"(r) : "v"(a), "v"(b)); return r; }
; __device__ __forceinline__ cf add_pib(cf a, cf b) { cf r; asm("v_pk_add_f32 %0, %1, %2 op_sel:[0,1] op_sel_hi:[1,0] neg_lo:[0,1]" : "=v"(r) : "v"(a), "v"(b)); return r; }
; template <bool INV, bool HALFIN = false> __device__ __forceinline__ void dft16(cf (&x)[16]) {
; #pragma unroll
;     for (int m2 = 0; m2 < 4; ++m2) {
;         if (HALFIN) { const cf a0 = x[m2], a1 = x[4 + m2]; x[m2] = a0 + a1; x[8 + m2] = a0 - a1; x[4 + m2] = add_mib(a0, a1); x[12 + m2] = add_pib(a0, a1); }
;         else dft4<INV>(x[m2], x[4 + m2], x[8 + m2], x[12 + m2]);
;     }
;     constexpr float C1 = 0.9238795325112867f, S1 = 0.3826834323650898f, C2 = 0.7071067811865476f;
;     x[4 * 1 + 1] = tw16<INV>(x[5], C1, S1);  x[4 * 1 + 2] = tw16<INV>(x[6], C2, C2);   x[4 * 1 + 3] = tw16<INV>(x[7], S1, C1);
;     x[4 * 2 + 1] = tw16<INV>(x[9], C2, C2);  x[4 * 2 + 2] = tw16<INV>(x[10], 0.f, 1.f); x[4 * 2 + 3] = tw16<INV>(x[11], -C2, C2);
;     x[4 * 3 + 1] = tw16<INV>(x[13], S1, C1); x[4 * 3 + 2] = tw16<INV>(x[14], -C2, C2); x[4 * 3 + 3] = tw16<INV>(x[15], -C1, -S1);
; #pragma unroll
;     for (int q1 = 0; q1 < 4; ++q1) dft4<INV>(x[4 * q1], x[4 * q1 + 1], x[4 * q1 + 2], x[4 * q1 + 3]);
; }
; template <bool INV, int LST, bool HALF = false> __device__ __forceinline__ void fft_pass16(LAS cf* z, const LAS cf* Thi, const LAS cf* Tlo, int tid) {
;     ...
; #pragma unroll
;             for (int m = 0; m < (HALF ? 8 : 16); ++m) z[pass_pos<LST>(base, phb, m)] = x[4 * (m & 3) + (m >> 2)];
	v_pk_mul_f32 v[226:227], v[102:103], v[112:113] op_sel:[0,0] op_sel_hi:[0,1] neg_hi:[0,1]
	s_waitcnt lgkmcnt(3)
	v_pk_mul_f32 v[230:231], v[104:105], v[114:115] op_sel:[0,0] op_sel_hi:[0,1] neg_hi:[0,1]
	s_waitcnt lgkmcnt(2)
	v_pk_mul_f32 v[232:233], v[106:107], v[238:239] op_sel:[0,0] op_sel_hi:[0,1] neg_hi:[0,1]
	s_waitcnt lgkmcnt(1)
	v_pk_mul_f32 v[234:235], v[108:109], v[240:241] op_sel:[0,0] op_sel_hi:[0,1] neg_hi:[0,1]
	v_pk_add_f32 v[244:245], v[84:85], v[30:31]
	v_pk_add_f32 v[30:31], v[84:85], v[30:31] neg_lo:[0,1] neg_hi:[0,1]
	v_pk_fma_f32 v[22:23], v[38:39], v[22:23], v[182:183] op_sel:[1,1,0] op_sel_hi:[1,0,1]
	v_pk_fma_f32 v[38:39], v[100:101], v[42:43], v[216:217] op_sel:[1,1,0] op_sel_hi:[1,0,1]
	v_pk_fma_f32 v[42:43], v[102:103], v[112:113], v[226:227] op_sel:[1,1,0] op_sel_hi:[1,0,1]
	v_pk_fma_f32 v[84:85], v[104:105], v[114:115], v[230:231] op_sel:[1,1,0] op_sel_hi:[1,0,1]
	v_pk_fma_f32 v[100:101], v[106:107], v[238:239], v[232:233] op_sel:[1,1,0] op_sel_hi:[1,0,1]
	v_pk_fma_f32 v[102:103], v[108:109], v[240:241], v[234:235] op_sel:[1,1,0] op_sel_hi:[1,0,1]
	s_waitcnt lgkmcnt(0)
	v_pk_mul_f32 v[236:237], v[110:111], v[242:243] op_sel:[0,0] op_sel_hi:[0,1] neg_hi:[0,1]
	s_mov_b64 s[46:47], 0
	v_pk_fma_f32 v[104:105], v[110:111], v[242:243], v[236:237] op_sel:[1,1,0] op_sel_hi:[1,0,1]
	v_pk_add_f32 v[106:107], v[92:93], v[84:85]
	v_pk_add_f32 v[84:85], v[92:93], v[84:85] neg_lo:[0,1] neg_hi:[0,1]
	v_pk_add_f32 v[92:93], v[86:87], v[22:23]
	v_pk_add_f32 v[22:23], v[86:87], v[22:23] neg_lo:[0,1] neg_hi:[0,1]
	v_pk_add_f32 v[86:87], v[94:95], v[100:101]
	v_pk_add_f32 v[94:95], v[94:95], v[100:101] neg_lo:[0,1] neg_hi:[0,1]
	v_pk_add_f32 v[100:101], v[88:89], v[38:39]
	v_pk_add_f32 v[38:39], v[88:89], v[38:39] neg_lo:[0,1] neg_hi:[0,1]
	v_pk_add_f32 v[88:89], v[96:97], v[102:103]
	v_pk_add_f32 v[96:97], v[96:97], v[102:103] neg_lo:[0,1] neg_hi:[0,1]
	v_pk_add_f32 v[102:103], v[90:91], v[42:43]
	v_pk_add_f32 v[42:43], v[90:91], v[42:43] neg_lo:[0,1] neg_hi:[0,1]
	v_pk_add_f32 v[90:91], v[98:99], v[104:105]
	v_pk_add_f32 v[98:99], v[98:99], v[104:105] neg_lo:[0,1] neg_hi:[0,1]
	v_pk_add_f32 v[104:105], v[244:245], v[106:107]
	v_pk_add_f32 v[108:109], v[30:31], v[84:85] op_sel:[0,1] op_sel_hi:[1,0] neg_lo:[0,1]
	v_pk_add_f32 v[30:31], v[30:31], v[84:85] op_sel:[0,1] op_sel_hi:[1,0] neg_hi:[0,1]
	v_pk_add_f32 v[84:85], v[92:93], v[86:87]
	v_pk_add_f32 v[86:87], v[92:93], v[86:87] neg_lo:[0,1] neg_hi:[0,1]
	v_pk_add_f32 v[92:93], v[22:23], v[94:95] op_sel:[0,1] op_sel_hi:[1,0] neg_lo:[0,1]
	v_pk_add_f32 v[22:23], v[22:23], v[94:95] op_sel:[0,1] op_sel_hi:[1,0] neg_hi:[0,1]
	v_pk_add_f32 v[94:95], v[100:101], v[88:89]
	v_pk_add_f32 v[88:89], v[100:101], v[88:89] neg_lo:[0,1] neg_hi:[0,1]
	v_pk_add_f32 v[100:101], v[38:39], v[96:97] op_sel:[0,1] op_sel_hi:[1,0] neg_lo:[0,1]
	v_pk_add_f32 v[38:39], v[38:39], v[96:97] op_sel:[0,1] op_sel_hi:[1,0] neg_hi:[0,1]
	v_pk_add_f32 v[96:97], v[102:103], v[90:91]
	v_pk_add_f32 v[90:91], v[102:103], v[90:91] neg_lo:[0,1] neg_hi:[0,1]
	v_pk_add_f32 v[102:103], v[42:43], v[98:99] op_sel:[0,1] op_sel_hi:[1,0] neg_lo:[0,1]
	v_pk_add_f32 v[42:43], v[42:43], v[98:99] op_sel:[0,1] op_sel_hi:[1,0] neg_hi:[0,1]
	v_mul_f32_e32 v76, 0x3ec3ef15, v93
	v_mul_f32_e32 v78, 0x3ec3ef15, v92
	v_pk_mul_f32 v[98:99], v[100:101], s[24:25] op_sel_hi:[1,0]
	v_pk_mul_f32 v[110:111], v[102:103], s[20:21] op_sel_hi:[1,0]
	v_pk_mul_f32 v[112:113], v[86:87], s[24:25] op_sel_hi:[1,0]
	v_pk_fma_f32 v[114:115], v[88:89], 0, v[88:89] op_sel:[0,0,1] op_sel_hi:[1,0,0] neg_lo:[0,0,1]
	v_mul_f32_e32 v80, 0x3f3504f3, v91
	v_pk_mul_f32 v[182:183], v[22:23], s[20:21] op_sel_hi:[1,0]
	v_mul_f32_e32 v82, 0x3f3504f3, v39
	v_pk_add_f32 v[226:227], v[104:105], v[94:95]
	v_pk_add_f32 v[94:95], v[104:105], v[94:95] neg_lo:[0,1] neg_hi:[0,1]
	v_pk_add_f32 v[104:105], v[84:85], v[96:97]
	v_pk_add_f32 v[84:85], v[84:85], v[96:97] neg_lo:[0,1] neg_hi:[0,1]
	v_pk_fma_f32 v[96:97], v[92:93], s[20:21], v[76:77] op_sel_hi:[1,1,0] neg_lo:[0,0,1] neg_hi:[0,0,1]
	v_pk_fma_f32 v[92:93], v[92:93], s[22:23], v[78:79] op_sel_hi:[1,1,0]
	v_pk_fma_f32 v[230:231], v[100:101], s[24:25], v[98:99] op_sel:[0,0,1] op_sel_hi:[1,0,0] neg_lo:[0,0,1]
	v_pk_fma_f32 v[100:101], v[102:103], s[22:23], v[110:111] op_sel:[0,0,1] op_sel_hi:[1,0,0] neg_lo:[0,0,1]
	v_pk_mul_f32 v[216:217], v[42:43], s[20:21] op_sel_hi:[0,1]
	v_pk_fma_f32 v[110:111], v[86:87], s[24:25], v[112:113] op_sel:[0,0,1] op_sel_hi:[1,0,0] neg_lo:[0,0,1]
	v_pk_fma_f32 v[88:89], v[90:91], s[48:49], v[80:81] op_sel_hi:[0,1,0] neg_lo:[0,0,1] neg_hi:[0,0,1]
	v_pk_fma_f32 v[90:91], v[22:23], s[22:23], v[182:183] op_sel:[0,0,1] op_sel_hi:[1,0,0] neg_lo:[0,0,1]
	v_pk_fma_f32 v[38:39], v[38:39], s[48:49], v[82:83] op_sel_hi:[0,1,0] neg_lo:[0,0,1] neg_hi:[0,0,1]
	s_mov_b32 s23, s37
	v_mov_b32_e32 v97, v93
	v_pk_add_f32 v[106:107], v[244:245], v[106:107] neg_lo:[0,1] neg_hi:[0,1]
	v_pk_fma_f32 v[22:23], v[42:43], s[22:23], v[216:217] op_sel:[1,0,0] neg_lo:[0,0,1] neg_hi:[0,0,1]
	v_pk_add_f32 v[92:93], v[30:31], v[38:39]
	v_pk_add_f32 v[30:31], v[30:31], v[38:39] neg_lo:[0,1] neg_hi:[0,1]
	v_pk_add_f32 v[38:39], v[108:109], v[230:231]
	v_pk_add_f32 v[98:99], v[96:97], v[100:101]
	v_pk_add_f32 v[104:105], v[226:227], v[104:105]
	v_pk_add_f32 v[42:43], v[106:107], v[114:115]
	v_pk_add_f32 v[86:87], v[106:107], v[114:115] neg_lo:[0,1] neg_hi:[0,1]
	v_pk_add_f32 v[96:97], v[96:97], v[100:101] neg_lo:[0,1] neg_hi:[0,1]
	v_pk_add_f32 v[100:101], v[110:111], v[88:89]
	v_pk_add_f32 v[88:89], v[110:111], v[88:89] neg_lo:[0,1] neg_hi:[0,1]
	v_pk_add_f32 v[102:103], v[90:91], v[22:23]
	v_pk_add_f32 v[22:23], v[90:91], v[22:23] neg_lo:[0,1] neg_hi:[0,1]
	v_pk_add_f32 v[38:39], v[38:39], v[98:99]
	v_pk_add_f32 v[84:85], v[94:95], v[84:85] op_sel:[0,1] op_sel_hi:[1,0] neg_lo:[0,1]
	v_pk_add_f32 v[94:95], v[108:109], v[230:231] neg_lo:[0,1] neg_hi:[0,1]
	v_pk_add_f32 v[42:43], v[42:43], v[100:101]
	v_pk_add_f32 v[90:91], v[94:95], v[96:97] op_sel:[0,1] op_sel_hi:[1,0] neg_lo:[0,1]
	v_pk_add_f32 v[86:87], v[86:87], v[88:89] op_sel:[0,1] op_sel_hi:[1,0] neg_lo:[0,1]
	v_pk_add_f32 v[88:89], v[92:93], v[102:103]
	v_pk_add_f32 v[22:23], v[30:31], v[22:23] op_sel:[0,1] op_sel_hi:[1,0] neg_lo:[0,1]
	ds_write2st64_b64 v29, v[104:105], v[38:39] offset1:16
	ds_write2st64_b64 v29, v[42:43], v[88:89] offset0:32 offset1:48
	ds_write2st64_b64 v29, v[84:85], v[90:91] offset0:64 offset1:80
	ds_write2st64_b64 v29, v[86:87], v[22:23] offset0:96 offset1:112
	s_cbranch_vccnz .LBB0_1084
; #define LAS __attribute__((address_space(3)))
; __device__ __forceinline__ void hyena_phase(LAS unsigned char* L, const Args& a, int vcu, int G) {
;     ...
;         float xa[2][8], xb[2][8];
;         {
;             const int r0a = ca, r0b = ca + 1;
;             const float wa0 = cw[r0a], wa1 = cw[3072 + r0a], wa2 = cw[6144 + r0a], c0a = cb[r0a];
;             const float wb0 = cw[r0b], wb1 = cw[3072 + r0b], wb2 = cw[6144 + r0b], c0b = cb[r0b];
;             const unsigned* p0a = (const unsigned*)(ZT + (size_t)r0a * ZLD + (size_t)b * SEQ); const unsigned* p0b = (const unsigned*)(ZT + (size_t)r0b * ZLD + (size_t)b * SEQ);
; #pragma unroll
;             for (int i = 0; i < 2; ++i) { const int cidx = tid + 512 * i; conv8(p0a, cidx, wa0, wa1, wa2, c0a, xa[i]); conv8(p0b, cidx, wb0, wb1, wb2, c0b, xb[i]); }
;         }
;         if (unit + G < 4096) HY_PREFETCH(unit + G);
;         fft_pass16<true, 10, true>(z, Thi, Tlo, tid);
;         {
;             const float ska = skip[ca], skb = skip[ca + 1];
;             u32x4* ga = (u32x4*)(Gc + (size_t)ca * GLD + (size_t)b * SEQ); u32x4* gb = (u32x4*)(Gc + (size_t)(ca + 1) * GLD + (size_t)b * SEQ);
; #pragma unroll
;             for (int i = 0; i < 2; ++i) { const int cidx = tid + 512 * i;
;                 float ya[8], yb[8];
; #pragma unroll
;                 for (int e = 0; e < 8; e += 2) { const f32x4 y = *(LAS f32x4*)(z + PH(8 * cidx + e)); ya[e] = y[0]; yb[e] = y[1]; ya[e + 1] = y[2]; yb[e + 1] = y[3]; }
	s_waitcnt vmcnt(0)
	v_and_b32_e32 v23, 0xffff0000, v60
	v_and_b32_e32 v60, 0xffff0000, v61
	v_mov_b32_e32 v84, v69
	v_mov_b32_e32 v85, v65
	v_mov_b32_e32 v22, v60
	v_lshlrev_b32_e32 v30, 16, v61
	v_pk_mul_f32 v[22:23], v[84:85], v[22:23]
	v_lshlrev_b32_e32 v61, 16, v62
	v_pk_fma_f32 v[22:23], v[84:85], v[30:31], v[22:23] op_sel:[0,0,1] op_sel_hi:[1,0,0]
	v_and_b32_e32 v39, 16, v63
	v_and_b32_e32 v38, 0xffff0000, v62
	v_pk_fma_f32 v[22:23], v[66:67], v[60:61], v[22:23] op_sel:[1,0,0]
	v_lshlrev_b32_e32 v91, 16, v74
	v_pk_add_f32 v[42:43], v[70:71], v[22:23] op_sel:[1,0]
	v_pk_mov_b32 v[22:23], v[60:61], v[38:39] op_sel:[1,0]
	v_and_b32_e32 v87, 0xffff0000, v74
	v_pk_mul_f32 v[22:23], v[68:69], v[22:23] op_sel:[1,0]
	v_and_b32_e32 v88, 0xffff0000, v63
	v_mov_b32_e32 v86, v91
	v_lshlrev_b32_e32 v93, 16, v63
	v_mov_b32_e32 v92, v38
	v_pk_fma_f32 v[22:23], v[64:65], v[60:61], v[22:23] op_sel:[1,0,0]
	v_and_b32_e32 v89, 16, v74
	v_mov_b32_e32 v90, v88
	v_pk_fma_f32 v[22:23], v[66:67], v[92:93], v[22:23] op_sel:[1,0,0]
	v_pk_mul_f32 v[30:31], v[68:69], v[86:87] op_sel:[1,0]
	v_pk_add_f32 v[38:39], v[70:71], v[22:23] op_sel:[1,0]
	v_pk_mov_b32 v[22:23], v[92:93], v[88:89] op_sel:[1,0]
	v_pk_fma_f32 v[30:31], v[64:65], v[90:91], v[30:31] op_sel:[1,0,0]
	v_mov_b32_e32 v82, v87
	v_and_b32_e32 v96, 0xffff0000, v57
	v_pk_mul_f32 v[22:23], v[68:69], v[22:23] op_sel:[1,0]
	v_pk_fma_f32 v[30:31], v[66:67], v[82:83], v[30:31] op_sel:[1,0,0]
	v_and_b32_e32 v61, 0xffff0000, v56
	v_mov_b32_e32 v82, v68
	v_mov_b32_e32 v83, v64
	v_mov_b32_e32 v60, v96
	v_pk_fma_f32 v[22:23], v[64:65], v[92:93], v[22:23] op_sel:[1,0,0]
	v_lshlrev_b32_e32 v56, 16, v57
	v_and_b32_e32 v88, 0xffff0000, v59
	v_and_b32_e32 v93, 16, v59
	v_and_b32_e32 v92, 0xffff0000, v58
	v_lshlrev_b32_e32 v95, 16, v59
	v_lshlrev_b32_e32 v97, 16, v58
	v_pk_mul_f32 v[58:59], v[82:83], v[60:61]
	v_mov_b32_e32 v94, v92
	v_pk_fma_f32 v[56:57], v[82:83], v[56:57], v[58:59] op_sel:[0,0,1] op_sel_hi:[1,0,0]
	s_add_u32 s38, s14, s38
	v_pk_fma_f32 v[56:57], v[66:67], v[96:97], v[56:57] op_sel_hi:[0,1,1]
	v_pk_add_f32 v[62:63], v[70:71], v[56:57] op_sel_hi:[0,1]
	v_pk_mov_b32 v[56:57], v[96:97], v[92:93] op_sel:[1,0]
	v_and_b32_e32 v89, 16, v72
	v_pk_mul_f32 v[56:57], v[68:69], v[56:57] op_sel_hi:[0,1]
	v_pk_fma_f32 v[56:57], v[64:65], v[96:97], v[56:57] op_sel_hi:[0,1,1]
	v_pk_fma_f32 v[56:57], v[66:67], v[94:95], v[56:57] op_sel_hi:[0,1,1]
	s_addc_u32 s39, s15, s39
	v_pk_fma_f32 v[22:23], v[66:67], v[90:91], v[22:23] op_sel:[1,0,0]
	v_mov_b32_e32 v90, v88
	v_pk_add_f32 v[60:61], v[70:71], v[56:57] op_sel_hi:[0,1]
	v_pk_mov_b32 v[56:57], v[94:95], v[88:89] op_sel:[1,0]
	s_waitcnt lgkmcnt(0)
	s_barrier
	global_load_dwordx2 v[88:89], v117, s[38:39]
	v_and_b32_e32 v87, 0xffff0000, v72
	v_lshlrev_b32_e32 v91, 16, v72
	v_lshlrev_b32_e32 v72, 16, v52
	v_and_b32_e32 v52, 0xffff0000, v52
	v_mov_b32_e32 v78, v52
	v_pk_mul_f32 v[78:79], v[84:85], v[78:79]
	v_and_b32_e32 v92, 0xffff0000, v53
	v_lshlrev_b32_e32 v53, 16, v53
	v_pk_fma_f32 v[78:79], v[84:85], v[72:73], v[78:79] op_sel:[0,0,1] op_sel_hi:[1,0,0]
	v_mov_b32_e32 v86, v91
	v_and_b32_e32 v93, 16, v54
	v_pk_fma_f32 v[78:79], v[66:67], v[52:53], v[78:79] op_sel:[1,0,0]
	v_pk_mul_f32 v[56:57], v[68:69], v[56:57] op_sel_hi:[0,1]
	v_pk_mul_f32 v[58:59], v[68:69], v[86:87] op_sel_hi:[0,1]
	v_pk_add_f32 v[84:85], v[70:71], v[78:79] op_sel:[1,0]
	v_pk_mov_b32 v[78:79], v[52:53], v[92:93] op_sel:[1,0]
	v_pk_fma_f32 v[56:57], v[64:65], v[94:95], v[56:57] op_sel_hi:[0,1,1]
	v_pk_fma_f32 v[58:59], v[64:65], v[90:91], v[58:59] op_sel_hi:[0,1,1]
	v_mov_b32_e32 v80, v87
	v_pk_mul_f32 v[78:79], v[68:69], v[78:79] op_sel:[1,0]
	v_pk_fma_f32 v[56:57], v[66:67], v[90:91], v[56:57] op_sel_hi:[0,1,1]
	v_pk_fma_f32 v[58:59], v[66:67], v[80:81], v[58:59] op_sel_hi:[0,1,1]
	v_and_b32_e32 v81, 0xffff0000, v55
	v_and_b32_e32 v87, 16, v55
	v_and_b32_e32 v86, 0xffff0000, v54
	v_lshlrev_b32_e32 v91, 16, v55
	v_lshlrev_b32_e32 v55, 16, v54
	v_mov_b32_e32 v54, v92
	v_pk_fma_f32 v[52:53], v[64:65], v[52:53], v[78:79] op_sel:[1,0,0]
	v_mov_b32_e32 v90, v86
	v_pk_fma_f32 v[52:53], v[66:67], v[54:55], v[52:53] op_sel:[1,0,0]
	v_mov_b32_e32 v80, v91
	v_pk_add_f32 v[92:93], v[70:71], v[52:53] op_sel:[1,0]
	v_pk_mov_b32 v[52:53], v[54:55], v[86:87] op_sel:[1,0]
	v_mov_b32_e32 v76, v81
	v_pk_mul_f32 v[52:53], v[68:69], v[52:53] op_sel:[1,0]
	v_lshlrev_b32_e32 v79, 16, v51
	v_pk_fma_f32 v[52:53], v[64:65], v[54:55], v[52:53] op_sel:[1,0,0]
	v_and_b32_e32 v55, 0xffff0000, v51
	v_pk_fma_f32 v[52:53], v[66:67], v[90:91], v[52:53] op_sel:[1,0,0]
	v_mov_b32_e32 v54, v79
	v_pk_add_f32 v[86:87], v[70:71], v[52:53] op_sel:[1,0]
	v_pk_mul_f32 v[52:53], v[68:69], v[80:81] op_sel:[1,0]
	v_and_b32_e32 v80, 0xffff0000, v49
	v_pk_fma_f32 v[52:53], v[64:65], v[90:91], v[52:53] op_sel:[1,0,0]
	v_lshlrev_b32_e32 v49, 16, v49
	v_pk_fma_f32 v[52:53], v[66:67], v[76:77], v[52:53] op_sel:[1,0,0]
	v_and_b32_e32 v81, 16, v50
	v_pk_add_f32 v[90:91], v[70:71], v[52:53] op_sel:[1,0]
	v_lshlrev_b32_e32 v52, 16, v48
	v_and_b32_e32 v48, 0xffff0000, v48
	v_mov_b32_e32 v74, v48
	v_pk_mul_f32 v[74:75], v[82:83], v[74:75]
	v_and_b32_e32 v77, 16, v51
	v_pk_fma_f32 v[52:53], v[82:83], v[52:53], v[74:75] op_sel:[0,0,1] op_sel_hi:[1,0,0]
	v_and_b32_e32 v76, 0xffff0000, v50
	v_pk_fma_f32 v[52:53], v[66:67], v[48:49], v[52:53] op_sel_hi:[0,1,1]
	v_pk_add_f32 v[82:83], v[70:71], v[52:53] op_sel_hi:[0,1]
	v_pk_mov_b32 v[52:53], v[48:49], v[80:81] op_sel:[1,0]
	v_lshlrev_b32_e32 v51, 16, v50
	v_pk_mul_f32 v[52:53], v[68:69], v[52:53] op_sel_hi:[0,1]
	v_mov_b32_e32 v50, v80
	v_pk_fma_f32 v[48:49], v[64:65], v[48:49], v[52:53] op_sel_hi:[0,1,1]
	v_pk_fma_f32 v[48:49], v[66:67], v[50:51], v[48:49] op_sel_hi:[0,1,1]
	v_pk_add_f32 v[80:81], v[70:71], v[48:49] op_sel_hi:[0,1]
	v_pk_mov_b32 v[48:49], v[50:51], v[76:77] op_sel:[1,0]
	v_mov_b32_e32 v78, v76
	v_pk_mul_f32 v[48:49], v[68:69], v[48:49] op_sel_hi:[0,1]
	v_pk_fma_f32 v[48:49], v[64:65], v[50:51], v[48:49] op_sel_hi:[0,1,1]
	v_pk_fma_f32 v[48:49], v[66:67], v[78:79], v[48:49] op_sel_hi:[0,1,1]
	v_pk_add_f32 v[94:95], v[70:71], v[48:49] op_sel_hi:[0,1]
	v_pk_mul_f32 v[48:49], v[68:69], v[54:55] op_sel_hi:[0,1]
	v_pk_fma_f32 v[48:49], v[64:65], v[78:79], v[48:49] op_sel_hi:[0,1,1]
	v_mov_b32_e32 v72, v55
	v_pk_fma_f32 v[48:49], v[66:67], v[72:73], v[48:49] op_sel_hi:[0,1,1]
	v_pk_add_f32 v[22:23], v[70:71], v[22:23] op_sel:[1,0]
	v_pk_add_f32 v[30:31], v[70:71], v[30:31] op_sel:[1,0]
	v_pk_add_f32 v[56:57], v[70:71], v[56:57] op_sel_hi:[0,1]
	v_pk_add_f32 v[58:59], v[70:71], v[58:59] op_sel_hi:[0,1]
	v_pk_add_f32 v[96:97], v[70:71], v[48:49] op_sel_hi:[0,1]
	ds_read_b128 v[48:51], v178
	ds_read_b128 v[52:55], v179
	ds_read_b128 v[64:67], v180
	ds_read_b128 v[68:71], v181
	ds_read_b128 v[72:75], v177
	s_lshl_b64 s[38:39], s[44:45], 1
	s_waitcnt lgkmcnt(4)
; __device__ __forceinline__ unsigned pk2(float lo, float hi) { f32x2 v = {lo, hi}; bf16x2_t b = __builtin_convertvector(v, bf16x2_t); return __builtin_bit_cast(unsigned, b); }
; #define LAS __attribute__((address_space(3)))
; __device__ __forceinline__ void hyena_phase(LAS unsigned char* L, const Args& a, int vcu, int G) {
;     ...
;         {
;             const float ska = skip[ca], skb = skip[ca + 1];
;             u32x4* ga = (u32x4*)(Gc + (size_t)ca * GLD + (size_t)b * SEQ); u32x4* gb = (u32x4*)(Gc + (size_t)(ca + 1) * GLD + (size_t)b * SEQ);
; #pragma unroll
;             for (int i = 0; i < 2; ++i) { const int cidx = tid + 512 * i;
;                 float ya[8], yb[8];
; #pragma unroll
;                 for (int e = 0; e < 8; e += 2) { const f32x4 y = *(LAS f32x4*)(z + PH(8 * cidx + e)); ya[e] = y[0]; yb[e] = y[1]; ya[e + 1] = y[2]; yb[e + 1] = y[3]; }
;                 u32x4 oa, ob;
;                 oa.x = pk2((ya[0] + ua[i][0] * ska) * xa[i][0], (ya[1] + ua[i][1] * ska) * xa[i][1]); oa.y = pk2((ya[2] + ua[i][2] * ska) * xa[i][2], (ya[3] + ua[i][3] * ska) * xa[i][3]);
;                 oa.z = pk2((ya[4] + ua[i][4] * ska) * xa[i][4], (ya[5] + ua[i][5] * ska) * xa[i][5]); oa.w = pk2((ya[6] + ua[i][6] * ska) * xa[i][6], (ya[7] + ua[i][7] * ska) * xa[i][7]);
;                 ob.x = pk2((yb[0] + ub[i][0] * skb) * xb[i][0], (yb[1] + ub[i][1] * skb) * xb[i][1]); ob.y = pk2((yb[2] + ub[i][2] * skb) * xb[i][2], (yb[3] + ub[i][3] * skb) * xb[i][3]);
;                 ob.z = pk2((yb[4] + ub[i][4] * skb) * xb[i][4], (yb[5] + ub[i][5] * skb) * xb[i][5]); ob.w = pk2((yb[6] + ub[i][6] * skb) * xb[i][6], (yb[7] + ub[i][7] * skb) * xb[i][7]);
;                 ga[cidx] = oa; gb[cidx] = ob; }
;         }
;         __syncthreads();
	v_mov_b32_e32 v76, v48
	v_mov_b32_e32 v77, v50
	s_waitcnt lgkmcnt(3)
	v_mov_b32_e32 v78, v52
	v_mov_b32_e32 v79, v54
	s_add_u32 s21, s60, s38
	s_waitcnt vmcnt(0)
	v_pk_fma_f32 v[76:77], v[132:133], v[88:89], v[76:77] op_sel_hi:[1,0,1]
	v_pk_fma_f32 v[78:79], v[128:129], v[88:89], v[78:79] op_sel_hi:[1,0,1]
	s_addc_u32 s23, s61, s39
	v_pk_mul_f32 v[76:77], v[82:83], v[76:77]
	v_pk_mul_f32 v[78:79], v[80:81], v[78:79]
	s_add_u32 s38, s21, s73
	v_cvt_pk_bf16_f32 v76, v76, v77
	v_cvt_pk_bf16_f32 v77, v78, v79
	s_waitcnt lgkmcnt(2)
	v_mov_b32_e32 v78, v64
	v_mov_b32_e32 v79, v66
	v_mov_b32_e32 v50, v49
	v_mov_b32_e32 v54, v53
	s_addc_u32 s39, s23, 0
	s_lshl_b64 s[40:41], s[40:41], 1
	v_pk_fma_f32 v[78:79], v[130:131], v[88:89], v[78:79] op_sel_hi:[1,0,1]
	v_pk_fma_f32 v[48:49], v[134:135], v[88:89], v[50:51] op_sel:[0,1,0]
	v_pk_fma_f32 v[50:51], v[136:137], v[88:89], v[54:55] op_sel:[0,1,0]
	s_add_u32 s21, s60, s40
	v_pk_mul_f32 v[78:79], v[94:95], v[78:79]
	s_waitcnt lgkmcnt(1)
	v_mov_b32_e32 v94, v68
	v_mov_b32_e32 v95, v70
	v_pk_mul_f32 v[48:49], v[84:85], v[48:49]
	v_pk_mul_f32 v[50:51], v[92:93], v[50:51]
	v_mov_b32_e32 v66, v65
	v_mov_b32_e32 v70, v69
	s_addc_u32 s23, s61, s41
	ds_read_b128 v[80:83], v210
	v_pk_fma_f32 v[94:95], v[126:127], v[88:89], v[94:95] op_sel_hi:[1,0,1]
	v_cvt_pk_bf16_f32 v48, v48, v49
	v_cvt_pk_bf16_f32 v49, v50, v51
	v_pk_fma_f32 v[50:51], v[140:141], v[88:89], v[66:67] op_sel:[0,1,0]
	v_pk_fma_f32 v[52:53], v[138:139], v[88:89], v[70:71] op_sel:[0,1,0]
	s_add_u32 s40, s21, s73
	v_pk_mul_f32 v[94:95], v[96:97], v[94:95]
	v_pk_mul_f32 v[50:51], v[86:87], v[50:51]
	v_pk_mul_f32 v[52:53], v[90:91], v[52:53]
	s_addc_u32 s41, s23, 0
	v_cvt_pk_bf16_f32 v78, v78, v79
	v_cvt_pk_bf16_f32 v79, v94, v95
	v_cvt_pk_bf16_f32 v50, v50, v51
	v_cvt_pk_bf16_f32 v51, v52, v53
	global_store_dwordx4 v124, v[76:79], s[38:39]
	global_store_dwordx4 v124, v[48:51], s[40:41]
	s_waitcnt lgkmcnt(1)
	v_mov_b32_e32 v64, v72
	v_mov_b32_e32 v65, v74
	ds_read_b128 v[48:51], v211
	ds_read_b128 v[52:55], v212
	v_pk_fma_f32 v[64:65], v[142:143], v[88:89], v[64:65] op_sel_hi:[1,0,1]
	v_mov_b32_e32 v74, v73
	v_pk_mul_f32 v[62:63], v[62:63], v[64:65]
	s_waitcnt lgkmcnt(2)
	v_mov_b32_e32 v64, v80
	v_mov_b32_e32 v65, v82
	v_pk_fma_f32 v[64:65], v[144:145], v[88:89], v[64:65] op_sel_hi:[1,0,1]
	v_cvt_pk_bf16_f32 v62, v62, v63
	v_pk_mul_f32 v[60:61], v[60:61], v[64:65]
	v_mov_b32_e32 v82, v81
	v_cvt_pk_bf16_f32 v63, v60, v61
	s_waitcnt lgkmcnt(1)
	v_mov_b32_e32 v60, v48
	v_mov_b32_e32 v61, v50
	v_pk_fma_f32 v[60:61], v[148:149], v[88:89], v[60:61] op_sel_hi:[1,0,1]
	v_mov_b32_e32 v50, v49
	v_pk_mul_f32 v[56:57], v[56:57], v[60:61]
	v_mov_b32_e32 v125, v117
	v_cvt_pk_bf16_f32 v64, v56, v57
	s_waitcnt lgkmcnt(0)
	v_mov_b32_e32 v56, v52
	v_mov_b32_e32 v57, v54
	v_pk_fma_f32 v[56:57], v[146:147], v[88:89], v[56:57] op_sel_hi:[1,0,1]
	v_mov_b32_e32 v54, v53
	v_pk_mul_f32 v[56:57], v[58:59], v[56:57]
	v_lshl_add_u64 v[66:67], s[38:39], 0, v[124:125]
	v_cvt_pk_bf16_f32 v65, v56, v57
	v_pk_fma_f32 v[56:57], v[150:151], v[88:89], v[74:75] op_sel:[0,1,0]
	v_lshl_add_u64 v[68:69], s[40:41], 0, v[124:125]
	v_pk_mul_f32 v[42:43], v[42:43], v[56:57]
	s_nop 0
	v_cvt_pk_bf16_f32 v56, v42, v43
	v_pk_fma_f32 v[42:43], v[154:155], v[88:89], v[82:83] op_sel:[0,1,0]
	s_nop 0
	v_pk_mul_f32 v[38:39], v[38:39], v[42:43]
	s_nop 0
	v_cvt_pk_bf16_f32 v57, v38, v39
	v_pk_fma_f32 v[38:39], v[158:159], v[88:89], v[50:51] op_sel:[0,1,0]
	s_nop 0
	v_pk_mul_f32 v[22:23], v[22:23], v[38:39]
	s_nop 0
	v_cvt_pk_bf16_f32 v58, v22, v23
	v_pk_fma_f32 v[22:23], v[156:157], v[88:89], v[54:55] op_sel:[0,1,0]
	s_nop 0
	v_pk_mul_f32 v[22:23], v[30:31], v[22:23]
	s_nop 0
	v_cvt_pk_bf16_f32 v59, v22, v23
	v_add_co_u32_e32 v22, vcc, s72, v66
	s_nop 1
	v_addc_co_u32_e32 v23, vcc, 0, v67, vcc
	global_store_dwordx4 v[22:23], v[62:65], off
	v_add_co_u32_e32 v22, vcc, 0x2000, v68
	s_nop 1
	v_addc_co_u32_e32 v23, vcc, 0, v69, vcc
	s_andn2_b64 vcc, exec, s[42:43]
	global_store_dwordx4 v[22:23], v[56:59], off
	s_barrier
	s_cbranch_vccnz .LBB0_1019
	v_lshrrev_b32_e32 v228, 6, v152
